# energy-lean combination: full-line (8 rows x 128 B) LDS-DMA staging layout + MFMA order sharing one operand between consecutive MFMAs, on top of the K-loop hand-off trim
# baseline (speedup 1.0000x reference)
.LBB0_539:
	v_readlane_b32 s8, v255, 41
	s_lshl_b32 s8, s8, 22
	s_andn2_b64 vcc, exec, s[24:25]
	s_cbranch_vccnz .LBB0_719
	v_ashrrev_i32_e32 v3, 31, v11
	v_lshrrev_b32_e32 v3, 26, v3
	v_add_u32_e32 v3, v11, v3
	v_ashrrev_i32_e32 v10, 6, v3
	v_bfe_i32 v3, v11, 27, 1
	v_lshlrev_b32_e32 v2, 4, v11
	v_lshrrev_b32_e32 v3, 22, v3
	v_add_u32_e32 v3, v2, v3
	v_and_b32_e32 v3, 0xfffffc00, v3
	v_sub_u32_e32 v3, v2, v3
	v_lshrrev_b32_e32 v4, 4, v3
	v_bitop3_b32 v3, v4, v3, 32 bitop3:0x6c
	v_ashrrev_i32_e32 v5, 31, v3
	v_lshrrev_b32_e32 v5, 26, v5
	v_add_u32_e32 v5, v3, v5
	v_lshlrev_b32_e32 v4, 3, v10
	v_ashrrev_i32_e32 v12, 6, v5
	v_and_b32_e32 v5, 0xc0, v5
	v_and_b32_e32 v4, -16, v4
	v_sub_u32_e32 v3, v3, v5
	v_add_u32_e32 v4, v12, v4
	v_ashrrev_i16_sdwa v3, v224, sext(v3) dst_sel:DWORD dst_unused:UNUSED_PAD src0_sel:DWORD src1_sel:BYTE_0
	v_lshlrev_b32_e32 v6, 5, v10
	v_bfe_i32 v13, v3, 0, 16
	v_lshlrev_b32_e32 v3, 1, v4
	v_lshrrev_b32_e32 v5, 2, v4
	v_and_b32_e32 v7, 3, v12
	s_mov_b32 s9, 0xfffe0
	v_and_b32_e32 v6, 32, v6
	v_and_b32_e32 v3, 24, v3
	v_and_b32_e32 v5, 4, v5
	v_and_or_b32 v7, v4, s9, v7
	v_or3_b32 v3, v7, v5, v3
	v_add_lshl_u32 v5, v6, v13, 1
	v_add_u32_e32 v2, 0x2000, v2
	s_waitcnt vmcnt(0)
	v_lshl_add_u32 v134, v3, 12, v5
	v_ashrrev_i32_e32 v3, 31, v2
	v_lshrrev_b32_e32 v3, 22, v3
	v_add_u32_e32 v3, v2, v3
	v_ashrrev_i32_e32 v14, 10, v3
	v_mul_i32_i24_e32 v3, 0x400, v14
	v_sub_u32_e32 v2, v2, v3
	v_lshrrev_b32_e32 v3, 4, v2
	v_bitop3_b32 v2, v3, v2, 32 bitop3:0x6c
	v_lshl_add_u32 v132, v4, 12, v5
	v_ashrrev_i32_e32 v4, 31, v2
	v_lshrrev_b32_e32 v4, 26, v4
	v_lshlrev_b32_e32 v3, 3, v14
	v_add_u32_e32 v4, v2, v4
	v_and_b32_e32 v3, -16, v3
	v_ashrrev_i32_e32 v15, 6, v4
	v_add_u32_e32 v3, v15, v3
	v_and_b32_e32 v6, 3, v15
	s_ashr_i32 s34, s30, 6
	s_ashr_i32 s31, s30, 8
	v_and_or_b32 v6, v3, s9, v6
	s_lshl_b32 s9, s34, 10
	s_add_u32 s12, s28, 0x1de00000
	v_and_b32_e32 v4, 0xc0, v4
	s_addc_u32 s21, s29, 0
	s_ashr_i32 s43, s42, 31
	s_ashr_i32 s41, s40, 31
	v_sub_u32_e32 v2, v2, v4
	s_lshl_b64 s[26:27], s[42:43], 20
	s_lshl_b64 s[38:39], s[40:41], 20
	v_ashrrev_i16_sdwa v2, v224, sext(v2) dst_sel:DWORD dst_unused:UNUSED_PAD src0_sel:DWORD src1_sel:BYTE_0
	s_add_u32 s54, s18, s38
	v_lshlrev_b32_e32 v5, 5, v14
	v_bfe_i32 v16, v2, 0, 16
	v_lshlrev_b32_e32 v2, 1, v3
	v_lshrrev_b32_e32 v4, 2, v3
	s_addc_u32 s55, s19, s39
	s_add_i32 s58, s9, 0
	v_and_b32_e32 v5, 32, v5
	v_and_b32_e32 v2, 24, v2
	v_and_b32_e32 v4, 4, v4
	s_add_i32 m0, s58, 0x10000
	v_or3_b32 v2, v6, v4, v2
	v_add_lshl_u32 v4, v5, v16, 1
	v_and_b32_e32 v144, 63, v0
	v_lshrrev_b32_e32 v145, 3, v144
	v_and_b32_e32 v144, 7, v144
	v_xor_b32_e32 v144, v144, v145
	v_lshlrev_b32_e32 v144, 4, v144
	v_lshrrev_b32_e32 v146, 6, v0
	v_lshl_add_u32 v145, v146, 3, v145
	v_mov_b32_e32 v146, 0x1000
	v_mad_u32_u24 v132, v145, v146, v144
	v_add_u32_e32 v136, 0x40000, v132
	v_and_b32_e32 v147, 15, v145
	v_lshrrev_b32_e32 v146, 2, v147
	v_and_b32_e32 v147, 3, v147
	v_lshl_add_u32 v147, v146, 3, v147
	v_bfe_u32 v146, v145, 4, 1
	v_lshl_add_u32 v147, v146, 2, v147
	v_and_b32_e32 v146, 0x60, v145
	v_or_b32_e32 v147, v146, v147
	v_mov_b32_e32 v146, 0x1000
	v_mad_u32_u24 v134, v147, v146, v144
	v_add_u32_e32 v138, 0x40000, v134
	global_load_lds_dwordx4 v134, s[54:55]
	s_add_i32 m0, s58, 0x12000
	s_nop 0
	s_add_u32 s38, s54, 0x80000
	global_load_lds_dwordx4 v138, s[54:55]
	s_addc_u32 s39, s55, 0
	s_add_i32 m0, s58, 0x14000
	s_nop 0
	global_load_lds_dwordx4 v134, s[38:39]
	s_add_i32 m0, s58, 0x16000
	s_add_u32 s44, s12, s26
	s_addc_u32 s45, s21, s27
	s_add_i32 s59, s58, 0x2000
	global_load_lds_dwordx4 v138, s[38:39]
	s_mov_b32 m0, s58
	s_add_u32 s26, s44, 0x80000
	global_load_lds_dwordx4 v132, s[44:45]
	s_mov_b32 m0, s59
	s_addc_u32 s27, s45, 0
	s_add_i32 s60, s58, 0x4000
	global_load_lds_dwordx4 v136, s[44:45]
	s_mov_b32 m0, s60
	s_add_i32 s61, s58, 0x6000
	global_load_lds_dwordx4 v132, s[26:27]
	s_mov_b32 m0, s61
	v_mov_b32_e32 v135, v181
	global_load_lds_dwordx4 v136, s[26:27]
	v_mov_b32_e32 v139, v181
	v_mov_b32_e32 v133, v181
	v_mov_b32_e32 v137, v181
	s_cmp_eq_u32 s31, 1
	v_lshl_add_u64 v[8:9], s[54:55], 0, v[134:135]
	v_lshl_add_u64 v[6:7], s[54:55], 0, v[138:139]
	v_lshl_add_u64 v[2:3], s[44:45], 0, v[132:133]
	s_cselect_b64 s[26:27], -1, 0
	s_cmp_lg_u32 s31, 1
	v_lshl_add_u64 v[4:5], s[44:45], 0, v[136:137]
	s_cbranch_scc1 .LBB0_542
	s_barrier
.LBB0_542:
	v_bfe_u32 v158, v11, 4, 2
	v_and_b32_e32 v131, 15, v11
	v_lshlrev_b32_e32 v17, 4, v158
	v_lshlrev_b32_e32 v11, 2, v11
	s_lshl_b32 s62, s31, 6
	v_lshl_or_b32 v17, v131, 6, v17
	s_lshl_b32 s31, s31, 13
	v_and_b32_e32 v11, 32, v11
	v_bitop3_b32 v18, v17, s31, v11 bitop3:0xde
	s_lshl_b32 s31, s34, 5
	s_and_b32 s63, s31, 0x60
	s_lshl_b32 s31, s63, 7
	s_add_u32 s28, s28, 0x37200000
	s_addc_u32 s29, s29, 0
	s_add_i32 m0, s58, 0x18000
	v_lshl_add_u64 v[8:9], v[8:9], 0, s[16:17]
	s_waitcnt vmcnt(2)
	s_barrier
	global_load_lds_dwordx4 v[8:9], off
	v_lshl_add_u64 v[6:7], v[6:7], 0, s[16:17]
	s_add_i32 m0, s58, 0x1a000
	s_add_i32 s64, s58, 0x8000
	s_add_i32 s69, s58, 0xa000
	global_load_lds_dwordx4 v[6:7], off
	v_lshl_add_u64 v[2:3], v[2:3], 0, s[16:17]
	s_mov_b32 m0, s64
	s_add_u32 s34, s54, 0x80080
	global_load_lds_dwordx4 v[2:3], off
	v_lshl_add_u64 v[2:3], v[4:5], 0, s[16:17]
	s_mov_b32 m0, s69
	s_addc_u32 s35, s55, 0
	global_load_lds_dwordx4 v[2:3], off
	s_add_i32 m0, s58, 0x1c000
	v_lshl_add_u64 v[2:3], s[34:35], 0, v[134:135]
	global_load_lds_dwordx4 v[2:3], off
	v_lshl_add_u64 v[2:3], s[34:35], 0, v[138:139]
	s_add_i32 m0, s58, 0x1e000
	s_cmpk_lt_u32 s30, 0x100
	global_load_lds_dwordx4 v[2:3], off
	v_lshlrev_b32_e32 v2, 15, v10
	v_and_b32_e32 v2, 0xffff0000, v2
	v_lshl_add_u32 v2, v12, 12, v2
	v_and_b32_e32 v3, 1, v10
	v_lshl_or_b32 v2, v3, 6, v2
	v_mov_b32_e32 v140, v132
	v_lshlrev_b32_e32 v2, 15, v14
	v_and_b32_e32 v2, 0xffff0000, v2
	s_waitcnt vmcnt(6)
	v_lshl_add_u32 v2, v15, 12, v2
	v_and_b32_e32 v3, 1, v14
	v_lshl_or_b32 v2, v3, 6, v2
	v_bitop3_b32 v159, v17, s31, v11 bitop3:0xde
	s_cselect_b64 s[30:31], -1, 0
	s_ashr_i32 s70, s7, 31
	v_mov_b32_e32 v141, v181
	v_mov_b32_e32 v142, v136
	v_mov_b32_e32 v143, v181
	s_mov_b32 s71, 0
	v_add_u32_e32 v160, 0, v18
	v_and_b32_e32 v144, 7, v0
	v_bfe_u32 v145, v0, 4, 2
	v_xor_b32_e32 v145, v145, v144
	v_lshlrev_b32_e32 v145, 4, v145
	v_lshl_add_u32 v145, v144, 7, v145
	v_bfe_u32 v144, v0, 3, 1
	v_lshl_add_u32 v145, v144, 10, v145
	v_lshrrev_b32_e32 v144, 8, v0
	v_lshl_add_u32 v160, v144, 13, v145
	v_bfe_u32 v144, v0, 6, 2
	v_lshl_add_u32 v159, v144, 12, v145
	s_barrier
	s_branch .LBB0_545

.LBB0_552:
	s_add_u32 s54, s44, 0xfff80080
	s_addc_u32 s55, s45, -1
	s_waitcnt lgkmcnt(0)
	s_add_i32 s82, 0, 0x10000
	s_cmp_eq_u32 s76, 28
	s_cselect_b32 s57, s41, s55
	s_cselect_b32 s56, s43, s54
	v_add_u32_e32 v161, s82, v159
	s_cselect_b32 s55, s35, s75
	s_cselect_b32 s54, s47, s74
	s_add_i32 vcc_lo, 0, 0x14000
	ds_read_b128 v[144:147], v161
	ds_read_b128 v[152:155], v161 offset:2048
	v_xor_b32_e32 v161, 64, v161
	ds_read_b128 v[148:151], v161
	ds_read_b128 v[162:165], v161 offset:2048
	v_add_u32_e32 v161, vcc_lo, v159
	ds_read_b128 v[166:169], v161
	ds_read_b128 v[174:177], v161 offset:2048
	v_xor_b32_e32 v161, 64, v161
	ds_read_b128 v[170:173], v161
	ds_read_b128 v[190:193], v161 offset:2048
	v_lshl_add_u64 v[178:179], s[44:45], 0, v[140:141]
	s_add_i32 m0, s58, 0xc000
	ds_read_b128 v[194:197], v160
	ds_read_b128 v[202:205], v160 offset:2048
	ds_read_b128 v[210:213], v160 offset:4096
	ds_read_b128 v[218:221], v160 offset:6144
	v_xor_b32_e32 v238, 64, v160
	ds_read_b128 v[198:201], v238
	ds_read_b128 v[206:209], v238 offset:2048
	ds_read_b128 v[214:217], v238 offset:4096
	ds_read_b128 v[238:241], v238 offset:6144
	global_load_lds_dwordx4 v[178:179], off
	v_lshl_add_u64 v[178:179], s[44:45], 0, v[142:143]
	s_add_i32 m0, s58, 0xe000
	s_nop 0
	global_load_lds_dwordx4 v[178:179], off
	s_waitcnt vmcnt(8)
	s_waitcnt lgkmcnt(0)
	s_setprio 1
	s_barrier
	v_mfma_f32_16x16x32_bf16 v[126:129], v[144:147], v[194:197], v[126:129]
	v_mfma_f32_16x16x32_bf16 v[122:125], v[152:155], v[194:197], v[122:125]
	v_mfma_f32_16x16x32_bf16 v[106:109], v[152:155], v[202:205], v[106:109]
	v_mfma_f32_16x16x32_bf16 v[110:113], v[144:147], v[202:205], v[110:113]
	v_mfma_f32_16x16x32_bf16 v[94:97], v[144:147], v[210:213], v[94:97]
	v_mfma_f32_16x16x32_bf16 v[90:93], v[152:155], v[210:213], v[90:93]
	v_mfma_f32_16x16x32_bf16 v[74:77], v[152:155], v[218:221], v[74:77]
	v_mfma_f32_16x16x32_bf16 v[78:81], v[144:147], v[218:221], v[78:81]
	v_mfma_f32_16x16x32_bf16 v[126:129], v[148:151], v[198:201], v[126:129]
	v_mfma_f32_16x16x32_bf16 v[122:125], v[162:165], v[198:201], v[122:125]
	v_mfma_f32_16x16x32_bf16 v[106:109], v[162:165], v[206:209], v[106:109]
	v_mfma_f32_16x16x32_bf16 v[110:113], v[148:151], v[206:209], v[110:113]
	v_mfma_f32_16x16x32_bf16 v[94:97], v[148:151], v[214:217], v[94:97]
	v_mfma_f32_16x16x32_bf16 v[90:93], v[162:165], v[214:217], v[90:93]
	v_mfma_f32_16x16x32_bf16 v[74:77], v[162:165], v[238:241], v[74:77]
	v_mfma_f32_16x16x32_bf16 v[78:81], v[148:151], v[238:241], v[78:81]
	v_mfma_f32_16x16x32_bf16 v[118:121], v[166:169], v[194:197], v[118:121]
	v_mfma_f32_16x16x32_bf16 v[114:117], v[174:177], v[194:197], v[114:117]
	v_mfma_f32_16x16x32_bf16 v[98:101], v[174:177], v[202:205], v[98:101]
	v_mfma_f32_16x16x32_bf16 v[102:105], v[166:169], v[202:205], v[102:105]
	v_mfma_f32_16x16x32_bf16 v[86:89], v[166:169], v[210:213], v[86:89]
	v_mfma_f32_16x16x32_bf16 v[82:85], v[174:177], v[210:213], v[82:85]
	v_mfma_f32_16x16x32_bf16 v[66:69], v[174:177], v[218:221], v[66:69]
	v_mfma_f32_16x16x32_bf16 v[70:73], v[166:169], v[218:221], v[70:73]
	v_mfma_f32_16x16x32_bf16 v[118:121], v[170:173], v[198:201], v[118:121]
	v_mfma_f32_16x16x32_bf16 v[114:117], v[190:193], v[198:201], v[114:117]
	v_mfma_f32_16x16x32_bf16 v[98:101], v[190:193], v[206:209], v[98:101]
	v_mfma_f32_16x16x32_bf16 v[102:105], v[170:173], v[206:209], v[102:105]
	v_mfma_f32_16x16x32_bf16 v[86:89], v[170:173], v[214:217], v[86:89]
	v_mfma_f32_16x16x32_bf16 v[82:85], v[190:193], v[214:217], v[82:85]
	v_mfma_f32_16x16x32_bf16 v[66:69], v[190:193], v[238:241], v[66:69]
	v_mfma_f32_16x16x32_bf16 v[70:73], v[170:173], v[238:241], v[70:73]
	s_barrier
	s_setprio 0
	s_add_i32 s82, s82, s9
	v_lshl_add_u64 v[178:179], s[54:55], 0, v[134:135]
	s_mov_b32 m0, s82
	ds_read_b128 v[194:197], v160 offset:16384
	ds_read_b128 v[202:205], v160 offset:18432
	ds_read_b128 v[210:213], v160 offset:20480
	ds_read_b128 v[218:221], v160 offset:22528
	v_xor_b32_e32 v238, 64, v160
	ds_read_b128 v[198:201], v238 offset:16384
	ds_read_b128 v[206:209], v238 offset:18432
	ds_read_b128 v[214:217], v238 offset:20480
	ds_read_b128 v[238:241], v238 offset:22528
	global_load_lds_dwordx4 v[178:179], off
	s_add_i32 m0, s82, 0x2000
	s_add_u32 s82, s54, 0x80000
	v_lshl_add_u64 v[222:223], s[54:55], 0, v[138:139]
	s_addc_u32 s83, s55, 0
	s_add_i32 vcc_lo, vcc_lo, s9
	global_load_lds_dwordx4 v[222:223], off
	v_lshl_add_u64 v[242:243], s[82:83], 0, v[134:135]
	s_mov_b32 m0, vcc_lo
	v_lshl_add_u64 v[244:245], s[56:57], 0, v[136:137]
	global_load_lds_dwordx4 v[242:243], off
	v_lshl_add_u64 v[242:243], s[82:83], 0, v[138:139]
	s_add_i32 m0, vcc_lo, 0x2000
	s_nop 0
	global_load_lds_dwordx4 v[242:243], off
	v_lshl_add_u64 v[242:243], s[56:57], 0, v[132:133]
	s_mov_b32 m0, s58
	s_nop 0
	global_load_lds_dwordx4 v[242:243], off
	s_mov_b32 m0, s59
	s_nop 0
	global_load_lds_dwordx4 v[244:245], off
	s_waitcnt vmcnt(8)
	s_waitcnt lgkmcnt(0)
	s_setprio 1
	s_barrier
	v_mfma_f32_16x16x32_bf16 v[62:65], v[144:147], v[194:197], v[62:65]
	v_mfma_f32_16x16x32_bf16 v[58:61], v[152:155], v[194:197], v[58:61]
	v_mfma_f32_16x16x32_bf16 v[42:45], v[152:155], v[202:205], v[42:45]
	v_mfma_f32_16x16x32_bf16 v[46:49], v[144:147], v[202:205], v[46:49]
	v_mfma_f32_16x16x32_bf16 v[30:33], v[144:147], v[210:213], v[30:33]
	v_mfma_f32_16x16x32_bf16 v[26:29], v[152:155], v[210:213], v[26:29]
	v_mfma_f32_16x16x32_bf16 v[10:13], v[152:155], v[218:221], v[10:13]
	v_mfma_f32_16x16x32_bf16 v[14:17], v[144:147], v[218:221], v[14:17]
	v_mfma_f32_16x16x32_bf16 v[62:65], v[148:151], v[198:201], v[62:65]
	v_mfma_f32_16x16x32_bf16 v[58:61], v[162:165], v[198:201], v[58:61]
	v_mfma_f32_16x16x32_bf16 v[42:45], v[162:165], v[206:209], v[42:45]
	v_mfma_f32_16x16x32_bf16 v[46:49], v[148:151], v[206:209], v[46:49]
	v_mfma_f32_16x16x32_bf16 v[30:33], v[148:151], v[214:217], v[30:33]
	v_mfma_f32_16x16x32_bf16 v[26:29], v[162:165], v[214:217], v[26:29]
	v_mfma_f32_16x16x32_bf16 v[10:13], v[162:165], v[238:241], v[10:13]
	v_mfma_f32_16x16x32_bf16 v[14:17], v[148:151], v[238:241], v[14:17]
	v_mfma_f32_16x16x32_bf16 v[54:57], v[166:169], v[194:197], v[54:57]
	v_mfma_f32_16x16x32_bf16 v[50:53], v[174:177], v[194:197], v[50:53]
	v_mfma_f32_16x16x32_bf16 v[34:37], v[174:177], v[202:205], v[34:37]
	v_mfma_f32_16x16x32_bf16 v[38:41], v[166:169], v[202:205], v[38:41]
	v_mfma_f32_16x16x32_bf16 v[22:25], v[166:169], v[210:213], v[22:25]
	v_mfma_f32_16x16x32_bf16 v[18:21], v[174:177], v[210:213], v[18:21]
	v_mfma_f32_16x16x32_bf16 v[2:5], v[174:177], v[218:221], v[2:5]
	v_mfma_f32_16x16x32_bf16 v[6:9], v[166:169], v[218:221], v[6:9]
	v_mfma_f32_16x16x32_bf16 v[54:57], v[170:173], v[198:201], v[54:57]
	v_mfma_f32_16x16x32_bf16 v[50:53], v[190:193], v[198:201], v[50:53]
	v_mfma_f32_16x16x32_bf16 v[34:37], v[190:193], v[206:209], v[34:37]
	v_mfma_f32_16x16x32_bf16 v[38:41], v[170:173], v[206:209], v[38:41]
	v_mfma_f32_16x16x32_bf16 v[22:25], v[170:173], v[214:217], v[22:25]
	v_mfma_f32_16x16x32_bf16 v[18:21], v[190:193], v[214:217], v[18:21]
	v_mfma_f32_16x16x32_bf16 v[2:5], v[190:193], v[238:241], v[2:5]
	v_mfma_f32_16x16x32_bf16 v[6:9], v[170:173], v[238:241], v[6:9]
	s_barrier
	s_setprio 0
	s_add_i32 s82, 0, 0x18000
	v_add_u32_e32 v161, s82, v159
	s_add_i32 s83, 0, 0x1c000
	ds_read_b128 v[144:147], v161
	ds_read_b128 v[152:155], v161 offset:2048
	v_xor_b32_e32 v161, 64, v161
	ds_read_b128 v[148:151], v161
	ds_read_b128 v[162:165], v161 offset:2048
	v_add_u32_e32 v161, s83, v159
	ds_read_b128 v[166:169], v161
	ds_read_b128 v[174:177], v161 offset:2048
	v_xor_b32_e32 v161, 64, v161
	ds_read_b128 v[170:173], v161
	ds_read_b128 v[190:193], v161 offset:2048
	s_add_u32 s56, s56, 0x80000
	s_addc_u32 s57, s57, 0
	s_mov_b32 m0, s60
	v_lshl_add_u64 v[246:247], s[56:57], 0, v[132:133]
	ds_read_b128 v[194:197], v160 offset:32768
	ds_read_b128 v[202:205], v160 offset:34816
	ds_read_b128 v[210:213], v160 offset:36864
	ds_read_b128 v[218:221], v160 offset:38912
	v_xor_b32_e32 v238, 64, v160
	ds_read_b128 v[198:201], v238 offset:32768
	ds_read_b128 v[206:209], v238 offset:34816
	ds_read_b128 v[214:217], v238 offset:36864
	ds_read_b128 v[238:241], v238 offset:38912
	global_load_lds_dwordx4 v[246:247], off
	v_lshl_add_u64 v[246:247], s[56:57], 0, v[136:137]
	s_mov_b32 m0, s61
	s_nop 0
	global_load_lds_dwordx4 v[246:247], off
	s_waitcnt vmcnt(8)
	s_waitcnt lgkmcnt(0)
	s_setprio 1
	s_barrier
	v_mfma_f32_16x16x32_bf16 v[126:129], v[144:147], v[194:197], v[126:129]
	v_mfma_f32_16x16x32_bf16 v[122:125], v[152:155], v[194:197], v[122:125]
	v_mfma_f32_16x16x32_bf16 v[106:109], v[152:155], v[202:205], v[106:109]
	v_mfma_f32_16x16x32_bf16 v[110:113], v[144:147], v[202:205], v[110:113]
	v_mfma_f32_16x16x32_bf16 v[94:97], v[144:147], v[210:213], v[94:97]
	v_mfma_f32_16x16x32_bf16 v[90:93], v[152:155], v[210:213], v[90:93]
	v_mfma_f32_16x16x32_bf16 v[74:77], v[152:155], v[218:221], v[74:77]
	v_mfma_f32_16x16x32_bf16 v[78:81], v[144:147], v[218:221], v[78:81]
	v_mfma_f32_16x16x32_bf16 v[126:129], v[148:151], v[198:201], v[126:129]
	v_mfma_f32_16x16x32_bf16 v[122:125], v[162:165], v[198:201], v[122:125]
	v_mfma_f32_16x16x32_bf16 v[106:109], v[162:165], v[206:209], v[106:109]
	v_mfma_f32_16x16x32_bf16 v[110:113], v[148:151], v[206:209], v[110:113]
	v_mfma_f32_16x16x32_bf16 v[94:97], v[148:151], v[214:217], v[94:97]
	v_mfma_f32_16x16x32_bf16 v[90:93], v[162:165], v[214:217], v[90:93]
	v_mfma_f32_16x16x32_bf16 v[74:77], v[162:165], v[238:241], v[74:77]
	v_mfma_f32_16x16x32_bf16 v[78:81], v[148:151], v[238:241], v[78:81]
	v_mfma_f32_16x16x32_bf16 v[118:121], v[166:169], v[194:197], v[118:121]
	v_mfma_f32_16x16x32_bf16 v[114:117], v[174:177], v[194:197], v[114:117]
	v_mfma_f32_16x16x32_bf16 v[98:101], v[174:177], v[202:205], v[98:101]
	v_mfma_f32_16x16x32_bf16 v[102:105], v[166:169], v[202:205], v[102:105]
	v_mfma_f32_16x16x32_bf16 v[86:89], v[166:169], v[210:213], v[86:89]
	v_mfma_f32_16x16x32_bf16 v[82:85], v[174:177], v[210:213], v[82:85]
	v_mfma_f32_16x16x32_bf16 v[66:69], v[174:177], v[218:221], v[66:69]
	v_mfma_f32_16x16x32_bf16 v[70:73], v[166:169], v[218:221], v[70:73]
	v_mfma_f32_16x16x32_bf16 v[118:121], v[170:173], v[198:201], v[118:121]
	v_mfma_f32_16x16x32_bf16 v[114:117], v[190:193], v[198:201], v[114:117]
	v_mfma_f32_16x16x32_bf16 v[98:101], v[190:193], v[206:209], v[98:101]
	v_mfma_f32_16x16x32_bf16 v[102:105], v[170:173], v[206:209], v[102:105]
	v_mfma_f32_16x16x32_bf16 v[86:89], v[170:173], v[214:217], v[86:89]
	v_mfma_f32_16x16x32_bf16 v[82:85], v[190:193], v[214:217], v[82:85]
	v_mfma_f32_16x16x32_bf16 v[66:69], v[190:193], v[238:241], v[66:69]
	v_mfma_f32_16x16x32_bf16 v[70:73], v[170:173], v[238:241], v[70:73]
	s_barrier
	s_setprio 0
	s_add_i32 s56, s82, s9
	v_lshl_add_u64 v[178:179], v[178:179], 0, s[16:17]
	s_mov_b32 m0, s56
	ds_read_b128 v[194:197], v160 offset:49152
	ds_read_b128 v[202:205], v160 offset:51200
	ds_read_b128 v[210:213], v160 offset:53248
	ds_read_b128 v[218:221], v160 offset:55296
	v_xor_b32_e32 v238, 64, v160
	ds_read_b128 v[198:201], v238 offset:49152
	ds_read_b128 v[206:209], v238 offset:51200
	ds_read_b128 v[214:217], v238 offset:53248
	ds_read_b128 v[238:241], v238 offset:55296
	global_load_lds_dwordx4 v[178:179], off
	s_add_i32 m0, s56, 0x2000
	s_add_u32 s54, s54, 0x80080
	v_lshl_add_u64 v[178:179], v[222:223], 0, s[16:17]
	s_addc_u32 s55, s55, 0
	s_add_i32 s56, s83, s9
	global_load_lds_dwordx4 v[178:179], off
	v_lshl_add_u64 v[178:179], s[54:55], 0, v[134:135]
	s_mov_b32 m0, s56
	s_nop 0
	global_load_lds_dwordx4 v[178:179], off
	v_lshl_add_u64 v[178:179], s[54:55], 0, v[138:139]
	s_add_i32 m0, s56, 0x2000
	s_nop 0
	global_load_lds_dwordx4 v[178:179], off
	v_lshl_add_u64 v[178:179], v[242:243], 0, s[16:17]
	s_mov_b32 m0, s64
	s_nop 0
	global_load_lds_dwordx4 v[178:179], off
	v_lshl_add_u64 v[178:179], v[244:245], 0, s[16:17]
	s_mov_b32 m0, s69
	s_nop 0
	global_load_lds_dwordx4 v[178:179], off
	s_waitcnt vmcnt(8)
	s_waitcnt lgkmcnt(0)
	s_setprio 1
	s_barrier
	v_mfma_f32_16x16x32_bf16 v[62:65], v[144:147], v[194:197], v[62:65]
	v_mfma_f32_16x16x32_bf16 v[58:61], v[152:155], v[194:197], v[58:61]
	v_mfma_f32_16x16x32_bf16 v[42:45], v[152:155], v[202:205], v[42:45]
	v_mfma_f32_16x16x32_bf16 v[46:49], v[144:147], v[202:205], v[46:49]
	v_mfma_f32_16x16x32_bf16 v[30:33], v[144:147], v[210:213], v[30:33]
	v_mfma_f32_16x16x32_bf16 v[26:29], v[152:155], v[210:213], v[26:29]
	v_mfma_f32_16x16x32_bf16 v[10:13], v[152:155], v[218:221], v[10:13]
	v_mfma_f32_16x16x32_bf16 v[14:17], v[144:147], v[218:221], v[14:17]
	v_mfma_f32_16x16x32_bf16 v[62:65], v[148:151], v[198:201], v[62:65]
	v_mfma_f32_16x16x32_bf16 v[58:61], v[162:165], v[198:201], v[58:61]
	v_mfma_f32_16x16x32_bf16 v[42:45], v[162:165], v[206:209], v[42:45]
	v_mfma_f32_16x16x32_bf16 v[46:49], v[148:151], v[206:209], v[46:49]
	v_mfma_f32_16x16x32_bf16 v[30:33], v[148:151], v[214:217], v[30:33]
	v_mfma_f32_16x16x32_bf16 v[26:29], v[162:165], v[214:217], v[26:29]
	v_mfma_f32_16x16x32_bf16 v[10:13], v[162:165], v[238:241], v[10:13]
	v_mfma_f32_16x16x32_bf16 v[14:17], v[148:151], v[238:241], v[14:17]
	v_mfma_f32_16x16x32_bf16 v[54:57], v[166:169], v[194:197], v[54:57]
	v_mfma_f32_16x16x32_bf16 v[50:53], v[174:177], v[194:197], v[50:53]
	v_mfma_f32_16x16x32_bf16 v[34:37], v[174:177], v[202:205], v[34:37]
	v_mfma_f32_16x16x32_bf16 v[38:41], v[166:169], v[202:205], v[38:41]
	v_mfma_f32_16x16x32_bf16 v[22:25], v[166:169], v[210:213], v[22:25]
	v_mfma_f32_16x16x32_bf16 v[18:21], v[174:177], v[210:213], v[18:21]
	v_mfma_f32_16x16x32_bf16 v[2:5], v[174:177], v[218:221], v[2:5]
	v_mfma_f32_16x16x32_bf16 v[6:9], v[166:169], v[218:221], v[6:9]
	v_mfma_f32_16x16x32_bf16 v[54:57], v[170:173], v[198:201], v[54:57]
	v_mfma_f32_16x16x32_bf16 v[50:53], v[190:193], v[198:201], v[50:53]
	v_mfma_f32_16x16x32_bf16 v[34:37], v[190:193], v[206:209], v[34:37]
	v_mfma_f32_16x16x32_bf16 v[38:41], v[170:173], v[206:209], v[38:41]
	v_mfma_f32_16x16x32_bf16 v[22:25], v[170:173], v[214:217], v[22:25]
	v_mfma_f32_16x16x32_bf16 v[18:21], v[190:193], v[214:217], v[18:21]
	v_mfma_f32_16x16x32_bf16 v[2:5], v[190:193], v[238:241], v[2:5]
	v_mfma_f32_16x16x32_bf16 v[6:9], v[170:173], v[238:241], v[6:9]
	s_barrier
	s_setprio 0
	s_add_i32 s76, s76, 2
	s_add_u32 s44, s44, 0x100
	s_addc_u32 s45, s45, 0
	s_add_u32 s74, s74, 0x100
	s_addc_u32 s75, s75, 0
	s_cmp_gt_u32 s76, 29
	s_cbranch_scc0 .LBB0_552
	s_and_b64 vcc, exec, s[30:31]
	s_cbranch_vccz .LBB0_555
	s_barrier

.LBB0_812:
	s_add_u32 s14, s0, s54
	s_movk_i32 s24, 0x180
	s_addc_u32 s15, s1, 0
	s_load_dwordx2 s[22:23], s[14:15], 0x118
	v_mov_b32_e32 v14, v0
	s_andn2_b64 vcc, exec, s[10:11]
	v_readfirstlane_b32 s26, v14
	s_cbranch_vccnz .LBB0_832
	v_lshlrev_b32_e32 v2, 4, v14
	v_add_u32_e32 v3, 0x2000, v2
	v_ashrrev_i32_e32 v4, 31, v3
	v_lshrrev_b32_e32 v4, 22, v4
	v_add_u32_e32 v4, v3, v4
	v_ashrrev_i32_e32 v4, 10, v4
	v_mul_i32_i24_e32 v5, 0x400, v4
	v_sub_u32_e32 v3, v3, v5
	v_lshrrev_b32_e32 v5, 4, v3
	v_bitop3_b32 v3, v5, v3, 32 bitop3:0x6c
	v_ashrrev_i32_e32 v5, 31, v3
	v_lshrrev_b32_e32 v5, 26, v5
	v_add_u32_e32 v5, v3, v5
	v_lshlrev_b32_e32 v7, 3, v4
	v_ashrrev_i32_e32 v6, 6, v5
	v_and_b32_e32 v7, -16, v7
	v_lshlrev_b32_e32 v4, 5, v4
	v_add_u32_e32 v7, v6, v7
	v_and_b32_e32 v15, 32, v4
	v_and_b32_e32 v4, 0xc0, v5
	v_and_b32_e32 v6, 3, v6
	s_mov_b32 s18, 0x7fffffe0
	v_lshrrev_b32_e32 v8, 2, v7
	v_lshlrev_b32_e32 v9, 1, v7
	v_sub_u32_e32 v3, v3, v4
	v_and_or_b32 v6, v7, s18, v6
	v_and_b32_e32 v8, 4, v8
	v_and_b32_e32 v9, 24, v9
	v_ashrrev_i16_sdwa v3, v224, sext(v3) dst_sel:DWORD dst_unused:UNUSED_PAD src0_sel:DWORD src1_sel:BYTE_0
	v_or3_b32 v6, v6, v8, v9
	v_bfe_i32 v16, v3, 0, 16
	v_mul_lo_u32 v6, v6, s24
	v_add_u32_e32 v3, v15, v16
	v_mul_lo_u32 v17, v7, s24
	s_waitcnt vmcnt(0)
	v_add_lshl_u32 v132, v6, v3, 1
	v_add_lshl_u32 v134, v3, v17, 1
	v_bfe_i32 v3, v14, 27, 1
	v_lshrrev_b32_e32 v3, 22, v3
	v_add_u32_e32 v3, v2, v3
	v_and_b32_e32 v3, 0xfffffc00, v3
	v_sub_u32_e32 v2, v2, v3
	v_lshrrev_b32_e32 v3, 4, v2
	v_ashrrev_i32_e32 v5, 31, v14
	s_waitcnt lgkmcnt(0)
	s_add_u32 s9, s22, 0x37200000
	v_bitop3_b32 v2, v3, v2, 32 bitop3:0x6c
	v_lshrrev_b32_e32 v5, 26, v5
	s_mul_i32 s11, s12, 0x30000
	s_addc_u32 s21, s23, 0
	v_ashrrev_i32_e32 v3, 31, v2
	v_add_u32_e32 v5, v14, v5
	s_mul_hi_u32 s10, s12, 0x30000
	s_add_u32 s11, s22, s11
	v_lshrrev_b32_e32 v3, 26, v3
	v_ashrrev_i32_e32 v5, 6, v5
	s_addc_u32 s10, s23, s10
	v_add_u32_e32 v3, v2, v3
	v_lshlrev_b32_e32 v6, 3, v5
	s_add_u32 s42, s11, 0x16900000
	v_ashrrev_i32_e32 v4, 6, v3
	v_and_b32_e32 v6, -16, v6
	s_addc_u32 s43, s10, 0
	s_ashr_i32 s25, s24, 31
	v_add_u32_e32 v6, v4, v6
	v_and_b32_e32 v4, 3, v4
	s_lshl_b64 s[14:15], s[24:25], 9
	v_and_or_b32 v4, v6, s18, v4
	s_ashr_i32 s18, s6, 31
	s_mul_i32 s18, s14, s18
	s_mul_hi_u32 s19, s14, s6
	s_add_i32 s29, s19, s18
	s_lshr_b64 s[18:19], s[24:25], 23
	s_mul_i32 s19, s18, s6
	s_add_i32 s29, s29, s19
	s_ashr_i32 s19, s8, 31
	v_and_b32_e32 v3, 0xc0, v3
	s_mul_i32 s19, s14, s19
	s_mul_hi_u32 s31, s14, s8
	s_ashr_i32 s27, s26, 6
	v_lshrrev_b32_e32 v7, 2, v6
	v_lshlrev_b32_e32 v8, 1, v6
	v_sub_u32_e32 v2, v2, v3
	s_add_i32 s19, s31, s19
	s_mul_i32 s18, s18, s8
	s_ashr_i32 s28, s26, 8
	s_lshl_b64 s[10:11], s[24:25], 8
	s_lshl_b32 s44, s27, 10
	v_and_b32_e32 v7, 4, v7
	v_and_b32_e32 v8, 24, v8
	v_lshlrev_b32_e32 v5, 5, v5
	v_ashrrev_i16_sdwa v2, v224, sext(v2) dst_sel:DWORD dst_unused:UNUSED_PAD src0_sel:DWORD src1_sel:BYTE_0
	s_add_i32 s19, s19, s18
	s_mul_i32 s18, s14, s8
	v_or3_b32 v4, v4, v7, v8
	v_and_b32_e32 v18, 32, v5
	v_bfe_i32 v19, v2, 0, 16
	s_add_u32 s40, s42, s18
	v_mul_lo_u32 v4, v4, s24
	v_add_u32_e32 v2, v18, v19
	s_addc_u32 s41, s43, s19
	s_add_i32 s45, s44, 0
	v_add_lshl_u32 v136, v4, v2, 1
	s_add_i32 m0, s45, 0x10000
	s_mul_i32 s30, s14, s6
	v_and_b32_e32 v154, 63, v0
	v_lshrrev_b32_e32 v155, 3, v154
	v_and_b32_e32 v154, 7, v154
	v_xor_b32_e32 v154, v154, v155
	v_lshlrev_b32_e32 v154, 4, v154
	v_lshrrev_b32_e32 v156, 6, v0
	v_lshl_add_u32 v155, v156, 3, v155
	v_mov_b32_e32 v156, 0x300
	v_mad_u32_u24 v138, v155, v156, v154
	v_add_u32_e32 v134, 0xc000, v138
	v_and_b32_e32 v157, 15, v155
	v_lshrrev_b32_e32 v156, 2, v157
	v_and_b32_e32 v157, 3, v157
	v_lshl_add_u32 v157, v156, 3, v157
	v_bfe_u32 v156, v155, 4, 1
	v_lshl_add_u32 v157, v156, 2, v157
	v_and_b32_e32 v156, 0x60, v155
	v_or_b32_e32 v157, v156, v157
	v_mov_b32_e32 v156, 0x300
	v_mad_u32_u24 v136, v157, v156, v154
	v_add_u32_e32 v132, 0xc000, v136
	global_load_lds_dwordx4 v136, s[40:41]
	s_add_i32 m0, s45, 0x12000
	s_add_u32 s18, s40, s10
	global_load_lds_dwordx4 v132, s[40:41]
	s_addc_u32 s19, s41, s11
	s_add_i32 m0, s45, 0x14000
	v_mul_lo_u32 v20, v6, s24
	global_load_lds_dwordx4 v136, s[18:19]
	s_add_i32 m0, s45, 0x16000
	s_add_u32 s34, s9, s30
	v_mov_b32_e32 v137, v181
	v_mov_b32_e32 v133, v181
	s_addc_u32 s35, s21, s29
	s_add_i32 s46, s45, 0x2000
	s_nop 0
	v_lshl_add_u64 v[6:7], s[18:19], 0, v[136:137]
	v_lshl_add_u64 v[8:9], s[18:19], 0, v[132:133]
	global_load_lds_dwordx4 v132, s[18:19]
	s_mov_b32 m0, s45
	s_add_u32 s18, s34, s10
	global_load_lds_dwordx4 v138, s[34:35]
	s_mov_b32 m0, s46
	s_addc_u32 s19, s35, s11
	s_add_i32 s47, s45, 0x4000
	global_load_lds_dwordx4 v134, s[34:35]
	s_mov_b32 m0, s47
	s_add_i32 s48, s45, 0x6000
	global_load_lds_dwordx4 v138, s[18:19]
	s_mov_b32 m0, s48
	v_mov_b32_e32 v139, v181
	global_load_lds_dwordx4 v134, s[18:19]
	v_mov_b32_e32 v135, v181
	s_cmp_eq_u32 s28, 1
	v_lshl_add_u64 v[2:3], s[40:41], 0, v[136:137]
	v_lshl_add_u64 v[4:5], s[40:41], 0, v[132:133]
	v_lshl_add_u64 v[10:11], s[34:35], 0, v[138:139]
	v_lshl_add_u64 v[12:13], s[34:35], 0, v[134:135]
	s_cselect_b64 s[18:19], -1, 0
	s_cmp_lg_u32 s28, 1
	s_cbranch_scc1 .LBB0_815
	s_barrier
.LBB0_815:
	s_add_u32 s22, s22, 0x39600000
	s_addc_u32 s23, s23, 0
	s_add_i32 m0, s45, 0x18000
	v_lshl_add_u64 v[2:3], v[2:3], 0, s[16:17]
	s_waitcnt vmcnt(2)
	s_barrier
	global_load_lds_dwordx4 v[2:3], off
	v_lshl_add_u64 v[2:3], v[4:5], 0, s[16:17]
	s_add_i32 m0, s45, 0x1a000
	s_add_i32 s49, s45, 0x8000
	global_load_lds_dwordx4 v[2:3], off
	v_lshl_add_u64 v[2:3], v[10:11], 0, s[16:17]
	s_mov_b32 m0, s49
	s_add_i32 s50, s45, 0xa000
	global_load_lds_dwordx4 v[2:3], off
	v_lshl_add_u64 v[2:3], v[12:13], 0, s[16:17]
	s_mov_b32 m0, s50
	v_bfe_u32 v144, v14, 4, 2
	global_load_lds_dwordx4 v[2:3], off
	s_add_i32 m0, s45, 0x1c000
	v_lshl_add_u64 v[2:3], v[6:7], 0, s[16:17]
	global_load_lds_dwordx4 v[2:3], off
	v_lshl_add_u64 v[2:3], v[8:9], 0, s[16:17]
	s_add_i32 m0, s45, 0x1e000
	s_lshr_b32 s25, s25, 26
	global_load_lds_dwordx4 v[2:3], off
	v_and_b32_e32 v145, 15, v14
	s_add_i32 s25, s24, s25
	v_lshlrev_b32_e32 v2, 4, v144
	v_lshlrev_b32_e32 v3, 2, v14
	s_ashr_i32 s51, s25, 6
	v_lshl_or_b32 v2, v145, 6, v2
	s_lshl_b32 s25, s28, 13
	v_and_b32_e32 v3, 32, v3
	v_bitop3_b32 v4, v2, s25, v3 bitop3:0xde
	s_lshl_b32 s25, s27, 5
	s_and_b32 s56, s25, 0x60
	s_lshl_b32 s55, s28, 6
	s_lshl_b32 s25, s56, 7
	v_bitop3_b32 v146, v2, s25, v3 bitop3:0xde
	s_cmp_gt_i32 s24, 63
	v_add_u32_e32 v2, v20, v18
	s_waitcnt vmcnt(6)
	s_cselect_b64 s[24:25], -1, 0
	s_add_i32 s57, s51, -2
	v_add_lshl_u32 v180, v2, v19, 1
	v_add_u32_e32 v2, v17, v15
	s_cmpk_lt_u32 s26, 0x100
	v_mov_b32_e32 v140, v138
	v_mov_b32_e32 v141, 0
	v_lshl_add_u64 v[140:141], v[140:141], 0, s[10:11]
	v_add_lshl_u32 v180, v2, v16, 1
	s_cselect_b64 s[26:27], -1, 0
	v_mov_b32_e32 v142, v134
	v_mov_b32_e32 v143, 0
	v_lshl_add_u64 v[142:143], v[142:143], 0, s[10:11]
	s_mov_b32 s58, 0
	v_add_u32_e32 v147, 0, v4
	s_mov_b32 s61, s6
	s_mov_b64 s[28:29], s[34:35]
	v_and_b32_e32 v154, 7, v0
	v_bfe_u32 v155, v0, 4, 2
	v_xor_b32_e32 v155, v155, v154
	v_lshlrev_b32_e32 v155, 4, v155
	v_lshl_add_u32 v155, v154, 7, v155
	v_bfe_u32 v154, v0, 3, 1
	v_lshl_add_u32 v155, v154, 10, v155
	v_lshrrev_b32_e32 v154, 8, v0
	v_lshl_add_u32 v147, v154, 13, v155
	v_bfe_u32 v154, v0, 6, 2
	v_lshl_add_u32 v146, v154, 12, v155
	s_barrier
	s_branch .LBB0_818

.LBB0_824:
	s_add_i32 s64, s40, 2
	s_add_u32 s69, s34, 0x80
	s_addc_u32 s41, s35, 0
	s_add_i32 s74, 0, 0x10000
	s_cmp_eq_u32 s57, s40
	s_cselect_b32 s41, s29, s41
	s_cselect_b32 s40, s28, s69
	v_add_u32_e32 v148, s74, v146
	s_cselect_b32 s71, s31, s63
	s_cselect_b32 s70, s30, s62
	s_add_i32 s69, 0, 0x14000
	ds_read_b128 v[154:157], v148
	ds_read_b128 v[162:165], v148 offset:2048
	v_xor_b32_e32 v148, 64, v148
	ds_read_b128 v[158:161], v148
	ds_read_b128 v[166:169], v148 offset:2048
	v_add_u32_e32 v148, s69, v146
	ds_read_b128 v[170:173], v148
	ds_read_b128 v[190:193], v148 offset:2048
	v_xor_b32_e32 v148, 64, v148
	ds_read_b128 v[174:177], v148
	ds_read_b128 v[194:197], v148 offset:2048
	v_lshl_add_u64 v[148:149], s[34:35], 0, v[140:141]
	s_add_i32 m0, s45, 0xc000
	ds_read_b128 v[198:201], v147
	ds_read_b128 v[206:209], v147 offset:2048
	ds_read_b128 v[214:217], v147 offset:4096
	ds_read_b128 v[238:241], v147 offset:6144
	v_xor_b32_e32 v242, 64, v147
	ds_read_b128 v[202:205], v242
	ds_read_b128 v[210:213], v242 offset:2048
	ds_read_b128 v[218:221], v242 offset:4096
	ds_read_b128 v[242:245], v242 offset:6144
	global_load_lds_dwordx4 v[148:149], off
	v_lshl_add_u64 v[148:149], s[34:35], 0, v[142:143]
	s_add_i32 m0, s45, 0xe000
	s_nop 0
	global_load_lds_dwordx4 v[148:149], off
	s_waitcnt vmcnt(8)
	s_waitcnt lgkmcnt(0)
	s_setprio 1
	s_barrier
	v_mfma_f32_16x16x32_bf16 v[126:129], v[154:157], v[198:201], v[126:129]
	v_mfma_f32_16x16x32_bf16 v[122:125], v[162:165], v[198:201], v[122:125]
	v_mfma_f32_16x16x32_bf16 v[106:109], v[162:165], v[206:209], v[106:109]
	v_mfma_f32_16x16x32_bf16 v[110:113], v[154:157], v[206:209], v[110:113]
	v_mfma_f32_16x16x32_bf16 v[94:97], v[154:157], v[214:217], v[94:97]
	v_mfma_f32_16x16x32_bf16 v[90:93], v[162:165], v[214:217], v[90:93]
	v_mfma_f32_16x16x32_bf16 v[74:77], v[162:165], v[238:241], v[74:77]
	v_mfma_f32_16x16x32_bf16 v[78:81], v[154:157], v[238:241], v[78:81]
	v_mfma_f32_16x16x32_bf16 v[126:129], v[158:161], v[202:205], v[126:129]
	v_mfma_f32_16x16x32_bf16 v[122:125], v[166:169], v[202:205], v[122:125]
	v_mfma_f32_16x16x32_bf16 v[106:109], v[166:169], v[210:213], v[106:109]
	v_mfma_f32_16x16x32_bf16 v[110:113], v[158:161], v[210:213], v[110:113]
	v_mfma_f32_16x16x32_bf16 v[94:97], v[158:161], v[218:221], v[94:97]
	v_mfma_f32_16x16x32_bf16 v[90:93], v[166:169], v[218:221], v[90:93]
	v_mfma_f32_16x16x32_bf16 v[74:77], v[166:169], v[242:245], v[74:77]
	v_mfma_f32_16x16x32_bf16 v[78:81], v[158:161], v[242:245], v[78:81]
	v_mfma_f32_16x16x32_bf16 v[118:121], v[170:173], v[198:201], v[118:121]
	v_mfma_f32_16x16x32_bf16 v[114:117], v[190:193], v[198:201], v[114:117]
	v_mfma_f32_16x16x32_bf16 v[98:101], v[190:193], v[206:209], v[98:101]
	v_mfma_f32_16x16x32_bf16 v[102:105], v[170:173], v[206:209], v[102:105]
	v_mfma_f32_16x16x32_bf16 v[86:89], v[170:173], v[214:217], v[86:89]
	v_mfma_f32_16x16x32_bf16 v[82:85], v[190:193], v[214:217], v[82:85]
	v_mfma_f32_16x16x32_bf16 v[66:69], v[190:193], v[238:241], v[66:69]
	v_mfma_f32_16x16x32_bf16 v[70:73], v[170:173], v[238:241], v[70:73]
	v_mfma_f32_16x16x32_bf16 v[118:121], v[174:177], v[202:205], v[118:121]
	v_mfma_f32_16x16x32_bf16 v[114:117], v[194:197], v[202:205], v[114:117]
	v_mfma_f32_16x16x32_bf16 v[98:101], v[194:197], v[210:213], v[98:101]
	v_mfma_f32_16x16x32_bf16 v[102:105], v[174:177], v[210:213], v[102:105]
	v_mfma_f32_16x16x32_bf16 v[86:89], v[174:177], v[218:221], v[86:89]
	v_mfma_f32_16x16x32_bf16 v[82:85], v[194:197], v[218:221], v[82:85]
	v_mfma_f32_16x16x32_bf16 v[66:69], v[194:197], v[242:245], v[66:69]
	v_mfma_f32_16x16x32_bf16 v[70:73], v[174:177], v[242:245], v[70:73]
	s_barrier
	s_setprio 0
	s_add_i32 s74, s74, s44
	v_lshl_add_u64 v[148:149], s[70:71], 0, v[136:137]
	s_mov_b32 m0, s74
	ds_read_b128 v[198:201], v147 offset:16384
	ds_read_b128 v[206:209], v147 offset:18432
	ds_read_b128 v[214:217], v147 offset:20480
	ds_read_b128 v[238:241], v147 offset:22528
	v_xor_b32_e32 v242, 64, v147
	ds_read_b128 v[202:205], v242 offset:16384
	ds_read_b128 v[210:213], v242 offset:18432
	ds_read_b128 v[218:221], v242 offset:20480
	ds_read_b128 v[242:245], v242 offset:22528
	global_load_lds_dwordx4 v[148:149], off
	s_add_i32 m0, s74, 0x2000
	v_lshl_add_u64 v[178:179], s[70:71], 0, v[132:133]
	s_add_u32 s70, s70, s10
	s_addc_u32 s71, s71, s11
	s_add_i32 s69, s69, s44
	global_load_lds_dwordx4 v[178:179], off
	v_lshl_add_u64 v[222:223], s[70:71], 0, v[136:137]
	s_mov_b32 m0, s69
	v_lshl_add_u64 v[246:247], s[70:71], 0, v[132:133]
	global_load_lds_dwordx4 v[222:223], off
	s_add_i32 m0, s69, 0x2000
	v_lshl_add_u64 v[248:249], s[40:41], 0, v[138:139]
	global_load_lds_dwordx4 v[246:247], off
	s_mov_b32 m0, s45
	v_lshl_add_u64 v[250:251], s[40:41], 0, v[134:135]
	global_load_lds_dwordx4 v[248:249], off
	s_mov_b32 m0, s46
	s_nop 0
	global_load_lds_dwordx4 v[250:251], off
	s_waitcnt vmcnt(8)
	s_waitcnt lgkmcnt(0)
	s_setprio 1
	s_barrier
	v_mfma_f32_16x16x32_bf16 v[62:65], v[154:157], v[198:201], v[62:65]
	v_mfma_f32_16x16x32_bf16 v[58:61], v[162:165], v[198:201], v[58:61]
	v_mfma_f32_16x16x32_bf16 v[42:45], v[162:165], v[206:209], v[42:45]
	v_mfma_f32_16x16x32_bf16 v[46:49], v[154:157], v[206:209], v[46:49]
	v_mfma_f32_16x16x32_bf16 v[30:33], v[154:157], v[214:217], v[30:33]
	v_mfma_f32_16x16x32_bf16 v[26:29], v[162:165], v[214:217], v[26:29]
	v_mfma_f32_16x16x32_bf16 v[10:13], v[162:165], v[238:241], v[10:13]
	v_mfma_f32_16x16x32_bf16 v[14:17], v[154:157], v[238:241], v[14:17]
	v_mfma_f32_16x16x32_bf16 v[62:65], v[158:161], v[202:205], v[62:65]
	v_mfma_f32_16x16x32_bf16 v[58:61], v[166:169], v[202:205], v[58:61]
	v_mfma_f32_16x16x32_bf16 v[42:45], v[166:169], v[210:213], v[42:45]
	v_mfma_f32_16x16x32_bf16 v[46:49], v[158:161], v[210:213], v[46:49]
	v_mfma_f32_16x16x32_bf16 v[30:33], v[158:161], v[218:221], v[30:33]
	v_mfma_f32_16x16x32_bf16 v[26:29], v[166:169], v[218:221], v[26:29]
	v_mfma_f32_16x16x32_bf16 v[10:13], v[166:169], v[242:245], v[10:13]
	v_mfma_f32_16x16x32_bf16 v[14:17], v[158:161], v[242:245], v[14:17]
	v_mfma_f32_16x16x32_bf16 v[54:57], v[170:173], v[198:201], v[54:57]
	v_mfma_f32_16x16x32_bf16 v[50:53], v[190:193], v[198:201], v[50:53]
	v_mfma_f32_16x16x32_bf16 v[34:37], v[190:193], v[206:209], v[34:37]
	v_mfma_f32_16x16x32_bf16 v[38:41], v[170:173], v[206:209], v[38:41]
	v_mfma_f32_16x16x32_bf16 v[22:25], v[170:173], v[214:217], v[22:25]
	v_mfma_f32_16x16x32_bf16 v[18:21], v[190:193], v[214:217], v[18:21]
	v_mfma_f32_16x16x32_bf16 v[2:5], v[190:193], v[238:241], v[2:5]
	v_mfma_f32_16x16x32_bf16 v[6:9], v[170:173], v[238:241], v[6:9]
	v_mfma_f32_16x16x32_bf16 v[54:57], v[174:177], v[202:205], v[54:57]
	v_mfma_f32_16x16x32_bf16 v[50:53], v[194:197], v[202:205], v[50:53]
	v_mfma_f32_16x16x32_bf16 v[34:37], v[194:197], v[210:213], v[34:37]
	v_mfma_f32_16x16x32_bf16 v[38:41], v[174:177], v[210:213], v[38:41]
	v_mfma_f32_16x16x32_bf16 v[22:25], v[174:177], v[218:221], v[22:25]
	v_mfma_f32_16x16x32_bf16 v[18:21], v[194:197], v[218:221], v[18:21]
	v_mfma_f32_16x16x32_bf16 v[2:5], v[194:197], v[242:245], v[2:5]
	v_mfma_f32_16x16x32_bf16 v[6:9], v[174:177], v[242:245], v[6:9]
	s_barrier
	s_setprio 0
	s_add_i32 s69, 0, 0x18000
	v_add_u32_e32 v151, s69, v146
	s_add_i32 s70, 0, 0x1c000
	ds_read_b128 v[154:157], v151
	ds_read_b128 v[162:165], v151 offset:2048
	v_xor_b32_e32 v151, 64, v151
	ds_read_b128 v[158:161], v151
	ds_read_b128 v[166:169], v151 offset:2048
	v_add_u32_e32 v151, s70, v146
	ds_read_b128 v[170:173], v151
	ds_read_b128 v[190:193], v151 offset:2048
	v_xor_b32_e32 v151, 64, v151
	ds_read_b128 v[174:177], v151
	ds_read_b128 v[194:197], v151 offset:2048
	s_add_u32 s40, s40, s10
	s_addc_u32 s41, s41, s11
	s_mov_b32 m0, s47
	v_lshl_add_u64 v[252:253], s[40:41], 0, v[138:139]
	ds_read_b128 v[198:201], v147 offset:32768
	ds_read_b128 v[206:209], v147 offset:34816
	ds_read_b128 v[214:217], v147 offset:36864
	ds_read_b128 v[238:241], v147 offset:38912
	v_xor_b32_e32 v242, 64, v147
	ds_read_b128 v[202:205], v242 offset:32768
	ds_read_b128 v[210:213], v242 offset:34816
	ds_read_b128 v[218:221], v242 offset:36864
	ds_read_b128 v[242:245], v242 offset:38912
	global_load_lds_dwordx4 v[252:253], off
	v_lshl_add_u64 v[252:253], s[40:41], 0, v[134:135]
	s_mov_b32 m0, s48
	s_nop 0
	global_load_lds_dwordx4 v[252:253], off
	s_waitcnt vmcnt(8)
	s_waitcnt lgkmcnt(0)
	s_setprio 1
	s_barrier
	v_mfma_f32_16x16x32_bf16 v[126:129], v[154:157], v[198:201], v[126:129]
	v_mfma_f32_16x16x32_bf16 v[122:125], v[162:165], v[198:201], v[122:125]
	v_mfma_f32_16x16x32_bf16 v[106:109], v[162:165], v[206:209], v[106:109]
	v_mfma_f32_16x16x32_bf16 v[110:113], v[154:157], v[206:209], v[110:113]
	v_mfma_f32_16x16x32_bf16 v[94:97], v[154:157], v[214:217], v[94:97]
	v_mfma_f32_16x16x32_bf16 v[90:93], v[162:165], v[214:217], v[90:93]
	v_mfma_f32_16x16x32_bf16 v[74:77], v[162:165], v[238:241], v[74:77]
	v_mfma_f32_16x16x32_bf16 v[78:81], v[154:157], v[238:241], v[78:81]
	v_mfma_f32_16x16x32_bf16 v[126:129], v[158:161], v[202:205], v[126:129]
	v_mfma_f32_16x16x32_bf16 v[122:125], v[166:169], v[202:205], v[122:125]
	v_mfma_f32_16x16x32_bf16 v[106:109], v[166:169], v[210:213], v[106:109]
	v_mfma_f32_16x16x32_bf16 v[110:113], v[158:161], v[210:213], v[110:113]
	v_mfma_f32_16x16x32_bf16 v[94:97], v[158:161], v[218:221], v[94:97]
	v_mfma_f32_16x16x32_bf16 v[90:93], v[166:169], v[218:221], v[90:93]
	v_mfma_f32_16x16x32_bf16 v[74:77], v[166:169], v[242:245], v[74:77]
	v_mfma_f32_16x16x32_bf16 v[78:81], v[158:161], v[242:245], v[78:81]
	v_mfma_f32_16x16x32_bf16 v[118:121], v[170:173], v[198:201], v[118:121]
	v_mfma_f32_16x16x32_bf16 v[114:117], v[190:193], v[198:201], v[114:117]
	v_mfma_f32_16x16x32_bf16 v[98:101], v[190:193], v[206:209], v[98:101]
	v_mfma_f32_16x16x32_bf16 v[102:105], v[170:173], v[206:209], v[102:105]
	v_mfma_f32_16x16x32_bf16 v[86:89], v[170:173], v[214:217], v[86:89]
	v_mfma_f32_16x16x32_bf16 v[82:85], v[190:193], v[214:217], v[82:85]
	v_mfma_f32_16x16x32_bf16 v[66:69], v[190:193], v[238:241], v[66:69]
	v_mfma_f32_16x16x32_bf16 v[70:73], v[170:173], v[238:241], v[70:73]
	v_mfma_f32_16x16x32_bf16 v[118:121], v[174:177], v[202:205], v[118:121]
	v_mfma_f32_16x16x32_bf16 v[114:117], v[194:197], v[202:205], v[114:117]
	v_mfma_f32_16x16x32_bf16 v[98:101], v[194:197], v[210:213], v[98:101]
	v_mfma_f32_16x16x32_bf16 v[102:105], v[174:177], v[210:213], v[102:105]
	v_mfma_f32_16x16x32_bf16 v[86:89], v[174:177], v[218:221], v[86:89]
	v_mfma_f32_16x16x32_bf16 v[82:85], v[194:197], v[218:221], v[82:85]
	v_mfma_f32_16x16x32_bf16 v[66:69], v[194:197], v[242:245], v[66:69]
	v_mfma_f32_16x16x32_bf16 v[70:73], v[174:177], v[242:245], v[70:73]
	s_barrier
	s_setprio 0
	s_add_i32 s40, s69, s44
	v_lshl_add_u64 v[148:149], v[148:149], 0, s[16:17]
	s_mov_b32 m0, s40
	ds_read_b128 v[198:201], v147 offset:49152
	ds_read_b128 v[206:209], v147 offset:51200
	ds_read_b128 v[214:217], v147 offset:53248
	ds_read_b128 v[238:241], v147 offset:55296
	v_xor_b32_e32 v242, 64, v147
	ds_read_b128 v[202:205], v242 offset:49152
	ds_read_b128 v[210:213], v242 offset:51200
	ds_read_b128 v[218:221], v242 offset:53248
	ds_read_b128 v[242:245], v242 offset:55296
	global_load_lds_dwordx4 v[148:149], off
	v_lshl_add_u64 v[148:149], v[178:179], 0, s[16:17]
	s_add_i32 m0, s40, 0x2000
	s_add_i32 s40, s70, s44
	global_load_lds_dwordx4 v[148:149], off
	v_lshl_add_u64 v[148:149], v[222:223], 0, s[16:17]
	s_mov_b32 m0, s40
	s_nop 0
	global_load_lds_dwordx4 v[148:149], off
	v_lshl_add_u64 v[148:149], v[246:247], 0, s[16:17]
	s_add_i32 m0, s40, 0x2000
	s_nop 0
	global_load_lds_dwordx4 v[148:149], off
	v_lshl_add_u64 v[148:149], v[248:249], 0, s[16:17]
	s_mov_b32 m0, s49
	s_nop 0
	global_load_lds_dwordx4 v[148:149], off
	v_lshl_add_u64 v[148:149], v[250:251], 0, s[16:17]
	s_mov_b32 m0, s50
	s_nop 0
	global_load_lds_dwordx4 v[148:149], off
	s_waitcnt vmcnt(8)
	s_waitcnt lgkmcnt(0)
	s_setprio 1
	s_barrier
	v_mfma_f32_16x16x32_bf16 v[62:65], v[154:157], v[198:201], v[62:65]
	v_mfma_f32_16x16x32_bf16 v[58:61], v[162:165], v[198:201], v[58:61]
	v_mfma_f32_16x16x32_bf16 v[42:45], v[162:165], v[206:209], v[42:45]
	v_mfma_f32_16x16x32_bf16 v[46:49], v[154:157], v[206:209], v[46:49]
	v_mfma_f32_16x16x32_bf16 v[30:33], v[154:157], v[214:217], v[30:33]
	v_mfma_f32_16x16x32_bf16 v[26:29], v[162:165], v[214:217], v[26:29]
	v_mfma_f32_16x16x32_bf16 v[10:13], v[162:165], v[238:241], v[10:13]
	v_mfma_f32_16x16x32_bf16 v[14:17], v[154:157], v[238:241], v[14:17]
	v_mfma_f32_16x16x32_bf16 v[62:65], v[158:161], v[202:205], v[62:65]
	v_mfma_f32_16x16x32_bf16 v[58:61], v[166:169], v[202:205], v[58:61]
	v_mfma_f32_16x16x32_bf16 v[42:45], v[166:169], v[210:213], v[42:45]
	v_mfma_f32_16x16x32_bf16 v[46:49], v[158:161], v[210:213], v[46:49]
	v_mfma_f32_16x16x32_bf16 v[30:33], v[158:161], v[218:221], v[30:33]
	v_mfma_f32_16x16x32_bf16 v[26:29], v[166:169], v[218:221], v[26:29]
	v_mfma_f32_16x16x32_bf16 v[10:13], v[166:169], v[242:245], v[10:13]
	v_mfma_f32_16x16x32_bf16 v[14:17], v[158:161], v[242:245], v[14:17]
	v_mfma_f32_16x16x32_bf16 v[54:57], v[170:173], v[198:201], v[54:57]
	v_mfma_f32_16x16x32_bf16 v[50:53], v[190:193], v[198:201], v[50:53]
	v_mfma_f32_16x16x32_bf16 v[34:37], v[190:193], v[206:209], v[34:37]
	v_mfma_f32_16x16x32_bf16 v[38:41], v[170:173], v[206:209], v[38:41]
	v_mfma_f32_16x16x32_bf16 v[22:25], v[170:173], v[214:217], v[22:25]
	v_mfma_f32_16x16x32_bf16 v[18:21], v[190:193], v[214:217], v[18:21]
	v_mfma_f32_16x16x32_bf16 v[2:5], v[190:193], v[238:241], v[2:5]
	v_mfma_f32_16x16x32_bf16 v[6:9], v[170:173], v[238:241], v[6:9]
	v_mfma_f32_16x16x32_bf16 v[54:57], v[174:177], v[202:205], v[54:57]
	v_mfma_f32_16x16x32_bf16 v[50:53], v[194:197], v[202:205], v[50:53]
	v_mfma_f32_16x16x32_bf16 v[34:37], v[194:197], v[210:213], v[34:37]
	v_mfma_f32_16x16x32_bf16 v[38:41], v[174:177], v[210:213], v[38:41]
	v_mfma_f32_16x16x32_bf16 v[22:25], v[174:177], v[218:221], v[22:25]
	v_mfma_f32_16x16x32_bf16 v[18:21], v[194:197], v[218:221], v[18:21]
	v_mfma_f32_16x16x32_bf16 v[2:5], v[194:197], v[242:245], v[2:5]
	v_mfma_f32_16x16x32_bf16 v[6:9], v[174:177], v[242:245], v[6:9]
	s_barrier
	s_setprio 0
	s_add_u32 s34, s34, 0x100
	s_addc_u32 s35, s35, 0
	s_add_u32 s62, s62, 0x100
	s_addc_u32 s63, s63, 0
	s_cmp_ge_i32 s64, s51
	s_mov_b32 s40, s64
	s_cbranch_scc0 .LBB0_824
	v_readlane_b32 s64, v255, 40
	s_mov_b32 s68, 0xff61b1e6
	s_mov_b32 s74, 0x24600000
	s_mov_b32 s69, 0xcf800000

.LBB0_921:
	v_ashrrev_i32_e32 v3, 31, v15
	v_lshrrev_b32_e32 v3, 26, v3
	v_add_u32_e32 v3, v15, v3
	v_ashrrev_i32_e32 v10, 6, v3
	v_bfe_i32 v3, v15, 27, 1
	v_lshlrev_b32_e32 v2, 4, v15
	v_lshrrev_b32_e32 v3, 22, v3
	v_add_u32_e32 v3, v2, v3
	v_and_b32_e32 v3, 0xfffffc00, v3
	v_sub_u32_e32 v3, v2, v3
	v_lshrrev_b32_e32 v4, 4, v3
	v_bitop3_b32 v3, v4, v3, 32 bitop3:0x6c
	v_ashrrev_i32_e32 v5, 31, v3
	v_lshrrev_b32_e32 v5, 26, v5
	v_lshlrev_b32_e32 v4, 3, v10
	v_add_u32_e32 v5, v3, v5
	v_and_b32_e32 v4, -16, v4
	v_ashrrev_i32_e32 v12, 6, v5
	v_and_b32_e32 v5, 0xc0, v5
	v_readlane_b32 s8, v255, 41
	v_add_u32_e32 v4, v12, v4
	v_lshlrev_b32_e32 v6, 5, v10
	v_sub_u32_e32 v3, v3, v5
	s_mul_i32 s12, s8, 0x240000
	s_waitcnt lgkmcnt(0)
	s_add_u32 s10, s22, 0x39600000
	v_and_b32_e32 v11, 32, v6
	v_ashrrev_i16_sdwa v3, v224, sext(v3) dst_sel:DWORD dst_unused:UNUSED_PAD src0_sel:DWORD src1_sel:BYTE_0
	v_lshlrev_b32_e32 v5, 1, v4
	v_lshrrev_b32_e32 v6, 2, v4
	v_and_b32_e32 v7, 3, v12
	s_mov_b32 s21, 0x7fffe0
	s_addc_u32 s11, s23, 0
	s_lshl_b64 s[8:9], s[12:13], 1
	v_bfe_i32 v13, v3, 0, 16
	v_and_b32_e32 v5, 24, v5
	v_and_b32_e32 v6, 4, v6
	v_and_or_b32 v7, v4, s21, v7
	s_movk_i32 s12, 0x600
	v_add_u32_e32 v3, v11, v13
	v_or3_b32 v5, v7, v6, v5
	v_mul_lo_u32 v4, v4, s12
	s_waitcnt vmcnt(1)
	v_add_lshl_u32 v130, v3, v4, 1
	v_mul_u32_u24_e32 v4, 0x600, v5
	v_add_u32_e32 v2, 0x2000, v2
	v_add_lshl_u32 v180, v4, v3, 1
	v_ashrrev_i32_e32 v3, 31, v2
	v_lshrrev_b32_e32 v3, 22, v3
	v_add_u32_e32 v3, v2, v3
	v_ashrrev_i32_e32 v14, 10, v3
	v_mul_i32_i24_e32 v3, 0x400, v14
	v_sub_u32_e32 v2, v2, v3
	v_lshrrev_b32_e32 v3, 4, v2
	v_bitop3_b32 v2, v3, v2, 32 bitop3:0x6c
	v_ashrrev_i32_e32 v4, 31, v2
	v_lshrrev_b32_e32 v4, 26, v4
	s_add_u32 s8, s22, s8
	v_lshlrev_b32_e32 v3, 3, v14
	v_add_u32_e32 v4, v2, v4
	s_addc_u32 s9, s23, s9
	v_and_b32_e32 v3, -16, v3
	v_ashrrev_i32_e32 v17, 6, v4
	s_add_u32 s8, s8, 0x4d00000
	v_add_u32_e32 v3, v17, v3
	v_lshlrev_b32_e32 v5, 5, v14
	v_and_b32_e32 v4, 0xc0, v4
	v_and_b32_e32 v6, 3, v17
	s_addc_u32 s9, s9, 0
	v_and_b32_e32 v16, 32, v5
	v_sub_u32_e32 v2, v2, v4
	v_lshlrev_b32_e32 v4, 1, v3
	v_lshrrev_b32_e32 v5, 2, v3
	v_and_or_b32 v6, v3, s21, v6
	v_mul_lo_u32 v3, v3, s12
	s_add_i32 s12, s14, s15
	s_mul_hi_i32 s14, s12, 0x2aaaaaab
	s_lshr_b32 s15, s14, 31
	s_ashr_i32 s14, s14, 3
	v_ashrrev_i16_sdwa v2, v224, sext(v2) dst_sel:DWORD dst_unused:UNUSED_PAD src0_sel:DWORD src1_sel:BYTE_0
	s_add_i32 s14, s14, s15
	v_bfe_i32 v18, v2, 0, 16
	v_and_b32_e32 v4, 24, v4
	v_and_b32_e32 v5, 4, v5
	s_lshl_b32 s27, s14, 3
	v_add_u32_e32 v2, v16, v18
	v_or3_b32 v4, v6, v5, v4
	s_sub_i32 s15, 33, s27
	s_waitcnt vmcnt(0)
	v_add_lshl_u32 v132, v2, v3, 1
	v_mul_u32_u24_e32 v3, 0x600, v4
	s_min_u32 s28, s15, 8
	s_mul_i32 s14, s14, 48
	v_add_lshl_u32 v134, v3, v2, 1
	s_sub_i32 s29, s12, s14
	v_cvt_f32_ubyte0_e32 v3, s28
	v_cvt_f32_i32_e32 v2, s29
	v_rcp_iflag_f32_e32 v4, v3
	s_ashr_i32 s26, s24, 6
	s_ashr_i32 s12, s29, 30
	s_ashr_i32 s25, s24, 8
	v_mul_f32_e32 v4, v2, v4
	v_trunc_f32_e32 v4, v4
	v_fma_f32 v2, -v4, v3, v2
	v_cvt_i32_f32_e32 v4, v4
	s_lshl_b32 s21, s26, 10
	s_or_b32 s12, s12, 1
	v_cmp_ge_f32_e64 s[14:15], |v2|, v3
	s_and_b64 s[14:15], s[14:15], exec
	s_cselect_b32 s12, s12, 0
	v_readfirstlane_b32 s14, v4
	s_add_i32 s12, s14, s12
	s_mul_i32 s14, s12, s28
	s_sub_i32 s14, s29, s14
	s_sext_i32_i8 s14, s14
	s_add_i32 s56, s27, s14
	s_bfe_i64 s[14:15], s[12:13], 0x80000
	s_mul_hi_i32 s15, s14, 0xc0000
	s_mul_i32 s14, s14, 0xc0000
	s_add_u32 s34, s8, s14
	s_addc_u32 s35, s9, s15
	s_add_i32 s44, s21, 0
	s_add_i32 m0, s44, 0x10000
	s_mul_i32 s28, s56, 0xc0000
	v_and_b32_e32 v140, 63, v0
	v_lshrrev_b32_e32 v141, 3, v140
	v_and_b32_e32 v140, 7, v140
	v_xor_b32_e32 v140, v140, v141
	v_lshlrev_b32_e32 v140, 4, v140
	v_lshrrev_b32_e32 v142, 6, v0
	v_lshl_add_u32 v141, v142, 3, v141
	v_mov_b32_e32 v142, 0xc00
	v_mad_u32_u24 v130, v141, v142, v140
	v_add_u32_e32 v132, 0x30000, v130
	v_and_b32_e32 v143, 15, v141
	v_lshrrev_b32_e32 v142, 2, v143
	v_and_b32_e32 v143, 3, v143
	v_lshl_add_u32 v143, v142, 3, v143
	v_bfe_u32 v142, v141, 4, 1
	v_lshl_add_u32 v143, v142, 2, v143
	v_and_b32_e32 v142, 0x60, v141
	v_or_b32_e32 v143, v142, v143
	v_mov_b32_e32 v142, 0xc00
	v_mad_u32_u24 v180, v143, v142, v140
	v_add_u32_e32 v134, 0x30000, v180
	global_load_lds_dwordx4 v180, s[34:35]
	s_add_i32 m0, s44, 0x12000
	s_add_u32 s14, s34, 0x60000
	global_load_lds_dwordx4 v134, s[34:35]
	s_addc_u32 s15, s35, 0
	s_add_i32 m0, s44, 0x14000
	s_mul_hi_i32 s27, s56, 0xc0000
	global_load_lds_dwordx4 v180, s[14:15]
	s_add_i32 m0, s44, 0x16000
	s_add_u32 s30, s10, s28
	s_addc_u32 s31, s11, s27
	s_add_i32 s45, s44, 0x2000
	global_load_lds_dwordx4 v134, s[14:15]
	s_mov_b32 m0, s44
	s_add_u32 s14, s30, 0x60000
	global_load_lds_dwordx4 v130, s[30:31]
	s_mov_b32 m0, s45
	s_addc_u32 s15, s31, 0
	s_add_i32 s46, s44, 0x4000
	global_load_lds_dwordx4 v132, s[30:31]
	s_mov_b32 m0, s46
	s_add_i32 s47, s44, 0x6000
	global_load_lds_dwordx4 v130, s[14:15]
	s_mov_b32 m0, s47
	v_mov_b32_e32 v135, v181
	global_load_lds_dwordx4 v132, s[14:15]
	v_mov_b32_e32 v131, v181
	v_mov_b32_e32 v133, v181
	s_cmp_eq_u32 s25, 1
	v_lshl_add_u64 v[8:9], s[34:35], 0, v[180:181]
	v_lshl_add_u64 v[6:7], s[34:35], 0, v[134:135]
	v_lshl_add_u64 v[2:3], s[30:31], 0, v[130:131]
	s_cselect_b64 s[14:15], -1, 0
	s_cmp_lg_u32 s25, 1
	v_lshl_add_u64 v[4:5], s[30:31], 0, v[132:133]
	s_cbranch_scc1 .LBB0_923
	s_barrier
.LBB0_923:
	s_sext_i32_i8 s57, s12
	v_readlane_b32 s12, v255, 41
	s_mulk_i32 s12, 0x600
	s_lshl_b64 s[28:29], s[12:13], 2
	s_add_u32 s18, s18, s28
	s_addc_u32 s19, s19, s29
	v_bfe_u32 v149, v15, 4, 2
	s_add_u32 s22, s22, 0x24600000
	v_and_b32_e32 v148, 15, v15
	v_lshlrev_b32_e32 v19, 4, v149
	v_lshlrev_b32_e32 v15, 2, v15
	s_addc_u32 s23, s23, 0
	s_lshl_b32 s12, s25, 6
	v_lshl_or_b32 v19, v148, 6, v19
	s_lshl_b32 s25, s25, 13
	v_and_b32_e32 v15, 32, v15
	v_bitop3_b32 v20, v19, s25, v15 bitop3:0xde
	s_lshl_b32 s25, s26, 5
	s_and_b32 s48, s25, 0x60
	s_add_i32 m0, s44, 0x18000
	v_lshl_add_u64 v[8:9], v[8:9], 0, s[16:17]
	s_lshl_b32 s25, s48, 7
	s_waitcnt vmcnt(2)
	s_barrier
	global_load_lds_dwordx4 v[8:9], off
	v_lshl_add_u64 v[6:7], v[6:7], 0, s[16:17]
	s_add_i32 m0, s44, 0x1a000
	s_add_i32 s49, s44, 0x8000
	s_add_i32 s50, s44, 0xa000
	global_load_lds_dwordx4 v[6:7], off
	v_lshl_add_u64 v[2:3], v[2:3], 0, s[16:17]
	s_mov_b32 m0, s49
	s_add_u32 s26, s34, 0x60080
	global_load_lds_dwordx4 v[2:3], off
	v_lshl_add_u64 v[2:3], v[4:5], 0, s[16:17]
	s_mov_b32 m0, s50
	s_addc_u32 s27, s35, 0
	global_load_lds_dwordx4 v[2:3], off
	s_add_i32 m0, s44, 0x1c000
	v_lshl_add_u64 v[2:3], s[26:27], 0, v[180:181]
	global_load_lds_dwordx4 v[2:3], off
	v_lshl_add_u64 v[2:3], s[26:27], 0, v[134:135]
	s_add_i32 m0, s44, 0x1e000
	s_movk_i32 s29, 0x600
	global_load_lds_dwordx4 v[2:3], off
	v_lshrrev_b32_e32 v3, 1, v10
	v_mul_lo_u32 v2, v12, s29
	s_movk_i32 s28, 0x6000
	v_mad_u64_u32 v[2:3], s[26:27], v3, s28, v[2:3]
	v_or_b32_e32 v2, v2, v11
	v_add_lshl_u32 v2, v2, v13, 1
	v_mov_b32_e32 v3, v181
	s_mov_b64 s[36:37], 0x60080
	v_mov_b32_e32 v136, v130
	v_mov_b32_e32 v137, 0
	v_lshl_add_u64 v[136:137], v[136:137], 0, s[36:37]
	v_lshrrev_b32_e32 v3, 1, v14
	v_mul_lo_u32 v2, v17, s29
	v_mad_u64_u32 v[2:3], s[26:27], v3, s28, v[2:3]
	s_waitcnt vmcnt(6)
	v_or_b32_e32 v2, v2, v16
	s_cmpk_lt_u32 s24, 0x100
	v_add_lshl_u32 v2, v2, v18, 1
	v_mov_b32_e32 v3, v181
	v_bitop3_b32 v150, v19, s25, v15 bitop3:0xde
	s_cselect_b64 s[24:25], -1, 0
	v_mov_b32_e32 v138, v132
	v_mov_b32_e32 v139, 0
	v_lshl_add_u64 v[138:139], v[138:139], 0, s[36:37]
	s_mov_b32 s51, 0
	v_add_u32_e32 v151, 0, v20
	v_and_b32_e32 v140, 7, v0
	v_bfe_u32 v141, v0, 4, 2
	v_xor_b32_e32 v141, v141, v140
	v_lshlrev_b32_e32 v141, 4, v141
	v_lshl_add_u32 v141, v140, 7, v141
	v_bfe_u32 v140, v0, 3, 1
	v_lshl_add_u32 v141, v140, 10, v141
	v_lshrrev_b32_e32 v140, 8, v0
	v_lshl_add_u32 v151, v140, 13, v141
	v_bfe_u32 v140, v0, 6, 2
	v_lshl_add_u32 v150, v140, 12, v141
	s_barrier
	s_branch .LBB0_926

.LBB0_937:
	s_add_u32 s34, s30, 0x100
	s_addc_u32 s35, s31, 0
	s_add_i32 s61, 0, 0x10000
	s_cmp_eq_u32 s60, 20
	s_cselect_b32 s43, s27, s35
	s_cselect_b32 s42, s26, s34
	s_cselect_b32 s41, s29, s59
	s_cselect_b32 s40, s28, s58
	s_add_i32 s62, 0, 0x14000
	v_add_u32_e32 v156, s61, v150
	v_add_u32_e32 v172, s62, v150
	ds_read_b128 v[140:143], v156
	ds_read_b128 v[152:155], v156 offset:2048
	v_xor_b32_e32 v156, 64, v156
	ds_read_b128 v[144:147], v156
	ds_read_b128 v[156:159], v156 offset:2048
	ds_read_b128 v[160:163], v172
	ds_read_b128 v[168:171], v172 offset:2048
	v_xor_b32_e32 v172, 64, v172
	ds_read_b128 v[164:167], v172
	ds_read_b128 v[172:175], v172 offset:2048
	v_lshl_add_u64 v[218:219], s[30:31], 0, v[136:137]
	s_add_i32 m0, s44, 0xc000
	ds_read_b128 v[176:179], v151
	ds_read_b128 v[194:197], v151 offset:2048
	ds_read_b128 v[202:205], v151 offset:4096
	ds_read_b128 v[210:213], v151 offset:6144
	v_xor_b32_e32 v214, 64, v151
	ds_read_b128 v[190:193], v214
	ds_read_b128 v[198:201], v214 offset:2048
	ds_read_b128 v[206:209], v214 offset:4096
	ds_read_b128 v[214:217], v214 offset:6144
	global_load_lds_dwordx4 v[218:219], off
	v_lshl_add_u64 v[218:219], s[30:31], 0, v[138:139]
	s_add_i32 m0, s44, 0xe000
	s_nop 0
	global_load_lds_dwordx4 v[218:219], off
	s_waitcnt vmcnt(8)
	s_waitcnt lgkmcnt(0)
	s_setprio 1
	s_barrier
	v_mfma_f32_16x16x32_bf16 v[126:129], v[140:143], v[176:179], v[126:129]
	v_mfma_f32_16x16x32_bf16 v[122:125], v[152:155], v[176:179], v[122:125]
	v_mfma_f32_16x16x32_bf16 v[106:109], v[152:155], v[194:197], v[106:109]
	v_mfma_f32_16x16x32_bf16 v[110:113], v[140:143], v[194:197], v[110:113]
	v_mfma_f32_16x16x32_bf16 v[94:97], v[140:143], v[202:205], v[94:97]
	v_mfma_f32_16x16x32_bf16 v[90:93], v[152:155], v[202:205], v[90:93]
	v_mfma_f32_16x16x32_bf16 v[74:77], v[152:155], v[210:213], v[74:77]
	v_mfma_f32_16x16x32_bf16 v[78:81], v[140:143], v[210:213], v[78:81]
	v_mfma_f32_16x16x32_bf16 v[126:129], v[144:147], v[190:193], v[126:129]
	v_mfma_f32_16x16x32_bf16 v[122:125], v[156:159], v[190:193], v[122:125]
	v_mfma_f32_16x16x32_bf16 v[106:109], v[156:159], v[198:201], v[106:109]
	v_mfma_f32_16x16x32_bf16 v[110:113], v[144:147], v[198:201], v[110:113]
	v_mfma_f32_16x16x32_bf16 v[94:97], v[144:147], v[206:209], v[94:97]
	v_mfma_f32_16x16x32_bf16 v[90:93], v[156:159], v[206:209], v[90:93]
	v_mfma_f32_16x16x32_bf16 v[74:77], v[156:159], v[214:217], v[74:77]
	v_mfma_f32_16x16x32_bf16 v[78:81], v[144:147], v[214:217], v[78:81]
	v_mfma_f32_16x16x32_bf16 v[118:121], v[160:163], v[176:179], v[118:121]
	v_mfma_f32_16x16x32_bf16 v[114:117], v[168:171], v[176:179], v[114:117]
	v_mfma_f32_16x16x32_bf16 v[98:101], v[168:171], v[194:197], v[98:101]
	v_mfma_f32_16x16x32_bf16 v[102:105], v[160:163], v[194:197], v[102:105]
	v_mfma_f32_16x16x32_bf16 v[86:89], v[160:163], v[202:205], v[86:89]
	v_mfma_f32_16x16x32_bf16 v[82:85], v[168:171], v[202:205], v[82:85]
	v_mfma_f32_16x16x32_bf16 v[66:69], v[168:171], v[210:213], v[66:69]
	v_mfma_f32_16x16x32_bf16 v[70:73], v[160:163], v[210:213], v[70:73]
	v_mfma_f32_16x16x32_bf16 v[118:121], v[164:167], v[190:193], v[118:121]
	v_mfma_f32_16x16x32_bf16 v[114:117], v[172:175], v[190:193], v[114:117]
	v_mfma_f32_16x16x32_bf16 v[98:101], v[172:175], v[198:201], v[98:101]
	v_mfma_f32_16x16x32_bf16 v[102:105], v[164:167], v[198:201], v[102:105]
	v_mfma_f32_16x16x32_bf16 v[86:89], v[164:167], v[206:209], v[86:89]
	v_mfma_f32_16x16x32_bf16 v[82:85], v[172:175], v[206:209], v[82:85]
	v_mfma_f32_16x16x32_bf16 v[66:69], v[172:175], v[214:217], v[66:69]
	v_mfma_f32_16x16x32_bf16 v[70:73], v[164:167], v[214:217], v[70:73]
	s_barrier
	s_setprio 0
	s_add_i32 s30, s61, s21
	v_lshl_add_u64 v[218:219], s[40:41], 0, v[180:181]
	s_mov_b32 m0, s30
	ds_read_b128 v[176:179], v151 offset:16384
	ds_read_b128 v[194:197], v151 offset:18432
	ds_read_b128 v[202:205], v151 offset:20480
	ds_read_b128 v[210:213], v151 offset:22528
	v_xor_b32_e32 v214, 64, v151
	ds_read_b128 v[190:193], v214 offset:16384
	ds_read_b128 v[198:201], v214 offset:18432
	ds_read_b128 v[206:209], v214 offset:20480
	ds_read_b128 v[214:217], v214 offset:22528
	global_load_lds_dwordx4 v[218:219], off
	s_add_i32 m0, s30, 0x2000
	s_add_u32 s30, s40, 0x60000
	v_lshl_add_u64 v[220:221], s[40:41], 0, v[134:135]
	s_addc_u32 s31, s41, 0
	s_add_i32 s61, s62, s21
	global_load_lds_dwordx4 v[220:221], off
	v_lshl_add_u64 v[222:223], s[30:31], 0, v[180:181]
	s_mov_b32 m0, s61
	v_lshl_add_u64 v[238:239], s[42:43], 0, v[132:133]
	global_load_lds_dwordx4 v[222:223], off
	v_lshl_add_u64 v[222:223], s[30:31], 0, v[134:135]
	s_add_i32 m0, s61, 0x2000
	s_nop 0
	global_load_lds_dwordx4 v[222:223], off
	v_lshl_add_u64 v[222:223], s[42:43], 0, v[130:131]
	s_mov_b32 m0, s44
	s_nop 0
	global_load_lds_dwordx4 v[222:223], off
	s_mov_b32 m0, s45
	s_nop 0
	global_load_lds_dwordx4 v[238:239], off
	s_waitcnt vmcnt(8)
	s_waitcnt lgkmcnt(0)
	s_setprio 1
	s_barrier
	v_mfma_f32_16x16x32_bf16 v[62:65], v[140:143], v[176:179], v[62:65]
	v_mfma_f32_16x16x32_bf16 v[58:61], v[152:155], v[176:179], v[58:61]
	v_mfma_f32_16x16x32_bf16 v[42:45], v[152:155], v[194:197], v[42:45]
	v_mfma_f32_16x16x32_bf16 v[46:49], v[140:143], v[194:197], v[46:49]
	v_mfma_f32_16x16x32_bf16 v[30:33], v[140:143], v[202:205], v[30:33]
	v_mfma_f32_16x16x32_bf16 v[26:29], v[152:155], v[202:205], v[26:29]
	v_mfma_f32_16x16x32_bf16 v[10:13], v[152:155], v[210:213], v[10:13]
	v_mfma_f32_16x16x32_bf16 v[14:17], v[140:143], v[210:213], v[14:17]
	v_mfma_f32_16x16x32_bf16 v[62:65], v[144:147], v[190:193], v[62:65]
	v_mfma_f32_16x16x32_bf16 v[58:61], v[156:159], v[190:193], v[58:61]
	v_mfma_f32_16x16x32_bf16 v[42:45], v[156:159], v[198:201], v[42:45]
	v_mfma_f32_16x16x32_bf16 v[46:49], v[144:147], v[198:201], v[46:49]
	v_mfma_f32_16x16x32_bf16 v[30:33], v[144:147], v[206:209], v[30:33]
	v_mfma_f32_16x16x32_bf16 v[26:29], v[156:159], v[206:209], v[26:29]
	v_mfma_f32_16x16x32_bf16 v[10:13], v[156:159], v[214:217], v[10:13]
	v_mfma_f32_16x16x32_bf16 v[14:17], v[144:147], v[214:217], v[14:17]
	v_mfma_f32_16x16x32_bf16 v[54:57], v[160:163], v[176:179], v[54:57]
	v_mfma_f32_16x16x32_bf16 v[50:53], v[168:171], v[176:179], v[50:53]
	v_mfma_f32_16x16x32_bf16 v[34:37], v[168:171], v[194:197], v[34:37]
	v_mfma_f32_16x16x32_bf16 v[38:41], v[160:163], v[194:197], v[38:41]
	v_mfma_f32_16x16x32_bf16 v[22:25], v[160:163], v[202:205], v[22:25]
	v_mfma_f32_16x16x32_bf16 v[18:21], v[168:171], v[202:205], v[18:21]
	v_mfma_f32_16x16x32_bf16 v[2:5], v[168:171], v[210:213], v[2:5]
	v_mfma_f32_16x16x32_bf16 v[6:9], v[160:163], v[210:213], v[6:9]
	v_mfma_f32_16x16x32_bf16 v[54:57], v[164:167], v[190:193], v[54:57]
	v_mfma_f32_16x16x32_bf16 v[50:53], v[172:175], v[190:193], v[50:53]
	v_mfma_f32_16x16x32_bf16 v[34:37], v[172:175], v[198:201], v[34:37]
	v_mfma_f32_16x16x32_bf16 v[38:41], v[164:167], v[198:201], v[38:41]
	v_mfma_f32_16x16x32_bf16 v[22:25], v[164:167], v[206:209], v[22:25]
	v_mfma_f32_16x16x32_bf16 v[18:21], v[172:175], v[206:209], v[18:21]
	v_mfma_f32_16x16x32_bf16 v[2:5], v[172:175], v[214:217], v[2:5]
	v_mfma_f32_16x16x32_bf16 v[6:9], v[164:167], v[214:217], v[6:9]
	s_barrier
	s_setprio 0
	s_add_i32 s61, 0, 0x18000
	s_add_i32 s62, 0, 0x1c000
	v_add_u32_e32 v156, s61, v150
	v_add_u32_e32 v172, s62, v150
	ds_read_b128 v[140:143], v156
	ds_read_b128 v[152:155], v156 offset:2048
	v_xor_b32_e32 v156, 64, v156
	ds_read_b128 v[144:147], v156
	ds_read_b128 v[156:159], v156 offset:2048
	ds_read_b128 v[160:163], v172
	ds_read_b128 v[168:171], v172 offset:2048
	v_xor_b32_e32 v172, 64, v172
	ds_read_b128 v[164:167], v172
	ds_read_b128 v[172:175], v172 offset:2048
	s_add_u32 s30, s42, 0x60000
	s_addc_u32 s31, s43, 0
	s_mov_b32 m0, s46
	v_lshl_add_u64 v[240:241], s[30:31], 0, v[130:131]
	ds_read_b128 v[176:179], v151 offset:32768
	ds_read_b128 v[194:197], v151 offset:34816
	ds_read_b128 v[202:205], v151 offset:36864
	ds_read_b128 v[210:213], v151 offset:38912
	v_xor_b32_e32 v214, 64, v151
	ds_read_b128 v[190:193], v214 offset:32768
	ds_read_b128 v[198:201], v214 offset:34816
	ds_read_b128 v[206:209], v214 offset:36864
	ds_read_b128 v[214:217], v214 offset:38912
	global_load_lds_dwordx4 v[240:241], off
	v_lshl_add_u64 v[240:241], s[30:31], 0, v[132:133]
	s_mov_b32 m0, s47
	s_nop 0
	global_load_lds_dwordx4 v[240:241], off
	s_waitcnt vmcnt(8)
	s_waitcnt lgkmcnt(0)
	s_setprio 1
	s_barrier
	v_mfma_f32_16x16x32_bf16 v[126:129], v[140:143], v[176:179], v[126:129]
	v_mfma_f32_16x16x32_bf16 v[122:125], v[152:155], v[176:179], v[122:125]
	v_mfma_f32_16x16x32_bf16 v[106:109], v[152:155], v[194:197], v[106:109]
	v_mfma_f32_16x16x32_bf16 v[110:113], v[140:143], v[194:197], v[110:113]
	v_mfma_f32_16x16x32_bf16 v[94:97], v[140:143], v[202:205], v[94:97]
	v_mfma_f32_16x16x32_bf16 v[90:93], v[152:155], v[202:205], v[90:93]
	v_mfma_f32_16x16x32_bf16 v[74:77], v[152:155], v[210:213], v[74:77]
	v_mfma_f32_16x16x32_bf16 v[78:81], v[140:143], v[210:213], v[78:81]
	v_mfma_f32_16x16x32_bf16 v[126:129], v[144:147], v[190:193], v[126:129]
	v_mfma_f32_16x16x32_bf16 v[122:125], v[156:159], v[190:193], v[122:125]
	v_mfma_f32_16x16x32_bf16 v[106:109], v[156:159], v[198:201], v[106:109]
	v_mfma_f32_16x16x32_bf16 v[110:113], v[144:147], v[198:201], v[110:113]
	v_mfma_f32_16x16x32_bf16 v[94:97], v[144:147], v[206:209], v[94:97]
	v_mfma_f32_16x16x32_bf16 v[90:93], v[156:159], v[206:209], v[90:93]
	v_mfma_f32_16x16x32_bf16 v[74:77], v[156:159], v[214:217], v[74:77]
	v_mfma_f32_16x16x32_bf16 v[78:81], v[144:147], v[214:217], v[78:81]
	v_mfma_f32_16x16x32_bf16 v[118:121], v[160:163], v[176:179], v[118:121]
	v_mfma_f32_16x16x32_bf16 v[114:117], v[168:171], v[176:179], v[114:117]
	v_mfma_f32_16x16x32_bf16 v[98:101], v[168:171], v[194:197], v[98:101]
	v_mfma_f32_16x16x32_bf16 v[102:105], v[160:163], v[194:197], v[102:105]
	v_mfma_f32_16x16x32_bf16 v[86:89], v[160:163], v[202:205], v[86:89]
	v_mfma_f32_16x16x32_bf16 v[82:85], v[168:171], v[202:205], v[82:85]
	v_mfma_f32_16x16x32_bf16 v[66:69], v[168:171], v[210:213], v[66:69]
	v_mfma_f32_16x16x32_bf16 v[70:73], v[160:163], v[210:213], v[70:73]
	v_mfma_f32_16x16x32_bf16 v[118:121], v[164:167], v[190:193], v[118:121]
	v_mfma_f32_16x16x32_bf16 v[114:117], v[172:175], v[190:193], v[114:117]
	v_mfma_f32_16x16x32_bf16 v[98:101], v[172:175], v[198:201], v[98:101]
	v_mfma_f32_16x16x32_bf16 v[102:105], v[164:167], v[198:201], v[102:105]
	v_mfma_f32_16x16x32_bf16 v[86:89], v[164:167], v[206:209], v[86:89]
	v_mfma_f32_16x16x32_bf16 v[82:85], v[172:175], v[206:209], v[82:85]
	v_mfma_f32_16x16x32_bf16 v[66:69], v[172:175], v[214:217], v[66:69]
	v_mfma_f32_16x16x32_bf16 v[70:73], v[164:167], v[214:217], v[70:73]
	s_barrier
	s_setprio 0
	s_add_i32 s30, s61, s21
	v_lshl_add_u64 v[218:219], v[218:219], 0, s[16:17]
	s_mov_b32 m0, s30
	ds_read_b128 v[176:179], v151 offset:49152
	ds_read_b128 v[194:197], v151 offset:51200
	ds_read_b128 v[202:205], v151 offset:53248
	ds_read_b128 v[210:213], v151 offset:55296
	v_xor_b32_e32 v214, 64, v151
	ds_read_b128 v[190:193], v214 offset:49152
	ds_read_b128 v[198:201], v214 offset:51200
	ds_read_b128 v[206:209], v214 offset:53248
	ds_read_b128 v[214:217], v214 offset:55296
	global_load_lds_dwordx4 v[218:219], off
	s_add_i32 m0, s30, 0x2000
	s_add_u32 s30, s40, 0x60080
	v_lshl_add_u64 v[218:219], v[220:221], 0, s[16:17]
	s_addc_u32 s31, s41, 0
	s_add_i32 s40, s62, s21
	global_load_lds_dwordx4 v[218:219], off
	v_lshl_add_u64 v[218:219], s[30:31], 0, v[180:181]
	s_mov_b32 m0, s40
	s_nop 0
	global_load_lds_dwordx4 v[218:219], off
	v_lshl_add_u64 v[218:219], s[30:31], 0, v[134:135]
	s_add_i32 m0, s40, 0x2000
	s_nop 0
	global_load_lds_dwordx4 v[218:219], off
	v_lshl_add_u64 v[218:219], v[222:223], 0, s[16:17]
	s_mov_b32 m0, s49
	s_nop 0
	global_load_lds_dwordx4 v[218:219], off
	v_lshl_add_u64 v[218:219], v[238:239], 0, s[16:17]
	s_mov_b32 m0, s50
	s_nop 0
	global_load_lds_dwordx4 v[218:219], off
	s_waitcnt vmcnt(8)
	s_waitcnt lgkmcnt(0)
	s_setprio 1
	s_barrier
	v_mfma_f32_16x16x32_bf16 v[62:65], v[140:143], v[176:179], v[62:65]
	v_mfma_f32_16x16x32_bf16 v[58:61], v[152:155], v[176:179], v[58:61]
	v_mfma_f32_16x16x32_bf16 v[42:45], v[152:155], v[194:197], v[42:45]
	v_mfma_f32_16x16x32_bf16 v[46:49], v[140:143], v[194:197], v[46:49]
	v_mfma_f32_16x16x32_bf16 v[30:33], v[140:143], v[202:205], v[30:33]
	v_mfma_f32_16x16x32_bf16 v[26:29], v[152:155], v[202:205], v[26:29]
	v_mfma_f32_16x16x32_bf16 v[10:13], v[152:155], v[210:213], v[10:13]
	v_mfma_f32_16x16x32_bf16 v[14:17], v[140:143], v[210:213], v[14:17]
	v_mfma_f32_16x16x32_bf16 v[62:65], v[144:147], v[190:193], v[62:65]
	v_mfma_f32_16x16x32_bf16 v[58:61], v[156:159], v[190:193], v[58:61]
	v_mfma_f32_16x16x32_bf16 v[42:45], v[156:159], v[198:201], v[42:45]
	v_mfma_f32_16x16x32_bf16 v[46:49], v[144:147], v[198:201], v[46:49]
	v_mfma_f32_16x16x32_bf16 v[30:33], v[144:147], v[206:209], v[30:33]
	v_mfma_f32_16x16x32_bf16 v[26:29], v[156:159], v[206:209], v[26:29]
	v_mfma_f32_16x16x32_bf16 v[10:13], v[156:159], v[214:217], v[10:13]
	v_mfma_f32_16x16x32_bf16 v[14:17], v[144:147], v[214:217], v[14:17]
	v_mfma_f32_16x16x32_bf16 v[54:57], v[160:163], v[176:179], v[54:57]
	v_mfma_f32_16x16x32_bf16 v[50:53], v[168:171], v[176:179], v[50:53]
	v_mfma_f32_16x16x32_bf16 v[34:37], v[168:171], v[194:197], v[34:37]
	v_mfma_f32_16x16x32_bf16 v[38:41], v[160:163], v[194:197], v[38:41]
	v_mfma_f32_16x16x32_bf16 v[22:25], v[160:163], v[202:205], v[22:25]
	v_mfma_f32_16x16x32_bf16 v[18:21], v[168:171], v[202:205], v[18:21]
	v_mfma_f32_16x16x32_bf16 v[2:5], v[168:171], v[210:213], v[2:5]
	v_mfma_f32_16x16x32_bf16 v[6:9], v[160:163], v[210:213], v[6:9]
	v_mfma_f32_16x16x32_bf16 v[54:57], v[164:167], v[190:193], v[54:57]
	v_mfma_f32_16x16x32_bf16 v[50:53], v[172:175], v[190:193], v[50:53]
	v_mfma_f32_16x16x32_bf16 v[34:37], v[172:175], v[198:201], v[34:37]
	v_mfma_f32_16x16x32_bf16 v[38:41], v[164:167], v[198:201], v[38:41]
	v_mfma_f32_16x16x32_bf16 v[22:25], v[164:167], v[206:209], v[22:25]
	v_mfma_f32_16x16x32_bf16 v[18:21], v[172:175], v[206:209], v[18:21]
	v_mfma_f32_16x16x32_bf16 v[2:5], v[172:175], v[214:217], v[2:5]
	v_mfma_f32_16x16x32_bf16 v[6:9], v[164:167], v[214:217], v[6:9]
	s_barrier
	s_setprio 0
	s_add_i32 s60, s60, 2
	s_add_u32 s58, s58, 0x100
	s_addc_u32 s59, s59, 0
	s_cmp_gt_u32 s60, 21
	s_mov_b64 s[30:31], s[34:35]
	s_cbranch_scc0 .LBB0_937
	s_and_b64 vcc, exec, s[24:25]
	s_cbranch_vccz .LBB0_940
	s_barrier

.LBB0_1005:
	v_readlane_b32 s3, v255, 41
	s_andn2_b64 vcc, exec, s[14:15]
	s_lshl_b32 s12, s3, 6
	s_cbranch_vccnz .LBB0_1222
	v_ashrrev_i32_e32 v3, 31, v10
	v_lshrrev_b32_e32 v3, 26, v3
	v_add_u32_e32 v3, v10, v3
	v_ashrrev_i32_e32 v11, 6, v3
	v_bfe_i32 v3, v10, 27, 1
	v_lshlrev_b32_e32 v2, 4, v10
	v_lshrrev_b32_e32 v3, 22, v3
	v_add_u32_e32 v3, v2, v3
	v_and_b32_e32 v3, 0xfffffc00, v3
	s_load_dwordx2 s[30:31], s[0:1], s69 offset:0x118
	v_sub_u32_e32 v3, v2, v3
	v_lshrrev_b32_e32 v4, 4, v3
	v_bitop3_b32 v3, v4, v3, 32 bitop3:0x6c
	v_ashrrev_i32_e32 v5, 31, v3
	v_lshrrev_b32_e32 v5, 26, v5
	v_readlane_b32 s3, v255, 41
	s_waitcnt lgkmcnt(0)
	s_add_u32 s7, s30, 0x1de00000
	v_add_u32_e32 v5, v3, v5
	s_mul_i32 s11, s3, 0xe00000
	s_addc_u32 s8, s31, 0
	v_lshlrev_b32_e32 v4, 3, v11
	v_ashrrev_i32_e32 v12, 6, v5
	v_and_b32_e32 v5, 0xc0, v5
	s_mul_hi_u32 s9, s3, 0xe00000
	s_add_u32 s11, s30, s11
	v_and_b32_e32 v4, -16, v4
	v_sub_u32_e32 v3, v3, v5
	s_addc_u32 s14, s31, s9
	v_add_u32_e32 v4, v12, v4
	v_ashrrev_i16_sdwa v3, v224, sext(v3) dst_sel:DWORD dst_unused:UNUSED_PAD src0_sel:DWORD src1_sel:BYTE_0
	s_add_u32 s9, s11, 0x100000
	v_lshlrev_b32_e32 v6, 5, v11
	v_bfe_i32 v13, v3, 0, 16
	v_lshlrev_b32_e32 v3, 1, v4
	v_lshrrev_b32_e32 v5, 2, v4
	v_and_b32_e32 v7, 3, v12
	s_mov_b32 s11, 0xfffe0
	v_and_b32_e32 v6, 32, v6
	v_and_b32_e32 v3, 24, v3
	v_and_b32_e32 v5, 4, v5
	v_and_or_b32 v7, v4, s11, v7
	v_or3_b32 v3, v7, v5, v3
	v_add_lshl_u32 v5, v6, v13, 1
	v_add_u32_e32 v2, 0x2000, v2
	v_lshl_add_u32 v180, v3, 12, v5
	v_ashrrev_i32_e32 v3, 31, v2
	v_lshrrev_b32_e32 v3, 22, v3
	v_add_u32_e32 v3, v2, v3
	v_ashrrev_i32_e32 v14, 10, v3
	v_mul_i32_i24_e32 v3, 0x400, v14
	v_sub_u32_e32 v2, v2, v3
	v_lshrrev_b32_e32 v3, 4, v2
	v_bitop3_b32 v2, v3, v2, 32 bitop3:0x6c
	s_waitcnt vmcnt(0)
	v_lshl_add_u32 v132, v4, 12, v5
	v_ashrrev_i32_e32 v4, 31, v2
	v_lshrrev_b32_e32 v4, 26, v4
	v_lshlrev_b32_e32 v3, 3, v14
	v_add_u32_e32 v4, v2, v4
	v_and_b32_e32 v3, -16, v3
	v_ashrrev_i32_e32 v15, 6, v4
	v_add_u32_e32 v3, v15, v3
	v_and_b32_e32 v6, 3, v15
	s_addc_u32 s21, s14, 0
	v_and_b32_e32 v4, 0xc0, v4
	v_and_or_b32 v6, v3, s11, v6
	s_ashr_i32 s42, s34, 6
	s_ashr_i32 s11, s10, 31
	s_ashr_i32 s37, s36, 31
	s_ashr_i32 s35, s34, 8
	v_sub_u32_e32 v2, v2, v4
	s_lshl_b32 s60, s42, 10
	s_lshl_b64 s[14:15], s[10:11], 20
	s_lshl_b64 s[18:19], s[36:37], 20
	v_ashrrev_i16_sdwa v2, v224, sext(v2) dst_sel:DWORD dst_unused:UNUSED_PAD src0_sel:DWORD src1_sel:BYTE_0
	s_add_u32 s40, s9, s18
	v_lshlrev_b32_e32 v5, 5, v14
	v_bfe_i32 v16, v2, 0, 16
	v_lshlrev_b32_e32 v2, 1, v3
	v_lshrrev_b32_e32 v4, 2, v3
	s_addc_u32 s41, s21, s19
	s_add_i32 s61, s60, 0
	v_and_b32_e32 v5, 32, v5
	v_and_b32_e32 v2, 24, v2
	v_and_b32_e32 v4, 4, v4
	s_add_i32 m0, s61, 0x10000
	v_or3_b32 v2, v6, v4, v2
	v_add_lshl_u32 v4, v5, v16, 1
	v_and_b32_e32 v142, 63, v0
	v_lshrrev_b32_e32 v143, 3, v142
	v_and_b32_e32 v142, 7, v142
	v_xor_b32_e32 v142, v142, v143
	v_lshlrev_b32_e32 v142, 4, v142
	v_lshrrev_b32_e32 v144, 6, v0
	v_lshl_add_u32 v143, v144, 3, v143
	v_mov_b32_e32 v144, 0x1000
	v_mad_u32_u24 v132, v143, v144, v142
	v_add_u32_e32 v134, 0x40000, v132
	v_and_b32_e32 v145, 15, v143
	v_lshrrev_b32_e32 v144, 2, v145
	v_and_b32_e32 v145, 3, v145
	v_lshl_add_u32 v145, v144, 3, v145
	v_bfe_u32 v144, v143, 4, 1
	v_lshl_add_u32 v145, v144, 2, v145
	v_and_b32_e32 v144, 0x60, v143
	v_or_b32_e32 v145, v144, v145
	v_mov_b32_e32 v144, 0x1000
	v_mad_u32_u24 v180, v145, v144, v142
	v_add_u32_e32 v136, 0x40000, v180
	global_load_lds_dwordx4 v180, s[40:41]
	s_add_i32 m0, s61, 0x12000
	s_nop 0
	s_add_u32 s18, s40, 0x80000
	global_load_lds_dwordx4 v136, s[40:41]
	s_addc_u32 s19, s41, 0
	s_add_i32 m0, s61, 0x14000
	s_nop 0
	global_load_lds_dwordx4 v180, s[18:19]
	s_add_i32 m0, s61, 0x16000
	s_add_u32 s38, s7, s14
	s_addc_u32 s39, s8, s15
	s_add_i32 s62, s61, 0x2000
	global_load_lds_dwordx4 v136, s[18:19]
	s_mov_b32 m0, s61
	s_add_u32 s14, s38, 0x80000
	global_load_lds_dwordx4 v132, s[38:39]
	s_mov_b32 m0, s62
	s_addc_u32 s15, s39, 0
	s_add_i32 s63, s61, 0x4000
	global_load_lds_dwordx4 v134, s[38:39]
	s_mov_b32 m0, s63
	s_add_i32 s64, s61, 0x6000
	global_load_lds_dwordx4 v132, s[14:15]
	s_mov_b32 m0, s64
	v_mov_b32_e32 v137, v181
	global_load_lds_dwordx4 v134, s[14:15]
	v_mov_b32_e32 v133, v181
	v_mov_b32_e32 v135, v181
	s_cmp_eq_u32 s35, 1
	v_lshl_add_u64 v[8:9], s[40:41], 0, v[180:181]
	v_lshl_add_u64 v[6:7], s[40:41], 0, v[136:137]
	v_lshl_add_u64 v[2:3], s[38:39], 0, v[132:133]
	s_cselect_b64 s[14:15], -1, 0
	s_cmp_lg_u32 s35, 1
	v_lshl_add_u64 v[4:5], s[38:39], 0, v[134:135]
	s_cbranch_scc1 .LBB0_1008
	s_barrier
.LBB0_1008:
	v_readlane_b32 s3, v255, 43
	s_mul_i32 s18, s3, 0x4200
	s_mov_b32 s19, s13
	s_lshl_b64 s[18:19], s[18:19], 3
	s_add_u32 s18, s30, s18
	s_addc_u32 s19, s31, s19
	s_add_u32 s18, s18, 0x10000
	s_addc_u32 s19, s19, 0
	s_add_u32 s22, s30, 0x20b00000
	s_addc_u32 s23, s31, 0
	s_add_u32 s24, s30, 0x22400000
	s_addc_u32 s25, s31, 0
	v_readlane_b32 s3, v255, 41
	s_add_u32 s26, s30, 0x23d00000
	s_mul_i32 s28, s3, 0x10800
	s_addc_u32 s27, s31, 0
	s_mul_hi_u32 s11, s3, 0x10800
	s_add_u32 s28, s30, s28
	s_addc_u32 s11, s31, s11
	s_add_u32 s28, s28, 0xb0000
	s_addc_u32 s29, s11, 0
	s_lshl_b64 s[44:45], s[12:13], 2
	s_add_u32 s11, s30, s44
	s_addc_u32 s31, s31, s45
	s_add_u32 s30, s11, 0xb000
	s_addc_u32 s31, s31, 0
	s_lshl_b32 s70, s35, 6
	s_lshl_b32 s11, s35, 13
	s_lshl_b32 s35, s42, 5
	s_and_b32 s71, s35, 0x60
	s_add_i32 m0, s61, 0x18000
	v_lshl_add_u64 v[8:9], v[8:9], 0, s[16:17]
	s_lshl_b32 s35, s71, 7
	s_waitcnt vmcnt(2)
	s_barrier
	global_load_lds_dwordx4 v[8:9], off
	v_lshl_add_u64 v[6:7], v[6:7], 0, s[16:17]
	s_add_i32 m0, s61, 0x1a000
	s_add_i32 s74, s61, 0x8000
	s_add_i32 s75, s61, 0xa000
	global_load_lds_dwordx4 v[6:7], off
	v_lshl_add_u64 v[2:3], v[2:3], 0, s[16:17]
	s_mov_b32 m0, s74
	s_add_u32 s42, s40, 0x80080
	global_load_lds_dwordx4 v[2:3], off
	v_lshl_add_u64 v[2:3], v[4:5], 0, s[16:17]
	s_mov_b32 m0, s75
	s_addc_u32 s43, s41, 0
	global_load_lds_dwordx4 v[2:3], off
	s_add_i32 m0, s61, 0x1c000
	v_lshl_add_u64 v[2:3], s[42:43], 0, v[180:181]
	global_load_lds_dwordx4 v[2:3], off
	v_lshl_add_u64 v[2:3], s[42:43], 0, v[136:137]
	s_add_i32 m0, s61, 0x1e000
	v_bfe_u32 v158, v10, 4, 2
	global_load_lds_dwordx4 v[2:3], off
	v_and_b32_e32 v131, 15, v10
	v_lshlrev_b32_e32 v2, 4, v158
	v_lshlrev_b32_e32 v3, 2, v10
	v_lshl_or_b32 v2, v131, 6, v2
	v_and_b32_e32 v3, 32, v3
	v_bitop3_b32 v4, v2, s11, v3 bitop3:0xde
	v_bitop3_b32 v159, v2, s35, v3 bitop3:0xde
	v_lshlrev_b32_e32 v2, 15, v11
	v_and_b32_e32 v2, 0xffff0000, v2
	v_lshl_add_u32 v2, v12, 12, v2
	v_and_b32_e32 v3, 1, v11
	v_lshl_or_b32 v2, v3, 6, v2
	v_mov_b32_e32 v138, v132
	v_lshlrev_b32_e32 v2, 15, v14
	v_and_b32_e32 v2, 0xffff0000, v2
	s_waitcnt vmcnt(6)
	v_lshl_add_u32 v2, v15, 12, v2
	v_and_b32_e32 v3, 1, v14
	s_cmpk_lt_u32 s34, 0x100
	v_lshl_or_b32 v2, v3, 6, v2
	s_cselect_b64 s[34:35], -1, 0
	s_ashr_i32 s76, s6, 31
	v_mov_b32_e32 v139, v181
	v_mov_b32_e32 v140, v134
	v_mov_b32_e32 v141, v181
	s_mov_b32 s82, 0
	v_add_u32_e32 v160, 0, v4
	v_and_b32_e32 v142, 7, v0
	v_bfe_u32 v143, v0, 4, 2
	v_xor_b32_e32 v143, v143, v142
	v_lshlrev_b32_e32 v143, 4, v143
	v_lshl_add_u32 v143, v142, 7, v143
	v_bfe_u32 v142, v0, 3, 1
	v_lshl_add_u32 v143, v142, 10, v143
	v_lshrrev_b32_e32 v142, 8, v0
	v_lshl_add_u32 v160, v142, 13, v143
	v_bfe_u32 v142, v0, 6, 2
	v_lshl_add_u32 v159, v142, 12, v143
	s_barrier
	s_branch .LBB0_1011

.LBB0_1018:
	s_add_u32 s40, s38, 0xfff80080
	s_addc_u32 s41, s39, -1
	s_add_i32 s51, 0, 0x10000
	s_cmp_eq_u32 s49, 28
	s_cselect_b32 s43, s11, s41
	s_cselect_b32 s42, s37, s40
	s_cselect_b32 s41, s44, s47
	s_cselect_b32 s40, s45, s46
	s_add_i32 s83, 0, 0x14000
	v_add_u32_e32 v154, s51, v159
	v_add_u32_e32 v161, s83, v159
	ds_read_b128 v[142:145], v154
	ds_read_b128 v[150:153], v154 offset:2048
	v_xor_b32_e32 v154, 64, v154
	ds_read_b128 v[146:149], v154
	ds_read_b128 v[154:157], v154 offset:2048
	ds_read_b128 v[162:165], v161
	ds_read_b128 v[170:173], v161 offset:2048
	v_xor_b32_e32 v161, 64, v161
	ds_read_b128 v[166:169], v161
	ds_read_b128 v[174:177], v161 offset:2048
	v_lshl_add_u64 v[178:179], s[38:39], 0, v[138:139]
	s_add_i32 m0, s61, 0xc000
	ds_read_b128 v[190:193], v160
	ds_read_b128 v[198:201], v160 offset:2048
	ds_read_b128 v[206:209], v160 offset:4096
	ds_read_b128 v[214:217], v160 offset:6144
	v_xor_b32_e32 v218, 64, v160
	ds_read_b128 v[194:197], v218
	ds_read_b128 v[202:205], v218 offset:2048
	ds_read_b128 v[210:213], v218 offset:4096
	ds_read_b128 v[218:221], v218 offset:6144
	global_load_lds_dwordx4 v[178:179], off
	v_lshl_add_u64 v[178:179], s[38:39], 0, v[140:141]
	s_add_i32 m0, s61, 0xe000
	s_nop 0
	global_load_lds_dwordx4 v[178:179], off
	s_waitcnt vmcnt(8)
	s_waitcnt lgkmcnt(0)
	s_setprio 1
	s_barrier
	v_mfma_f32_16x16x32_bf16 v[126:129], v[142:145], v[190:193], v[126:129]
	v_mfma_f32_16x16x32_bf16 v[122:125], v[150:153], v[190:193], v[122:125]
	v_mfma_f32_16x16x32_bf16 v[106:109], v[150:153], v[198:201], v[106:109]
	v_mfma_f32_16x16x32_bf16 v[110:113], v[142:145], v[198:201], v[110:113]
	v_mfma_f32_16x16x32_bf16 v[94:97], v[142:145], v[206:209], v[94:97]
	v_mfma_f32_16x16x32_bf16 v[90:93], v[150:153], v[206:209], v[90:93]
	v_mfma_f32_16x16x32_bf16 v[74:77], v[150:153], v[214:217], v[74:77]
	v_mfma_f32_16x16x32_bf16 v[78:81], v[142:145], v[214:217], v[78:81]
	v_mfma_f32_16x16x32_bf16 v[126:129], v[146:149], v[194:197], v[126:129]
	v_mfma_f32_16x16x32_bf16 v[122:125], v[154:157], v[194:197], v[122:125]
	v_mfma_f32_16x16x32_bf16 v[106:109], v[154:157], v[202:205], v[106:109]
	v_mfma_f32_16x16x32_bf16 v[110:113], v[146:149], v[202:205], v[110:113]
	v_mfma_f32_16x16x32_bf16 v[94:97], v[146:149], v[210:213], v[94:97]
	v_mfma_f32_16x16x32_bf16 v[90:93], v[154:157], v[210:213], v[90:93]
	v_mfma_f32_16x16x32_bf16 v[74:77], v[154:157], v[218:221], v[74:77]
	v_mfma_f32_16x16x32_bf16 v[78:81], v[146:149], v[218:221], v[78:81]
	v_mfma_f32_16x16x32_bf16 v[118:121], v[162:165], v[190:193], v[118:121]
	v_mfma_f32_16x16x32_bf16 v[114:117], v[170:173], v[190:193], v[114:117]
	v_mfma_f32_16x16x32_bf16 v[98:101], v[170:173], v[198:201], v[98:101]
	v_mfma_f32_16x16x32_bf16 v[102:105], v[162:165], v[198:201], v[102:105]
	v_mfma_f32_16x16x32_bf16 v[86:89], v[162:165], v[206:209], v[86:89]
	v_mfma_f32_16x16x32_bf16 v[82:85], v[170:173], v[206:209], v[82:85]
	v_mfma_f32_16x16x32_bf16 v[66:69], v[170:173], v[214:217], v[66:69]
	v_mfma_f32_16x16x32_bf16 v[70:73], v[162:165], v[214:217], v[70:73]
	v_mfma_f32_16x16x32_bf16 v[118:121], v[166:169], v[194:197], v[118:121]
	v_mfma_f32_16x16x32_bf16 v[114:117], v[174:177], v[194:197], v[114:117]
	v_mfma_f32_16x16x32_bf16 v[98:101], v[174:177], v[202:205], v[98:101]
	v_mfma_f32_16x16x32_bf16 v[102:105], v[166:169], v[202:205], v[102:105]
	v_mfma_f32_16x16x32_bf16 v[86:89], v[166:169], v[210:213], v[86:89]
	v_mfma_f32_16x16x32_bf16 v[82:85], v[174:177], v[210:213], v[82:85]
	v_mfma_f32_16x16x32_bf16 v[66:69], v[174:177], v[218:221], v[66:69]
	v_mfma_f32_16x16x32_bf16 v[70:73], v[166:169], v[218:221], v[70:73]
	s_barrier
	s_setprio 0
	s_add_i32 s51, s51, s60
	v_lshl_add_u64 v[178:179], s[40:41], 0, v[180:181]
	s_mov_b32 m0, s51
	ds_read_b128 v[190:193], v160 offset:16384
	ds_read_b128 v[198:201], v160 offset:18432
	ds_read_b128 v[206:209], v160 offset:20480
	ds_read_b128 v[214:217], v160 offset:22528
	v_xor_b32_e32 v218, 64, v160
	ds_read_b128 v[194:197], v218 offset:16384
	ds_read_b128 v[202:205], v218 offset:18432
	ds_read_b128 v[210:213], v218 offset:20480
	ds_read_b128 v[218:221], v218 offset:22528
	global_load_lds_dwordx4 v[178:179], off
	s_add_i32 m0, s51, 0x2000
	s_add_u32 vcc_lo, s40, 0x80000
	v_lshl_add_u64 v[222:223], s[40:41], 0, v[136:137]
	s_addc_u32 vcc_hi, s41, 0
	s_add_i32 s51, s83, s60
	global_load_lds_dwordx4 v[222:223], off
	v_lshl_add_u64 v[238:239], vcc, 0, v[180:181]
	s_mov_b32 m0, s51
	v_lshl_add_u64 v[240:241], s[42:43], 0, v[134:135]
	global_load_lds_dwordx4 v[238:239], off
	v_lshl_add_u64 v[238:239], vcc, 0, v[136:137]
	s_add_i32 m0, s51, 0x2000
	s_nop 0
	global_load_lds_dwordx4 v[238:239], off
	v_lshl_add_u64 v[238:239], s[42:43], 0, v[132:133]
	s_mov_b32 m0, s61
	s_nop 0
	global_load_lds_dwordx4 v[238:239], off
	s_mov_b32 m0, s62
	s_nop 0
	global_load_lds_dwordx4 v[240:241], off
	s_waitcnt vmcnt(8)
	s_waitcnt lgkmcnt(0)
	s_setprio 1
	s_barrier
	v_mfma_f32_16x16x32_bf16 v[62:65], v[142:145], v[190:193], v[62:65]
	v_mfma_f32_16x16x32_bf16 v[58:61], v[150:153], v[190:193], v[58:61]
	v_mfma_f32_16x16x32_bf16 v[42:45], v[150:153], v[198:201], v[42:45]
	v_mfma_f32_16x16x32_bf16 v[46:49], v[142:145], v[198:201], v[46:49]
	v_mfma_f32_16x16x32_bf16 v[30:33], v[142:145], v[206:209], v[30:33]
	v_mfma_f32_16x16x32_bf16 v[26:29], v[150:153], v[206:209], v[26:29]
	v_mfma_f32_16x16x32_bf16 v[10:13], v[150:153], v[214:217], v[10:13]
	v_mfma_f32_16x16x32_bf16 v[14:17], v[142:145], v[214:217], v[14:17]
	v_mfma_f32_16x16x32_bf16 v[62:65], v[146:149], v[194:197], v[62:65]
	v_mfma_f32_16x16x32_bf16 v[58:61], v[154:157], v[194:197], v[58:61]
	v_mfma_f32_16x16x32_bf16 v[42:45], v[154:157], v[202:205], v[42:45]
	v_mfma_f32_16x16x32_bf16 v[46:49], v[146:149], v[202:205], v[46:49]
	v_mfma_f32_16x16x32_bf16 v[30:33], v[146:149], v[210:213], v[30:33]
	v_mfma_f32_16x16x32_bf16 v[26:29], v[154:157], v[210:213], v[26:29]
	v_mfma_f32_16x16x32_bf16 v[10:13], v[154:157], v[218:221], v[10:13]
	v_mfma_f32_16x16x32_bf16 v[14:17], v[146:149], v[218:221], v[14:17]
	v_mfma_f32_16x16x32_bf16 v[54:57], v[162:165], v[190:193], v[54:57]
	v_mfma_f32_16x16x32_bf16 v[50:53], v[170:173], v[190:193], v[50:53]
	v_mfma_f32_16x16x32_bf16 v[34:37], v[170:173], v[198:201], v[34:37]
	v_mfma_f32_16x16x32_bf16 v[38:41], v[162:165], v[198:201], v[38:41]
	v_mfma_f32_16x16x32_bf16 v[22:25], v[162:165], v[206:209], v[22:25]
	v_mfma_f32_16x16x32_bf16 v[18:21], v[170:173], v[206:209], v[18:21]
	v_mfma_f32_16x16x32_bf16 v[2:5], v[170:173], v[214:217], v[2:5]
	v_mfma_f32_16x16x32_bf16 v[6:9], v[162:165], v[214:217], v[6:9]
	v_mfma_f32_16x16x32_bf16 v[54:57], v[166:169], v[194:197], v[54:57]
	v_mfma_f32_16x16x32_bf16 v[50:53], v[174:177], v[194:197], v[50:53]
	v_mfma_f32_16x16x32_bf16 v[34:37], v[174:177], v[202:205], v[34:37]
	v_mfma_f32_16x16x32_bf16 v[38:41], v[166:169], v[202:205], v[38:41]
	v_mfma_f32_16x16x32_bf16 v[22:25], v[166:169], v[210:213], v[22:25]
	v_mfma_f32_16x16x32_bf16 v[18:21], v[174:177], v[210:213], v[18:21]
	v_mfma_f32_16x16x32_bf16 v[2:5], v[174:177], v[218:221], v[2:5]
	v_mfma_f32_16x16x32_bf16 v[6:9], v[166:169], v[218:221], v[6:9]
	s_barrier
	s_setprio 0
	s_add_i32 s51, 0, 0x18000
	s_add_i32 s83, 0, 0x1c000
	v_add_u32_e32 v154, s51, v159
	v_add_u32_e32 v161, s83, v159
	ds_read_b128 v[142:145], v154
	ds_read_b128 v[150:153], v154 offset:2048
	v_xor_b32_e32 v154, 64, v154
	ds_read_b128 v[146:149], v154
	ds_read_b128 v[154:157], v154 offset:2048
	ds_read_b128 v[162:165], v161
	ds_read_b128 v[170:173], v161 offset:2048
	v_xor_b32_e32 v161, 64, v161
	ds_read_b128 v[166:169], v161
	ds_read_b128 v[174:177], v161 offset:2048
	s_add_u32 s42, s42, 0x80000
	s_addc_u32 s43, s43, 0
	s_mov_b32 m0, s63
	v_lshl_add_u64 v[242:243], s[42:43], 0, v[132:133]
	ds_read_b128 v[190:193], v160 offset:32768
	ds_read_b128 v[198:201], v160 offset:34816
	ds_read_b128 v[206:209], v160 offset:36864
	ds_read_b128 v[214:217], v160 offset:38912
	v_xor_b32_e32 v218, 64, v160
	ds_read_b128 v[194:197], v218 offset:32768
	ds_read_b128 v[202:205], v218 offset:34816
	ds_read_b128 v[210:213], v218 offset:36864
	ds_read_b128 v[218:221], v218 offset:38912
	global_load_lds_dwordx4 v[242:243], off
	v_lshl_add_u64 v[242:243], s[42:43], 0, v[134:135]
	s_mov_b32 m0, s64
	s_nop 0
	global_load_lds_dwordx4 v[242:243], off
	s_waitcnt vmcnt(8)
	s_waitcnt lgkmcnt(0)
	s_setprio 1
	s_barrier
	v_mfma_f32_16x16x32_bf16 v[126:129], v[142:145], v[190:193], v[126:129]
	v_mfma_f32_16x16x32_bf16 v[122:125], v[150:153], v[190:193], v[122:125]
	v_mfma_f32_16x16x32_bf16 v[106:109], v[150:153], v[198:201], v[106:109]
	v_mfma_f32_16x16x32_bf16 v[110:113], v[142:145], v[198:201], v[110:113]
	v_mfma_f32_16x16x32_bf16 v[94:97], v[142:145], v[206:209], v[94:97]
	v_mfma_f32_16x16x32_bf16 v[90:93], v[150:153], v[206:209], v[90:93]
	v_mfma_f32_16x16x32_bf16 v[74:77], v[150:153], v[214:217], v[74:77]
	v_mfma_f32_16x16x32_bf16 v[78:81], v[142:145], v[214:217], v[78:81]
	v_mfma_f32_16x16x32_bf16 v[126:129], v[146:149], v[194:197], v[126:129]
	v_mfma_f32_16x16x32_bf16 v[122:125], v[154:157], v[194:197], v[122:125]
	v_mfma_f32_16x16x32_bf16 v[106:109], v[154:157], v[202:205], v[106:109]
	v_mfma_f32_16x16x32_bf16 v[110:113], v[146:149], v[202:205], v[110:113]
	v_mfma_f32_16x16x32_bf16 v[94:97], v[146:149], v[210:213], v[94:97]
	v_mfma_f32_16x16x32_bf16 v[90:93], v[154:157], v[210:213], v[90:93]
	v_mfma_f32_16x16x32_bf16 v[74:77], v[154:157], v[218:221], v[74:77]
	v_mfma_f32_16x16x32_bf16 v[78:81], v[146:149], v[218:221], v[78:81]
	v_mfma_f32_16x16x32_bf16 v[118:121], v[162:165], v[190:193], v[118:121]
	v_mfma_f32_16x16x32_bf16 v[114:117], v[170:173], v[190:193], v[114:117]
	v_mfma_f32_16x16x32_bf16 v[98:101], v[170:173], v[198:201], v[98:101]
	v_mfma_f32_16x16x32_bf16 v[102:105], v[162:165], v[198:201], v[102:105]
	v_mfma_f32_16x16x32_bf16 v[86:89], v[162:165], v[206:209], v[86:89]
	v_mfma_f32_16x16x32_bf16 v[82:85], v[170:173], v[206:209], v[82:85]
	v_mfma_f32_16x16x32_bf16 v[66:69], v[170:173], v[214:217], v[66:69]
	v_mfma_f32_16x16x32_bf16 v[70:73], v[162:165], v[214:217], v[70:73]
	v_mfma_f32_16x16x32_bf16 v[118:121], v[166:169], v[194:197], v[118:121]
	v_mfma_f32_16x16x32_bf16 v[114:117], v[174:177], v[194:197], v[114:117]
	v_mfma_f32_16x16x32_bf16 v[98:101], v[174:177], v[202:205], v[98:101]
	v_mfma_f32_16x16x32_bf16 v[102:105], v[166:169], v[202:205], v[102:105]
	v_mfma_f32_16x16x32_bf16 v[86:89], v[166:169], v[210:213], v[86:89]
	v_mfma_f32_16x16x32_bf16 v[82:85], v[174:177], v[210:213], v[82:85]
	v_mfma_f32_16x16x32_bf16 v[66:69], v[174:177], v[218:221], v[66:69]
	v_mfma_f32_16x16x32_bf16 v[70:73], v[166:169], v[218:221], v[70:73]
	s_barrier
	s_setprio 0
	s_add_i32 s42, s51, s60
	v_lshl_add_u64 v[178:179], v[178:179], 0, s[16:17]
	s_mov_b32 m0, s42
	ds_read_b128 v[190:193], v160 offset:49152
	ds_read_b128 v[198:201], v160 offset:51200
	ds_read_b128 v[206:209], v160 offset:53248
	ds_read_b128 v[214:217], v160 offset:55296
	v_xor_b32_e32 v218, 64, v160
	ds_read_b128 v[194:197], v218 offset:49152
	ds_read_b128 v[202:205], v218 offset:51200
	ds_read_b128 v[210:213], v218 offset:53248
	ds_read_b128 v[218:221], v218 offset:55296
	global_load_lds_dwordx4 v[178:179], off
	s_add_i32 m0, s42, 0x2000
	s_add_u32 s40, s40, 0x80080
	v_lshl_add_u64 v[178:179], v[222:223], 0, s[16:17]
	s_addc_u32 s41, s41, 0
	s_add_i32 s42, s83, s60
	global_load_lds_dwordx4 v[178:179], off
	v_lshl_add_u64 v[178:179], s[40:41], 0, v[180:181]
	s_mov_b32 m0, s42
	s_nop 0
	global_load_lds_dwordx4 v[178:179], off
	v_lshl_add_u64 v[178:179], s[40:41], 0, v[136:137]
	s_add_i32 m0, s42, 0x2000
	s_nop 0
	global_load_lds_dwordx4 v[178:179], off
	v_lshl_add_u64 v[178:179], v[238:239], 0, s[16:17]
	s_mov_b32 m0, s74
	s_nop 0
	global_load_lds_dwordx4 v[178:179], off
	v_lshl_add_u64 v[178:179], v[240:241], 0, s[16:17]
	s_mov_b32 m0, s75
	s_nop 0
	global_load_lds_dwordx4 v[178:179], off
	s_waitcnt vmcnt(8)
	s_waitcnt lgkmcnt(0)
	s_setprio 1
	s_barrier
	v_mfma_f32_16x16x32_bf16 v[62:65], v[142:145], v[190:193], v[62:65]
	v_mfma_f32_16x16x32_bf16 v[58:61], v[150:153], v[190:193], v[58:61]
	v_mfma_f32_16x16x32_bf16 v[42:45], v[150:153], v[198:201], v[42:45]
	v_mfma_f32_16x16x32_bf16 v[46:49], v[142:145], v[198:201], v[46:49]
	v_mfma_f32_16x16x32_bf16 v[30:33], v[142:145], v[206:209], v[30:33]
	v_mfma_f32_16x16x32_bf16 v[26:29], v[150:153], v[206:209], v[26:29]
	v_mfma_f32_16x16x32_bf16 v[10:13], v[150:153], v[214:217], v[10:13]
	v_mfma_f32_16x16x32_bf16 v[14:17], v[142:145], v[214:217], v[14:17]
	v_mfma_f32_16x16x32_bf16 v[62:65], v[146:149], v[194:197], v[62:65]
	v_mfma_f32_16x16x32_bf16 v[58:61], v[154:157], v[194:197], v[58:61]
	v_mfma_f32_16x16x32_bf16 v[42:45], v[154:157], v[202:205], v[42:45]
	v_mfma_f32_16x16x32_bf16 v[46:49], v[146:149], v[202:205], v[46:49]
	v_mfma_f32_16x16x32_bf16 v[30:33], v[146:149], v[210:213], v[30:33]
	v_mfma_f32_16x16x32_bf16 v[26:29], v[154:157], v[210:213], v[26:29]
	v_mfma_f32_16x16x32_bf16 v[10:13], v[154:157], v[218:221], v[10:13]
	v_mfma_f32_16x16x32_bf16 v[14:17], v[146:149], v[218:221], v[14:17]
	v_mfma_f32_16x16x32_bf16 v[54:57], v[162:165], v[190:193], v[54:57]
	v_mfma_f32_16x16x32_bf16 v[50:53], v[170:173], v[190:193], v[50:53]
	v_mfma_f32_16x16x32_bf16 v[34:37], v[170:173], v[198:201], v[34:37]
	v_mfma_f32_16x16x32_bf16 v[38:41], v[162:165], v[198:201], v[38:41]
	v_mfma_f32_16x16x32_bf16 v[22:25], v[162:165], v[206:209], v[22:25]
	v_mfma_f32_16x16x32_bf16 v[18:21], v[170:173], v[206:209], v[18:21]
	v_mfma_f32_16x16x32_bf16 v[2:5], v[170:173], v[214:217], v[2:5]
	v_mfma_f32_16x16x32_bf16 v[6:9], v[162:165], v[214:217], v[6:9]
	v_mfma_f32_16x16x32_bf16 v[54:57], v[166:169], v[194:197], v[54:57]
	v_mfma_f32_16x16x32_bf16 v[50:53], v[174:177], v[194:197], v[50:53]
	v_mfma_f32_16x16x32_bf16 v[34:37], v[174:177], v[202:205], v[34:37]
	v_mfma_f32_16x16x32_bf16 v[38:41], v[166:169], v[202:205], v[38:41]
	v_mfma_f32_16x16x32_bf16 v[22:25], v[166:169], v[210:213], v[22:25]
	v_mfma_f32_16x16x32_bf16 v[18:21], v[174:177], v[210:213], v[18:21]
	v_mfma_f32_16x16x32_bf16 v[2:5], v[174:177], v[218:221], v[2:5]
	v_mfma_f32_16x16x32_bf16 v[6:9], v[166:169], v[218:221], v[6:9]
	s_barrier
	s_setprio 0
	s_add_i32 s49, s49, 2
	s_add_u32 s38, s38, 0x100
	s_addc_u32 s39, s39, 0
	s_add_u32 s46, s46, 0x100
	s_addc_u32 s47, s47, 0
	s_cmp_gt_u32 s49, 29
	s_cbranch_scc0 .LBB0_1018
	s_and_b64 vcc, exec, s[34:35]
	s_cbranch_vccz .LBB0_1021
	s_barrier

.LBB0_1222:
	s_add_u32 s8, s0, s69
	s_addc_u32 s9, s1, 0
	s_load_dwordx2 s[28:29], s[8:9], 0x118
	v_readlane_b32 s2, v255, 43
	s_cmp_lg_u32 s2, 0
	s_mov_b32 s66, 0x3f22f983
	s_cbranch_scc1 .LBB0_1327
	s_add_i32 s6, s6, s33
	v_readlane_b32 s7, v255, 17
	s_sub_i32 s7, s6, s7
	s_ashr_i32 s8, s7, 31
	s_abs_i32 s7, s7
	v_readlane_b32 s9, v255, 20
	s_mul_hi_u32 s9, s7, s9
	v_readlane_b32 s10, v255, 21
	s_mul_i32 s9, s9, s10
	s_sub_i32 s7, s7, s9
	s_sub_i32 s9, s7, s10
	s_cmp_ge_u32 s7, s10
	s_cselect_b32 s7, s9, s7
	s_sub_i32 s9, s7, s10
	s_cmp_ge_u32 s7, s10
	s_cselect_b32 s7, s9, s7
	s_xor_b32 s7, s7, s8
	v_mov_b32_e32 v16, v0
	s_sub_i32 s7, s7, s8
	s_cmp_gt_i32 s7, 15
	v_readfirstlane_b32 s30, v16
	s_cbranch_scc1 .LBB0_1237
	v_lshlrev_b32_e32 v2, 4, v16
	s_waitcnt lgkmcnt(0)
	v_add_u32_e32 v3, 0x2000, v2
	v_ashrrev_i32_e32 v4, 31, v3
	v_lshrrev_b32_e32 v4, 22, v4
	v_add_u32_e32 v4, v3, v4
	v_ashrrev_i32_e32 v10, 10, v4
	v_mul_i32_i24_e32 v5, 0x400, v10
	v_sub_u32_e32 v3, v3, v5
	v_lshrrev_b32_e32 v5, 4, v3
	v_bitop3_b32 v3, v5, v3, 32 bitop3:0x6c
	v_ashrrev_i32_e32 v5, 31, v3
	v_lshrrev_b32_e32 v5, 26, v5
	v_add_u32_e32 v5, v3, v5
	v_ashrrev_i32_e32 v11, 6, v5
	v_and_b32_e32 v5, 0xc0, v5
	v_sub_u32_e32 v3, v3, v5
	v_lshlrev_b32_e32 v4, 5, v10
	v_ashrrev_i16_sdwa v3, v224, sext(v3) dst_sel:DWORD dst_unused:UNUSED_PAD src0_sel:DWORD src1_sel:BYTE_0
	v_and_b32_e32 v4, 32, v4
	v_bfe_i32 v12, v3, 0, 16
	v_add_u32_e32 v3, v4, v12
	v_lshlrev_b32_e32 v4, 3, v10
	v_and_b32_e32 v4, 0xffff0, v4
	v_add_lshl_u32 v4, v11, v4, 12
	s_waitcnt vmcnt(0)
	v_lshl_add_u32 v132, v3, 1, v4
	v_bfe_i32 v4, v16, 27, 1
	v_lshrrev_b32_e32 v4, 22, v4
	v_add_u32_e32 v4, v2, v4
	v_and_b32_e32 v4, 0xfffffc00, v4
	v_sub_u32_e32 v2, v2, v4
	v_lshrrev_b32_e32 v4, 4, v2
	v_bitop3_b32 v2, v4, v2, 32 bitop3:0x6c
	s_add_u32 s8, s28, 0x1ff00000
	v_ashrrev_i32_e32 v4, 31, v2
	s_addc_u32 s9, s29, 0
	v_ashrrev_i32_e32 v3, 31, v16
	v_lshrrev_b32_e32 v4, 26, v4
	s_add_u32 s21, s28, 0x15800000
	v_lshrrev_b32_e32 v3, 26, v3
	v_add_u32_e32 v4, v2, v4
	s_addc_u32 s42, s29, 0
	v_add_u32_e32 v3, v16, v3
	v_ashrrev_i32_e32 v14, 6, v4
	v_and_b32_e32 v4, 0xc0, v4
	s_add_u32 s18, s0, s69
	v_ashrrev_i32_e32 v13, 6, v3
	v_sub_u32_e32 v2, v2, v4
	s_addc_u32 s19, s1, 0
	s_ashr_i32 s10, s7, 2
	v_lshlrev_b32_e32 v3, 5, v13
	v_ashrrev_i16_sdwa v2, v224, sext(v2) dst_sel:DWORD dst_unused:UNUSED_PAD src0_sel:DWORD src1_sel:BYTE_0
	s_ashr_i32 s31, s30, 6
	s_and_b32 s44, s7, 3
	v_and_b32_e32 v3, 32, v3
	v_bfe_i32 v15, v2, 0, 16
	s_ashr_i32 s11, s10, 31
	s_ashr_i32 s34, s30, 8
	s_lshl_b32 s43, s31, 10
	v_add_u32_e32 v2, v3, v15
	v_lshlrev_b32_e32 v3, 3, v13
	s_lshl_b32 s24, s44, 20
	s_lshl_b64 s[14:15], s[10:11], 20
	v_and_b32_e32 v3, 0xffff0, v3
	s_add_u32 s14, s21, s14
	v_add_lshl_u32 v3, v14, v3, 12
	s_addc_u32 s15, s42, s15
	s_add_i32 s11, s43, 0
	v_lshl_add_u32 v134, v2, 1, v3
	s_add_i32 m0, s11, 0x10000
	s_load_dwordx2 s[18:19], s[18:19], 0x110
	v_and_b32_e32 v140, 63, v0
	v_lshrrev_b32_e32 v141, 3, v140
	v_and_b32_e32 v140, 7, v140
	v_xor_b32_e32 v140, v140, v141
	v_lshlrev_b32_e32 v140, 4, v140
	v_lshrrev_b32_e32 v142, 6, v0
	v_lshl_add_u32 v141, v142, 3, v141
	v_mov_b32_e32 v142, 0x1000
	v_mad_u32_u24 v134, v141, v142, v140
	v_add_u32_e32 v132, 0x40000, v134
	global_load_lds_dwordx4 v134, s[14:15]
	s_add_i32 m0, s11, 0x12000
	s_add_u32 s22, s14, 0x80000
	global_load_lds_dwordx4 v132, s[14:15]
	s_addc_u32 s23, s15, 0
	s_add_i32 m0, s11, 0x14000
	v_mov_b32_e32 v135, v181
	global_load_lds_dwordx4 v134, s[22:23]
	s_add_i32 m0, s11, 0x16000
	v_mov_b32_e32 v133, v181
	global_load_lds_dwordx4 v132, s[22:23]
	s_add_u32 s22, s8, s24
	s_addc_u32 s23, s9, 0
	s_add_i32 s45, s11, 0x2000
	s_mov_b32 m0, s11
	s_add_u32 s24, s22, 0x80000
	global_load_lds_dwordx4 v134, s[22:23]
	s_mov_b32 m0, s45
	s_addc_u32 s25, s23, 0
	s_add_i32 s46, s11, 0x4000
	global_load_lds_dwordx4 v132, s[22:23]
	s_mov_b32 m0, s46
	s_add_i32 s47, s11, 0x6000
	global_load_lds_dwordx4 v134, s[24:25]
	s_mov_b32 m0, s47
	s_cmp_eq_u32 s34, 1
	global_load_lds_dwordx4 v132, s[24:25]
	v_lshl_add_u64 v[8:9], s[14:15], 0, v[134:135]
	v_lshl_add_u64 v[6:7], s[14:15], 0, v[132:133]
	v_lshl_add_u64 v[2:3], s[22:23], 0, v[134:135]
	s_cselect_b64 s[24:25], -1, 0
	s_cmp_lg_u32 s34, 1
	v_lshl_add_u64 v[4:5], s[22:23], 0, v[132:133]
	s_cbranch_scc1 .LBB0_1226
	s_barrier
.LBB0_1226:
	s_add_u32 s26, s28, 0xe0000
	s_addc_u32 s27, s29, 0
	s_add_u32 s28, s28, 0x20300000
	s_addc_u32 s29, s29, 0
	v_bfe_u32 v152, v16, 4, 2
	s_lshl_b32 s31, s31, 5
	v_and_b32_e32 v131, 15, v16
	v_lshlrev_b32_e32 v17, 4, v152
	v_lshlrev_b32_e32 v16, 2, v16
	s_and_b32 s49, s31, 0x60
	s_add_i32 m0, s11, 0x18000
	v_lshl_add_u64 v[8:9], v[8:9], 0, s[16:17]
	s_lshl_b32 s48, s34, 6
	v_lshl_or_b32 v17, v131, 6, v17
	s_lshl_b32 s34, s34, 13
	v_and_b32_e32 v16, 32, v16
	s_lshl_b32 s31, s49, 7
	s_waitcnt vmcnt(2)
	s_barrier
	global_load_lds_dwordx4 v[8:9], off
	v_lshl_add_u64 v[6:7], v[6:7], 0, s[16:17]
	s_add_i32 m0, s11, 0x1a000
	s_add_i32 s50, s11, 0x8000
	s_add_i32 s51, s11, 0xa000
	v_bitop3_b32 v18, v17, s34, v16 bitop3:0xde
	global_load_lds_dwordx4 v[6:7], off
	v_lshl_add_u64 v[2:3], v[2:3], 0, s[16:17]
	s_mov_b32 m0, s50
	s_add_u32 s34, s14, 0x80080
	global_load_lds_dwordx4 v[2:3], off
	v_lshl_add_u64 v[2:3], v[4:5], 0, s[16:17]
	s_mov_b32 m0, s51
	s_addc_u32 s35, s15, 0
	global_load_lds_dwordx4 v[2:3], off
	s_add_i32 m0, s11, 0x1c000
	v_lshl_add_u64 v[2:3], s[34:35], 0, v[134:135]
	global_load_lds_dwordx4 v[2:3], off
	v_lshl_add_u64 v[2:3], s[34:35], 0, v[132:133]
	s_add_i32 m0, s11, 0x1e000
	s_cmpk_lt_u32 s30, 0x100
	global_load_lds_dwordx4 v[2:3], off
	v_lshlrev_b32_e32 v2, 15, v13
	v_and_b32_e32 v2, 0xffff0000, v2
	v_lshl_add_u32 v2, v14, 12, v2
	v_and_b32_e32 v3, 1, v13
	v_lshl_or_b32 v2, v3, 6, v2
	v_mov_b32_e32 v136, v134
	v_lshlrev_b32_e32 v2, 15, v10
	v_and_b32_e32 v2, 0xffff0000, v2
	s_waitcnt vmcnt(6)
	v_lshl_add_u32 v2, v11, 12, v2
	v_and_b32_e32 v3, 1, v10
	v_lshl_or_b32 v2, v3, 6, v2
	v_bitop3_b32 v153, v17, s31, v16 bitop3:0xde
	s_cselect_b64 s[30:31], -1, 0
	v_mov_b32_e32 v137, v181
	v_mov_b32_e32 v138, v132
	v_mov_b32_e32 v139, v181
	s_mov_b32 s54, 0
	v_add_u32_e32 v154, 0, v18
	v_and_b32_e32 v140, 7, v0
	v_bfe_u32 v141, v0, 4, 2
	v_xor_b32_e32 v141, v141, v140
	v_lshlrev_b32_e32 v141, 4, v141
	v_lshl_add_u32 v141, v140, 7, v141
	v_bfe_u32 v140, v0, 3, 1
	v_lshl_add_u32 v141, v140, 10, v141
	v_lshrrev_b32_e32 v140, 8, v0
	v_lshl_add_u32 v154, v140, 13, v141
	v_bfe_u32 v140, v0, 6, 2
	v_lshl_add_u32 v153, v140, 12, v141
	s_barrier
	s_branch .LBB0_1229

.LBB0_1230:
	s_add_u32 s38, s36, 0xfff80080
	s_addc_u32 s39, s37, -1
	s_add_i32 s64, 0, 0x10000
	s_cmp_eq_u32 s63, 28
	s_cselect_b32 s41, s57, s39
	s_cselect_b32 s40, s58, s38
	v_add_u32_e32 v155, s64, v153
	s_cselect_b32 s39, s59, s62
	s_cselect_b32 s38, s60, s61
	s_add_i32 s74, 0, 0x14000
	ds_read_b128 v[140:143], v155
	ds_read_b128 v[148:151], v155 offset:2048
	v_xor_b32_e32 v155, 64, v155
	ds_read_b128 v[144:147], v155
	ds_read_b128 v[156:159], v155 offset:2048
	v_add_u32_e32 v155, s74, v153
	ds_read_b128 v[160:163], v155
	ds_read_b128 v[168:171], v155 offset:2048
	v_xor_b32_e32 v155, 64, v155
	ds_read_b128 v[164:167], v155
	ds_read_b128 v[172:175], v155 offset:2048
	v_lshl_add_u64 v[218:219], s[36:37], 0, v[136:137]
	s_add_i32 m0, s11, 0xc000
	ds_read_b128 v[176:179], v154
	ds_read_b128 v[194:197], v154 offset:2048
	ds_read_b128 v[202:205], v154 offset:4096
	ds_read_b128 v[210:213], v154 offset:6144
	v_xor_b32_e32 v214, 64, v154
	ds_read_b128 v[190:193], v214
	ds_read_b128 v[198:201], v214 offset:2048
	ds_read_b128 v[206:209], v214 offset:4096
	ds_read_b128 v[214:217], v214 offset:6144
	global_load_lds_dwordx4 v[218:219], off
	v_lshl_add_u64 v[218:219], s[36:37], 0, v[138:139]
	s_add_i32 m0, s11, 0xe000
	s_nop 0
	global_load_lds_dwordx4 v[218:219], off
	s_waitcnt vmcnt(8)
	s_waitcnt lgkmcnt(0)
	s_setprio 1
	s_barrier
	v_mfma_f32_16x16x32_bf16 v[126:129], v[140:143], v[176:179], v[126:129]
	v_mfma_f32_16x16x32_bf16 v[122:125], v[148:151], v[176:179], v[122:125]
	v_mfma_f32_16x16x32_bf16 v[106:109], v[148:151], v[194:197], v[106:109]
	v_mfma_f32_16x16x32_bf16 v[110:113], v[140:143], v[194:197], v[110:113]
	v_mfma_f32_16x16x32_bf16 v[94:97], v[140:143], v[202:205], v[94:97]
	v_mfma_f32_16x16x32_bf16 v[90:93], v[148:151], v[202:205], v[90:93]
	v_mfma_f32_16x16x32_bf16 v[74:77], v[148:151], v[210:213], v[74:77]
	v_mfma_f32_16x16x32_bf16 v[78:81], v[140:143], v[210:213], v[78:81]
	v_mfma_f32_16x16x32_bf16 v[126:129], v[144:147], v[190:193], v[126:129]
	v_mfma_f32_16x16x32_bf16 v[122:125], v[156:159], v[190:193], v[122:125]
	v_mfma_f32_16x16x32_bf16 v[106:109], v[156:159], v[198:201], v[106:109]
	v_mfma_f32_16x16x32_bf16 v[110:113], v[144:147], v[198:201], v[110:113]
	v_mfma_f32_16x16x32_bf16 v[94:97], v[144:147], v[206:209], v[94:97]
	v_mfma_f32_16x16x32_bf16 v[90:93], v[156:159], v[206:209], v[90:93]
	v_mfma_f32_16x16x32_bf16 v[74:77], v[156:159], v[214:217], v[74:77]
	v_mfma_f32_16x16x32_bf16 v[78:81], v[144:147], v[214:217], v[78:81]
	v_mfma_f32_16x16x32_bf16 v[118:121], v[160:163], v[176:179], v[118:121]
	v_mfma_f32_16x16x32_bf16 v[114:117], v[168:171], v[176:179], v[114:117]
	v_mfma_f32_16x16x32_bf16 v[98:101], v[168:171], v[194:197], v[98:101]
	v_mfma_f32_16x16x32_bf16 v[102:105], v[160:163], v[194:197], v[102:105]
	v_mfma_f32_16x16x32_bf16 v[86:89], v[160:163], v[202:205], v[86:89]
	v_mfma_f32_16x16x32_bf16 v[82:85], v[168:171], v[202:205], v[82:85]
	v_mfma_f32_16x16x32_bf16 v[66:69], v[168:171], v[210:213], v[66:69]
	v_mfma_f32_16x16x32_bf16 v[70:73], v[160:163], v[210:213], v[70:73]
	v_mfma_f32_16x16x32_bf16 v[118:121], v[164:167], v[190:193], v[118:121]
	v_mfma_f32_16x16x32_bf16 v[114:117], v[172:175], v[190:193], v[114:117]
	v_mfma_f32_16x16x32_bf16 v[98:101], v[172:175], v[198:201], v[98:101]
	v_mfma_f32_16x16x32_bf16 v[102:105], v[164:167], v[198:201], v[102:105]
	v_mfma_f32_16x16x32_bf16 v[86:89], v[164:167], v[206:209], v[86:89]
	v_mfma_f32_16x16x32_bf16 v[82:85], v[172:175], v[206:209], v[82:85]
	v_mfma_f32_16x16x32_bf16 v[66:69], v[172:175], v[214:217], v[66:69]
	v_mfma_f32_16x16x32_bf16 v[70:73], v[164:167], v[214:217], v[70:73]
	s_barrier
	s_setprio 0
	s_add_i32 s64, s64, s43
	v_lshl_add_u64 v[218:219], s[38:39], 0, v[134:135]
	s_mov_b32 m0, s64
	ds_read_b128 v[176:179], v154 offset:16384
	ds_read_b128 v[194:197], v154 offset:18432
	ds_read_b128 v[202:205], v154 offset:20480
	ds_read_b128 v[210:213], v154 offset:22528
	v_xor_b32_e32 v214, 64, v154
	ds_read_b128 v[190:193], v214 offset:16384
	ds_read_b128 v[198:201], v214 offset:18432
	ds_read_b128 v[206:209], v214 offset:20480
	ds_read_b128 v[214:217], v214 offset:22528
	global_load_lds_dwordx4 v[218:219], off
	s_add_i32 m0, s64, 0x2000
	s_add_u32 s70, s38, 0x80000
	v_lshl_add_u64 v[220:221], s[38:39], 0, v[132:133]
	s_addc_u32 s71, s39, 0
	s_add_i32 s64, s74, s43
	global_load_lds_dwordx4 v[220:221], off
	v_lshl_add_u64 v[222:223], s[70:71], 0, v[134:135]
	s_mov_b32 m0, s64
	v_lshl_add_u64 v[238:239], s[40:41], 0, v[132:133]
	global_load_lds_dwordx4 v[222:223], off
	v_lshl_add_u64 v[222:223], s[70:71], 0, v[132:133]
	s_add_i32 m0, s64, 0x2000
	s_nop 0
	global_load_lds_dwordx4 v[222:223], off
	v_lshl_add_u64 v[222:223], s[40:41], 0, v[134:135]
	s_mov_b32 m0, s11
	s_nop 0
	global_load_lds_dwordx4 v[222:223], off
	s_mov_b32 m0, s45
	s_nop 0
	global_load_lds_dwordx4 v[238:239], off
	s_waitcnt vmcnt(8)
	s_waitcnt lgkmcnt(0)
	s_setprio 1
	s_barrier
	v_mfma_f32_16x16x32_bf16 v[62:65], v[140:143], v[176:179], v[62:65]
	v_mfma_f32_16x16x32_bf16 v[58:61], v[148:151], v[176:179], v[58:61]
	v_mfma_f32_16x16x32_bf16 v[42:45], v[148:151], v[194:197], v[42:45]
	v_mfma_f32_16x16x32_bf16 v[46:49], v[140:143], v[194:197], v[46:49]
	v_mfma_f32_16x16x32_bf16 v[30:33], v[140:143], v[202:205], v[30:33]
	v_mfma_f32_16x16x32_bf16 v[26:29], v[148:151], v[202:205], v[26:29]
	v_mfma_f32_16x16x32_bf16 v[10:13], v[148:151], v[210:213], v[10:13]
	v_mfma_f32_16x16x32_bf16 v[14:17], v[140:143], v[210:213], v[14:17]
	v_mfma_f32_16x16x32_bf16 v[62:65], v[144:147], v[190:193], v[62:65]
	v_mfma_f32_16x16x32_bf16 v[58:61], v[156:159], v[190:193], v[58:61]
	v_mfma_f32_16x16x32_bf16 v[42:45], v[156:159], v[198:201], v[42:45]
	v_mfma_f32_16x16x32_bf16 v[46:49], v[144:147], v[198:201], v[46:49]
	v_mfma_f32_16x16x32_bf16 v[30:33], v[144:147], v[206:209], v[30:33]
	v_mfma_f32_16x16x32_bf16 v[26:29], v[156:159], v[206:209], v[26:29]
	v_mfma_f32_16x16x32_bf16 v[10:13], v[156:159], v[214:217], v[10:13]
	v_mfma_f32_16x16x32_bf16 v[14:17], v[144:147], v[214:217], v[14:17]
	v_mfma_f32_16x16x32_bf16 v[54:57], v[160:163], v[176:179], v[54:57]
	v_mfma_f32_16x16x32_bf16 v[50:53], v[168:171], v[176:179], v[50:53]
	v_mfma_f32_16x16x32_bf16 v[34:37], v[168:171], v[194:197], v[34:37]
	v_mfma_f32_16x16x32_bf16 v[38:41], v[160:163], v[194:197], v[38:41]
	v_mfma_f32_16x16x32_bf16 v[22:25], v[160:163], v[202:205], v[22:25]
	v_mfma_f32_16x16x32_bf16 v[18:21], v[168:171], v[202:205], v[18:21]
	v_mfma_f32_16x16x32_bf16 v[2:5], v[168:171], v[210:213], v[2:5]
	v_mfma_f32_16x16x32_bf16 v[6:9], v[160:163], v[210:213], v[6:9]
	v_mfma_f32_16x16x32_bf16 v[54:57], v[164:167], v[190:193], v[54:57]
	v_mfma_f32_16x16x32_bf16 v[50:53], v[172:175], v[190:193], v[50:53]
	v_mfma_f32_16x16x32_bf16 v[34:37], v[172:175], v[198:201], v[34:37]
	v_mfma_f32_16x16x32_bf16 v[38:41], v[164:167], v[198:201], v[38:41]
	v_mfma_f32_16x16x32_bf16 v[22:25], v[164:167], v[206:209], v[22:25]
	v_mfma_f32_16x16x32_bf16 v[18:21], v[172:175], v[206:209], v[18:21]
	v_mfma_f32_16x16x32_bf16 v[2:5], v[172:175], v[214:217], v[2:5]
	v_mfma_f32_16x16x32_bf16 v[6:9], v[164:167], v[214:217], v[6:9]
	s_barrier
	s_setprio 0
	s_add_i32 s64, 0, 0x18000
	v_add_u32_e32 v155, s64, v153
	s_add_i32 s70, 0, 0x1c000
	ds_read_b128 v[140:143], v155
	ds_read_b128 v[148:151], v155 offset:2048
	v_xor_b32_e32 v155, 64, v155
	ds_read_b128 v[144:147], v155
	ds_read_b128 v[156:159], v155 offset:2048
	v_add_u32_e32 v155, s70, v153
	ds_read_b128 v[160:163], v155
	ds_read_b128 v[168:171], v155 offset:2048
	v_xor_b32_e32 v155, 64, v155
	ds_read_b128 v[164:167], v155
	ds_read_b128 v[172:175], v155 offset:2048
	s_add_u32 s40, s40, 0x80000
	s_addc_u32 s41, s41, 0
	s_mov_b32 m0, s46
	v_lshl_add_u64 v[240:241], s[40:41], 0, v[134:135]
	ds_read_b128 v[176:179], v154 offset:32768
	ds_read_b128 v[194:197], v154 offset:34816
	ds_read_b128 v[202:205], v154 offset:36864
	ds_read_b128 v[210:213], v154 offset:38912
	v_xor_b32_e32 v214, 64, v154
	ds_read_b128 v[190:193], v214 offset:32768
	ds_read_b128 v[198:201], v214 offset:34816
	ds_read_b128 v[206:209], v214 offset:36864
	ds_read_b128 v[214:217], v214 offset:38912
	global_load_lds_dwordx4 v[240:241], off
	v_lshl_add_u64 v[240:241], s[40:41], 0, v[132:133]
	s_mov_b32 m0, s47
	s_nop 0
	global_load_lds_dwordx4 v[240:241], off
	s_waitcnt vmcnt(8)
	s_waitcnt lgkmcnt(0)
	s_setprio 1
	s_barrier
	v_mfma_f32_16x16x32_bf16 v[126:129], v[140:143], v[176:179], v[126:129]
	v_mfma_f32_16x16x32_bf16 v[122:125], v[148:151], v[176:179], v[122:125]
	v_mfma_f32_16x16x32_bf16 v[106:109], v[148:151], v[194:197], v[106:109]
	v_mfma_f32_16x16x32_bf16 v[110:113], v[140:143], v[194:197], v[110:113]
	v_mfma_f32_16x16x32_bf16 v[94:97], v[140:143], v[202:205], v[94:97]
	v_mfma_f32_16x16x32_bf16 v[90:93], v[148:151], v[202:205], v[90:93]
	v_mfma_f32_16x16x32_bf16 v[74:77], v[148:151], v[210:213], v[74:77]
	v_mfma_f32_16x16x32_bf16 v[78:81], v[140:143], v[210:213], v[78:81]
	v_mfma_f32_16x16x32_bf16 v[126:129], v[144:147], v[190:193], v[126:129]
	v_mfma_f32_16x16x32_bf16 v[122:125], v[156:159], v[190:193], v[122:125]
	v_mfma_f32_16x16x32_bf16 v[106:109], v[156:159], v[198:201], v[106:109]
	v_mfma_f32_16x16x32_bf16 v[110:113], v[144:147], v[198:201], v[110:113]
	v_mfma_f32_16x16x32_bf16 v[94:97], v[144:147], v[206:209], v[94:97]
	v_mfma_f32_16x16x32_bf16 v[90:93], v[156:159], v[206:209], v[90:93]
	v_mfma_f32_16x16x32_bf16 v[74:77], v[156:159], v[214:217], v[74:77]
	v_mfma_f32_16x16x32_bf16 v[78:81], v[144:147], v[214:217], v[78:81]
	v_mfma_f32_16x16x32_bf16 v[118:121], v[160:163], v[176:179], v[118:121]
	v_mfma_f32_16x16x32_bf16 v[114:117], v[168:171], v[176:179], v[114:117]
	v_mfma_f32_16x16x32_bf16 v[98:101], v[168:171], v[194:197], v[98:101]
	v_mfma_f32_16x16x32_bf16 v[102:105], v[160:163], v[194:197], v[102:105]
	v_mfma_f32_16x16x32_bf16 v[86:89], v[160:163], v[202:205], v[86:89]
	v_mfma_f32_16x16x32_bf16 v[82:85], v[168:171], v[202:205], v[82:85]
	v_mfma_f32_16x16x32_bf16 v[66:69], v[168:171], v[210:213], v[66:69]
	v_mfma_f32_16x16x32_bf16 v[70:73], v[160:163], v[210:213], v[70:73]
	v_mfma_f32_16x16x32_bf16 v[118:121], v[164:167], v[190:193], v[118:121]
	v_mfma_f32_16x16x32_bf16 v[114:117], v[172:175], v[190:193], v[114:117]
	v_mfma_f32_16x16x32_bf16 v[98:101], v[172:175], v[198:201], v[98:101]
	v_mfma_f32_16x16x32_bf16 v[102:105], v[164:167], v[198:201], v[102:105]
	v_mfma_f32_16x16x32_bf16 v[86:89], v[164:167], v[206:209], v[86:89]
	v_mfma_f32_16x16x32_bf16 v[82:85], v[172:175], v[206:209], v[82:85]
	v_mfma_f32_16x16x32_bf16 v[66:69], v[172:175], v[214:217], v[66:69]
	v_mfma_f32_16x16x32_bf16 v[70:73], v[164:167], v[214:217], v[70:73]
	s_barrier
	s_setprio 0
	s_add_i32 s40, s64, s43
	v_lshl_add_u64 v[218:219], v[218:219], 0, s[16:17]
	s_mov_b32 m0, s40
	ds_read_b128 v[176:179], v154 offset:49152
	ds_read_b128 v[194:197], v154 offset:51200
	ds_read_b128 v[202:205], v154 offset:53248
	ds_read_b128 v[210:213], v154 offset:55296
	v_xor_b32_e32 v214, 64, v154
	ds_read_b128 v[190:193], v214 offset:49152
	ds_read_b128 v[198:201], v214 offset:51200
	ds_read_b128 v[206:209], v214 offset:53248
	ds_read_b128 v[214:217], v214 offset:55296
	global_load_lds_dwordx4 v[218:219], off
	s_add_i32 m0, s40, 0x2000
	s_add_u32 s38, s38, 0x80080
	v_lshl_add_u64 v[218:219], v[220:221], 0, s[16:17]
	s_addc_u32 s39, s39, 0
	s_add_i32 s40, s70, s43
	global_load_lds_dwordx4 v[218:219], off
	v_lshl_add_u64 v[218:219], s[38:39], 0, v[134:135]
	s_mov_b32 m0, s40
	s_nop 0
	global_load_lds_dwordx4 v[218:219], off
	v_lshl_add_u64 v[218:219], s[38:39], 0, v[132:133]
	s_add_i32 m0, s40, 0x2000
	s_nop 0
	global_load_lds_dwordx4 v[218:219], off
	v_lshl_add_u64 v[218:219], v[222:223], 0, s[16:17]
	s_mov_b32 m0, s50
	s_nop 0
	global_load_lds_dwordx4 v[218:219], off
	v_lshl_add_u64 v[218:219], v[238:239], 0, s[16:17]
	s_mov_b32 m0, s51
	s_nop 0
	global_load_lds_dwordx4 v[218:219], off
	s_waitcnt vmcnt(8)
	s_waitcnt lgkmcnt(0)
	s_setprio 1
	s_barrier
	v_mfma_f32_16x16x32_bf16 v[62:65], v[140:143], v[176:179], v[62:65]
	v_mfma_f32_16x16x32_bf16 v[58:61], v[148:151], v[176:179], v[58:61]
	v_mfma_f32_16x16x32_bf16 v[42:45], v[148:151], v[194:197], v[42:45]
	v_mfma_f32_16x16x32_bf16 v[46:49], v[140:143], v[194:197], v[46:49]
	v_mfma_f32_16x16x32_bf16 v[30:33], v[140:143], v[202:205], v[30:33]
	v_mfma_f32_16x16x32_bf16 v[26:29], v[148:151], v[202:205], v[26:29]
	v_mfma_f32_16x16x32_bf16 v[10:13], v[148:151], v[210:213], v[10:13]
	v_mfma_f32_16x16x32_bf16 v[14:17], v[140:143], v[210:213], v[14:17]
	v_mfma_f32_16x16x32_bf16 v[62:65], v[144:147], v[190:193], v[62:65]
	v_mfma_f32_16x16x32_bf16 v[58:61], v[156:159], v[190:193], v[58:61]
	v_mfma_f32_16x16x32_bf16 v[42:45], v[156:159], v[198:201], v[42:45]
	v_mfma_f32_16x16x32_bf16 v[46:49], v[144:147], v[198:201], v[46:49]
	v_mfma_f32_16x16x32_bf16 v[30:33], v[144:147], v[206:209], v[30:33]
	v_mfma_f32_16x16x32_bf16 v[26:29], v[156:159], v[206:209], v[26:29]
	v_mfma_f32_16x16x32_bf16 v[10:13], v[156:159], v[214:217], v[10:13]
	v_mfma_f32_16x16x32_bf16 v[14:17], v[144:147], v[214:217], v[14:17]
	v_mfma_f32_16x16x32_bf16 v[54:57], v[160:163], v[176:179], v[54:57]
	v_mfma_f32_16x16x32_bf16 v[50:53], v[168:171], v[176:179], v[50:53]
	v_mfma_f32_16x16x32_bf16 v[34:37], v[168:171], v[194:197], v[34:37]
	v_mfma_f32_16x16x32_bf16 v[38:41], v[160:163], v[194:197], v[38:41]
	v_mfma_f32_16x16x32_bf16 v[22:25], v[160:163], v[202:205], v[22:25]
	v_mfma_f32_16x16x32_bf16 v[18:21], v[168:171], v[202:205], v[18:21]
	v_mfma_f32_16x16x32_bf16 v[2:5], v[168:171], v[210:213], v[2:5]
	v_mfma_f32_16x16x32_bf16 v[6:9], v[160:163], v[210:213], v[6:9]
	v_mfma_f32_16x16x32_bf16 v[54:57], v[164:167], v[190:193], v[54:57]
	v_mfma_f32_16x16x32_bf16 v[50:53], v[172:175], v[190:193], v[50:53]
	v_mfma_f32_16x16x32_bf16 v[34:37], v[172:175], v[198:201], v[34:37]
	v_mfma_f32_16x16x32_bf16 v[38:41], v[164:167], v[198:201], v[38:41]
	v_mfma_f32_16x16x32_bf16 v[22:25], v[164:167], v[206:209], v[22:25]
	v_mfma_f32_16x16x32_bf16 v[18:21], v[172:175], v[206:209], v[18:21]
	v_mfma_f32_16x16x32_bf16 v[2:5], v[172:175], v[214:217], v[2:5]
	v_mfma_f32_16x16x32_bf16 v[6:9], v[164:167], v[214:217], v[6:9]
	s_barrier
	s_setprio 0
	s_add_i32 s63, s63, 2
	s_add_u32 s36, s36, 0x100
	s_addc_u32 s37, s37, 0
	s_add_u32 s61, s61, 0x100
	s_addc_u32 s62, s62, 0
	s_cmp_gt_u32 s63, 29
	s_cbranch_scc0 .LBB0_1230
	s_and_b64 vcc, exec, s[30:31]
	s_cbranch_vccz .LBB0_1233
	s_barrier

.LBB0_1571:
	v_ashrrev_i32_e32 v4, 31, v2
	v_lshrrev_b32_e32 v4, 26, v4
	v_add_u32_e32 v4, v2, v4
	v_ashrrev_i32_e32 v146, 6, v4
	v_bfe_i32 v4, v2, 27, 1
	v_lshlrev_b32_e32 v3, 4, v2
	v_lshrrev_b32_e32 v4, 22, v4
	v_add_u32_e32 v4, v3, v4
	v_and_b32_e32 v4, 0xfffffc00, v4
	v_sub_u32_e32 v4, v3, v4
	v_lshrrev_b32_e32 v5, 4, v4
	v_bitop3_b32 v4, v5, v4, 32 bitop3:0x6c
	v_ashrrev_i32_e32 v6, 31, v4
	v_lshrrev_b32_e32 v6, 26, v6
	v_add_u32_e32 v6, v4, v6
	v_lshlrev_b32_e32 v5, 3, v146
	v_ashrrev_i32_e32 v147, 6, v6
	v_and_b32_e32 v6, 0xc0, v6
	v_and_b32_e32 v5, -16, v5
	v_sub_u32_e32 v4, v4, v6
	v_add_u32_e32 v5, v147, v5
	v_ashrrev_i16_sdwa v4, v224, sext(v4) dst_sel:DWORD dst_unused:UNUSED_PAD src0_sel:DWORD src1_sel:BYTE_0
	v_lshlrev_b32_e32 v7, 5, v146
	v_bfe_i32 v153, v4, 0, 16
	v_lshlrev_b32_e32 v4, 1, v5
	v_lshrrev_b32_e32 v6, 2, v5
	v_and_b32_e32 v8, 3, v147
	s_mov_b32 s8, 0xfffe0
	v_and_b32_e32 v7, 32, v7
	v_and_b32_e32 v4, 24, v4
	v_and_b32_e32 v6, 4, v6
	v_and_or_b32 v8, v5, s8, v8
	v_or3_b32 v4, v8, v6, v4
	v_add_lshl_u32 v6, v7, v153, 1
	v_add_u32_e32 v3, 0x2000, v3
	s_waitcnt vmcnt(0)
	v_lshl_add_u32 v134, v4, 12, v6
	v_ashrrev_i32_e32 v4, 31, v3
	v_lshrrev_b32_e32 v4, 22, v4
	v_add_u32_e32 v4, v3, v4
	v_ashrrev_i32_e32 v154, 10, v4
	v_mul_i32_i24_e32 v4, 0x400, v154
	v_sub_u32_e32 v3, v3, v4
	v_lshrrev_b32_e32 v4, 4, v3
	v_bitop3_b32 v3, v4, v3, 32 bitop3:0x6c
	v_lshl_add_u32 v132, v5, 12, v6
	v_ashrrev_i32_e32 v5, 31, v3
	v_lshrrev_b32_e32 v5, 26, v5
	v_lshlrev_b32_e32 v4, 3, v154
	v_add_u32_e32 v5, v3, v5
	v_and_b32_e32 v4, -16, v4
	v_ashrrev_i32_e32 v155, 6, v5
	v_add_u32_e32 v4, v155, v4
	v_and_b32_e32 v7, 3, v155
	s_ashr_i32 s12, s30, 6
	s_ashr_i32 s28, s30, 8
	v_and_b32_e32 v5, 0xc0, v5
	v_and_or_b32 v7, v4, s8, v7
	s_lshl_b32 s8, s12, 10
	s_lshl_b32 s12, s12, 5
	v_sub_u32_e32 v3, v3, v5
	s_lshl_b32 s9, s28, 6
	s_and_b32 s21, s12, 0x60
	v_ashrrev_i16_sdwa v3, v224, sext(v3) dst_sel:DWORD dst_unused:UNUSED_PAD src0_sel:DWORD src1_sel:BYTE_0
	s_add_u32 s54, s26, 0x24600000
	v_lshlrev_b32_e32 v6, 5, v154
	v_bfe_i32 v156, v3, 0, 16
	v_lshlrev_b32_e32 v3, 1, v4
	v_lshrrev_b32_e32 v5, 2, v4
	s_addc_u32 s55, s27, 0
	s_lshl_b32 s12, s44, 8
	v_and_b32_e32 v6, 32, v6
	v_and_b32_e32 v3, 24, v3
	v_and_b32_e32 v5, 4, v5
	v_and_b32_e32 v150, 15, v2
	s_add_i32 s12, s12, s9
	v_bfe_u32 v131, v2, 4, 2
	v_or3_b32 v3, v7, v5, v3
	v_add_lshl_u32 v5, v6, v156, 1
	v_or_b32_e32 v2, s12, v150
	v_lshl_add_u32 v138, v3, 12, v5
	v_ashrrev_i32_e32 v3, 31, v2
	v_lshlrev_b64 v[2:3], 12, v[2:3]
	s_lshl_b32 s26, s38, 8
	v_lshl_add_u64 v[2:3], s[14:15], 0, v[2:3]
	s_ashr_i32 s27, s26, 31
	v_lshl_add_u64 v[2:3], s[26:27], 1, v[2:3]
	s_lshl_b32 s12, s21, 1
	v_lshl_add_u64 v[2:3], v[2:3], 0, s[12:13]
	v_lshlrev_b32_e32 v180, 4, v131
	v_lshl_add_u64 v[2:3], v[2:3], 0, v[180:181]
	s_mov_b32 s26, 0x10000
	v_lshl_add_u32 v136, v4, 12, v5
	v_add_co_u32_e32 v4, vcc, s26, v2
	s_mov_b32 s26, 0x20000
	s_nop 0
	v_addc_co_u32_e32 v5, vcc, 0, v3, vcc
	global_load_dwordx4 v[64:67], v[2:3], off
	global_load_dwordx4 v[60:63], v[2:3], off offset:256
	global_load_dwordx4 v[56:59], v[4:5], off
	global_load_dwordx4 v[52:55], v[4:5], off offset:256
	v_add_co_u32_e32 v4, vcc, s26, v2
	s_mov_b32 s26, 0x30000
	s_nop 0
	v_addc_co_u32_e32 v5, vcc, 0, v3, vcc
	global_load_dwordx4 v[48:51], v[4:5], off
	global_load_dwordx4 v[44:47], v[4:5], off offset:256
	v_add_co_u32_e32 v4, vcc, s26, v2
	s_mov_b32 s26, 0x80000
	s_nop 0
	v_addc_co_u32_e32 v5, vcc, 0, v3, vcc
	global_load_dwordx4 v[40:43], v[4:5], off
	global_load_dwordx4 v[36:39], v[4:5], off offset:256
	v_add_co_u32_e32 v4, vcc, s26, v2
	s_mov_b32 s26, 0x90000
	s_nop 0
	v_addc_co_u32_e32 v5, vcc, 0, v3, vcc
	global_load_dwordx4 v[32:35], v[4:5], off
	global_load_dwordx4 v[28:31], v[4:5], off offset:256
	v_add_co_u32_e32 v4, vcc, s26, v2
	s_mov_b32 s26, 0xa0000
	s_nop 0
	v_addc_co_u32_e32 v5, vcc, 0, v3, vcc
	global_load_dwordx4 v[24:27], v[4:5], off
	global_load_dwordx4 v[18:21], v[4:5], off offset:256
	v_add_co_u32_e32 v4, vcc, s26, v2
	s_mov_b32 s26, 0xb0000
	s_nop 0
	v_addc_co_u32_e32 v5, vcc, 0, v3, vcc
	s_ashr_i32 s45, s44, 31
	s_ashr_i32 s39, s38, 31
	v_add_co_u32_e32 v14, vcc, s26, v2
	s_lshl_b64 s[26:27], s[44:45], 20
	s_lshl_b64 s[34:35], s[38:39], 20
	s_add_u32 s46, s18, s34
	s_addc_u32 s47, s19, s35
	s_add_i32 s56, s8, 0
	v_addc_co_u32_e32 v15, vcc, 0, v3, vcc
	s_add_i32 m0, s56, 0x10000
	global_load_dwordx4 v[10:13], v[4:5], off
	global_load_dwordx4 v[6:9], v[4:5], off offset:256
	s_nop 0
	global_load_dwordx4 v[2:5], v[14:15], off
	s_nop 0
	global_load_dwordx4 v[14:17], v[14:15], off offset:256
	v_mov_b32_e32 v135, v181
	v_and_b32_e32 v144, 63, v0
	v_lshrrev_b32_e32 v145, 3, v144
	v_and_b32_e32 v144, 7, v144
	v_xor_b32_e32 v144, v144, v145
	v_lshlrev_b32_e32 v144, 4, v144
	v_lshrrev_b32_e32 v157, 6, v0
	v_lshl_add_u32 v145, v157, 3, v145
	v_mov_b32_e32 v157, 0x1000
	v_mad_u32_u24 v132, v145, v157, v144
	v_add_u32_e32 v136, 0x40000, v132
	v_and_b32_e32 v158, 15, v145
	v_lshrrev_b32_e32 v157, 2, v158
	v_and_b32_e32 v158, 3, v158
	v_lshl_add_u32 v158, v157, 3, v158
	v_bfe_u32 v157, v145, 4, 1
	v_lshl_add_u32 v158, v157, 2, v158
	v_and_b32_e32 v157, 0x60, v145
	v_or_b32_e32 v158, v157, v158
	v_mov_b32_e32 v157, 0x1000
	v_mad_u32_u24 v134, v158, v157, v144
	v_add_u32_e32 v138, 0x40000, v134
	global_load_lds_dwordx4 v134, s[46:47]
	s_add_i32 m0, s56, 0x12000
	s_add_u32 s34, s46, 0x80000
	global_load_lds_dwordx4 v138, s[46:47]
	s_addc_u32 s35, s47, 0
	s_add_i32 m0, s56, 0x14000
	v_mov_b32_e32 v139, v181
	global_load_lds_dwordx4 v134, s[34:35]
	s_add_i32 m0, s56, 0x16000
	s_add_u32 s48, s54, s26
	s_addc_u32 s49, s55, s27
	s_add_i32 s57, s56, 0x2000
	global_load_lds_dwordx4 v138, s[34:35]
	s_mov_b32 m0, s56
	s_add_u32 s26, s48, 0x80000
	global_load_lds_dwordx4 v132, s[48:49]
	s_mov_b32 m0, s57
	s_addc_u32 s27, s49, 0
	s_add_i32 s58, s56, 0x4000
	global_load_lds_dwordx4 v136, s[48:49]
	s_mov_b32 m0, s58
	s_add_i32 s59, s56, 0x6000
	global_load_lds_dwordx4 v132, s[26:27]
	s_mov_b32 m0, s59
	v_mov_b32_e32 v133, v181
	global_load_lds_dwordx4 v136, s[26:27]
	v_mov_b32_e32 v137, v181
	s_cmp_eq_u32 s28, 1
	v_lshl_add_u64 v[144:145], s[46:47], 0, v[134:135]
	v_lshl_add_u64 v[142:143], s[46:47], 0, v[138:139]
	v_lshl_add_u64 v[68:69], s[48:49], 0, v[132:133]
	s_cselect_b64 s[26:27], -1, 0
	s_cmp_lg_u32 s28, 1
	v_lshl_add_u64 v[140:141], s[48:49], 0, v[136:137]
	s_cbranch_scc1 .LBB0_1573
	s_barrier
.LBB0_1573:
	s_waitcnt vmcnt(0)
	v_lshlrev_b32_e32 v90, 16, v48
	v_and_b32_e32 v91, 0xffff0000, v48
	v_lshlrev_b32_e32 v92, 16, v49
	v_and_b32_e32 v93, 0xffff0000, v49
	v_lshlrev_b32_e32 v94, 16, v46
	v_and_b32_e32 v95, 0xffff0000, v46
	v_lshlrev_b32_e32 v96, 16, v47
	v_and_b32_e32 v97, 0xffff0000, v47
	v_lshlrev_b32_e32 v46, 16, v28
	v_and_b32_e32 v47, 0xffff0000, v28
	v_lshlrev_b32_e32 v48, 16, v29
	v_and_b32_e32 v49, 0xffff0000, v29
	s_add_i32 m0, s56, 0x18000
	v_lshl_add_u64 v[28:29], v[144:145], 0, s[16:17]
	s_lshl_b32 s31, s28, 13
	s_lshl_b32 s34, s21, 7
	s_waitcnt vmcnt(2)
	s_barrier
	global_load_lds_dwordx4 v[28:29], off
	v_lshl_add_u64 v[28:29], v[142:143], 0, s[16:17]
	s_add_i32 m0, s56, 0x1a000
	s_add_i32 s60, s56, 0x8000
	s_add_i32 s61, s56, 0xa000
	global_load_lds_dwordx4 v[28:29], off
	v_lshl_add_u64 v[28:29], v[68:69], 0, s[16:17]
	s_mov_b32 m0, s60
	s_add_u32 s28, s46, 0x80080
	global_load_lds_dwordx4 v[28:29], off
	v_lshl_add_u64 v[28:29], v[140:141], 0, s[16:17]
	s_mov_b32 m0, s61
	s_addc_u32 s29, s47, 0
	global_load_lds_dwordx4 v[28:29], off
	s_add_i32 m0, s56, 0x1c000
	v_lshl_add_u64 v[28:29], s[28:29], 0, v[134:135]
	global_load_lds_dwordx4 v[28:29], off
	v_lshl_add_u64 v[28:29], s[28:29], 0, v[138:139]
	s_add_i32 m0, s56, 0x1e000
	v_or_b32_e32 v151, s9, v150
	global_load_lds_dwordx4 v[28:29], off
	v_lshlrev_b32_e32 v140, 6, v151
	s_movk_i32 s28, 0x3c0
	v_lshlrev_b32_e32 v141, 2, v151
	v_and_or_b32 v140, v140, s28, v180
	v_and_b32_e32 v141, 32, v141
	v_bitop3_b32 v144, v140, s31, v141 bitop3:0xde
	v_lshlrev_b32_e32 v141, 2, v150
	v_lshl_or_b32 v140, v150, 6, v180
	v_and_b32_e32 v141, 32, v141
	v_bitop3_b32 v152, v140, s34, v141 bitop3:0xde
	v_lshlrev_b32_e32 v140, 15, v146
	v_lshlrev_b32_e32 v142, 15, v154
	v_and_b32_e32 v140, 0xffff0000, v140
	v_and_b32_e32 v142, 0xffff0000, v142
	s_waitcnt vmcnt(6)
	v_lshl_add_u32 v140, v147, 12, v140
	v_and_b32_e32 v141, 1, v146
	v_lshl_add_u32 v142, v155, 12, v142
	v_and_b32_e32 v143, 1, v154
	v_lshlrev_b32_e32 v157, 3, v131
	s_cmpk_lt_u32 s30, 0x100
	v_lshl_or_b32 v140, v141, 6, v140
	v_lshl_or_b32 v142, v143, 6, v142
	v_lshlrev_b32_e32 v126, 16, v64
	v_and_b32_e32 v127, 0xffff0000, v64
	v_lshlrev_b32_e32 v128, 16, v65
	v_and_b32_e32 v129, 0xffff0000, v65
	v_lshlrev_b32_e32 v114, 16, v66
	v_and_b32_e32 v115, 0xffff0000, v66
	v_lshlrev_b32_e32 v116, 16, v67
	v_and_b32_e32 v117, 0xffff0000, v67
	v_lshlrev_b32_e32 v118, 16, v60
	v_and_b32_e32 v119, 0xffff0000, v60
	v_lshlrev_b32_e32 v120, 16, v61
	v_and_b32_e32 v121, 0xffff0000, v61
	v_lshlrev_b32_e32 v122, 16, v62
	v_and_b32_e32 v123, 0xffff0000, v62
	v_lshlrev_b32_e32 v124, 16, v63
	v_and_b32_e32 v125, 0xffff0000, v63
	v_lshlrev_b32_e32 v106, 16, v56
	v_and_b32_e32 v107, 0xffff0000, v56
	v_lshlrev_b32_e32 v108, 16, v57
	v_and_b32_e32 v109, 0xffff0000, v57
	v_lshlrev_b32_e32 v98, 16, v58
	v_and_b32_e32 v99, 0xffff0000, v58
	v_lshlrev_b32_e32 v100, 16, v59
	v_and_b32_e32 v101, 0xffff0000, v59
	v_lshlrev_b32_e32 v102, 16, v52
	v_and_b32_e32 v103, 0xffff0000, v52
	v_lshlrev_b32_e32 v104, 16, v53
	v_and_b32_e32 v105, 0xffff0000, v53
	v_lshlrev_b32_e32 v110, 16, v54
	v_and_b32_e32 v111, 0xffff0000, v54
	v_lshlrev_b32_e32 v112, 16, v55
	v_and_b32_e32 v113, 0xffff0000, v55
	v_lshlrev_b32_e32 v82, 16, v50
	v_and_b32_e32 v83, 0xffff0000, v50
	v_lshlrev_b32_e32 v84, 16, v51
	v_and_b32_e32 v85, 0xffff0000, v51
	v_lshlrev_b32_e32 v86, 16, v44
	v_and_b32_e32 v87, 0xffff0000, v44
	v_lshlrev_b32_e32 v88, 16, v45
	v_and_b32_e32 v89, 0xffff0000, v45
	v_lshlrev_b32_e32 v74, 16, v40
	v_and_b32_e32 v75, 0xffff0000, v40
	v_lshlrev_b32_e32 v76, 16, v41
	v_and_b32_e32 v77, 0xffff0000, v41
	v_lshlrev_b32_e32 v54, 16, v42
	v_and_b32_e32 v55, 0xffff0000, v42
	v_lshlrev_b32_e32 v56, 16, v43
	v_and_b32_e32 v57, 0xffff0000, v43
	v_lshlrev_b32_e32 v70, 16, v36
	v_and_b32_e32 v71, 0xffff0000, v36
	v_lshlrev_b32_e32 v72, 16, v37
	v_and_b32_e32 v73, 0xffff0000, v37
	v_lshlrev_b32_e32 v78, 16, v38
	v_and_b32_e32 v79, 0xffff0000, v38
	v_lshlrev_b32_e32 v80, 16, v39
	v_and_b32_e32 v81, 0xffff0000, v39
	v_lshlrev_b32_e32 v50, 16, v32
	v_and_b32_e32 v51, 0xffff0000, v32
	v_lshlrev_b32_e32 v52, 16, v33
	v_and_b32_e32 v53, 0xffff0000, v33
	v_lshlrev_b32_e32 v38, 16, v34
	v_and_b32_e32 v39, 0xffff0000, v34
	v_lshlrev_b32_e32 v40, 16, v35
	v_and_b32_e32 v41, 0xffff0000, v35
	v_lshlrev_b32_e32 v58, 16, v30
	v_and_b32_e32 v59, 0xffff0000, v30
	v_lshlrev_b32_e32 v60, 16, v31
	v_and_b32_e32 v61, 0xffff0000, v31
	v_lshlrev_b32_e32 v22, 16, v24
	v_and_b32_e32 v23, 0xffff0000, v24
	v_lshlrev_b32_e32 v24, 16, v25
	v_and_b32_e32 v25, 0xffff0000, v25
	v_lshlrev_b32_e32 v42, 16, v26
	v_and_b32_e32 v43, 0xffff0000, v26
	v_lshlrev_b32_e32 v44, 16, v27
	v_and_b32_e32 v45, 0xffff0000, v27
	v_lshlrev_b32_e32 v62, 16, v18
	v_and_b32_e32 v63, 0xffff0000, v18
	v_lshlrev_b32_e32 v64, 16, v19
	v_and_b32_e32 v65, 0xffff0000, v19
	v_lshlrev_b32_e32 v66, 16, v20
	v_and_b32_e32 v67, 0xffff0000, v20
	v_lshlrev_b32_e32 v68, 16, v21
	v_and_b32_e32 v69, 0xffff0000, v21
	v_lshlrev_b32_e32 v30, 16, v10
	v_and_b32_e32 v31, 0xffff0000, v10
	v_lshlrev_b32_e32 v32, 16, v11
	v_and_b32_e32 v33, 0xffff0000, v11
	v_lshlrev_b32_e32 v18, 16, v12
	v_and_b32_e32 v19, 0xffff0000, v12
	v_lshlrev_b32_e32 v20, 16, v13
	v_and_b32_e32 v21, 0xffff0000, v13
	v_lshlrev_b32_e32 v26, 16, v6
	v_and_b32_e32 v27, 0xffff0000, v6
	v_lshlrev_b32_e32 v28, 16, v7
	v_and_b32_e32 v29, 0xffff0000, v7
	v_lshlrev_b32_e32 v34, 16, v8
	v_and_b32_e32 v35, 0xffff0000, v8
	v_lshlrev_b32_e32 v36, 16, v9
	v_and_b32_e32 v37, 0xffff0000, v9
	v_lshlrev_b32_e32 v10, 16, v2
	v_and_b32_e32 v11, 0xffff0000, v2
	v_lshlrev_b32_e32 v12, 16, v3
	v_and_b32_e32 v13, 0xffff0000, v3
	v_lshlrev_b32_e32 v2, 16, v4
	v_and_b32_e32 v3, 0xffff0000, v4
	v_lshlrev_b32_e32 v4, 16, v5
	v_and_b32_e32 v5, 0xffff0000, v5
	v_lshlrev_b32_e32 v6, 16, v14
	v_and_b32_e32 v7, 0xffff0000, v14
	v_lshlrev_b32_e32 v8, 16, v15
	v_and_b32_e32 v9, 0xffff0000, v15
	v_lshlrev_b32_e32 v14, 16, v16
	v_and_b32_e32 v15, 0xffff0000, v16
	v_lshlrev_b32_e32 v16, 16, v17
	v_and_b32_e32 v17, 0xffff0000, v17
	s_cselect_b64 s[28:29], -1, 0
	s_ashr_i32 s62, s7, 31
	v_mov_b32_e32 v140, v132
	v_mov_b32_e32 v141, v181
	v_mov_b32_e32 v142, v136
	v_mov_b32_e32 v143, v181
	s_mov_b32 s63, 0
	v_add_u32_e32 v153, 0, v144
	v_lshlrev_b32_e32 v180, 1, v157
	v_and_b32_e32 v144, 7, v0
	v_bfe_u32 v145, v0, 4, 2
	v_xor_b32_e32 v145, v145, v144
	v_lshlrev_b32_e32 v145, 4, v145
	v_lshl_add_u32 v145, v144, 7, v145
	v_bfe_u32 v144, v0, 3, 1
	v_lshl_add_u32 v145, v144, 10, v145
	v_lshrrev_b32_e32 v144, 8, v0
	v_lshl_add_u32 v153, v144, 13, v145
	v_bfe_u32 v144, v0, 6, 2
	v_lshl_add_u32 v152, v144, 12, v145
	s_barrier
	s_branch .LBB0_1576

.LBB0_1583:
	s_add_u32 s46, s48, 0xfff80080
	s_addc_u32 s47, s49, -1
	s_add_i32 s68, 0, 0x10000
	s_cmp_eq_u32 s67, 28
	s_cselect_b32 s51, s35, s47
	s_cselect_b32 s50, s39, s46
	s_cselect_b32 s47, s31, s66
	s_cselect_b32 s46, s45, s64
	s_add_i32 s70, 0, 0x14000
	v_add_u32_e32 v162, s68, v152
	v_add_u32_e32 v178, s70, v152
	ds_read_b128 v[144:147], v162
	ds_read_b128 v[158:161], v162 offset:2048
	v_xor_b32_e32 v162, 64, v162
	ds_read_b128 v[154:157], v162
	ds_read_b128 v[162:165], v162 offset:2048
	ds_read_b128 v[166:169], v178
	ds_read_b128 v[174:177], v178 offset:2048
	v_xor_b32_e32 v178, 64, v178
	ds_read_b128 v[170:173], v178
	ds_read_b128 v[190:193], v178 offset:2048
	v_lshl_add_u64 v[178:179], s[48:49], 0, v[140:141]
	s_add_i32 m0, s56, 0xc000
	ds_read_b128 v[194:197], v153
	ds_read_b128 v[202:205], v153 offset:2048
	ds_read_b128 v[210:213], v153 offset:4096
	ds_read_b128 v[218:221], v153 offset:6144
	v_xor_b32_e32 v238, 64, v153
	ds_read_b128 v[198:201], v238
	ds_read_b128 v[206:209], v238 offset:2048
	ds_read_b128 v[214:217], v238 offset:4096
	ds_read_b128 v[238:241], v238 offset:6144
	global_load_lds_dwordx4 v[178:179], off
	v_lshl_add_u64 v[178:179], s[48:49], 0, v[142:143]
	s_add_i32 m0, s56, 0xe000
	s_nop 0
	global_load_lds_dwordx4 v[178:179], off
	s_waitcnt vmcnt(8)
	s_waitcnt lgkmcnt(0)
	s_setprio 1
	s_barrier
	v_mfma_f32_16x16x32_bf16 v[126:129], v[144:147], v[194:197], v[126:129]
	v_mfma_f32_16x16x32_bf16 v[114:117], v[158:161], v[194:197], v[114:117]
	v_mfma_f32_16x16x32_bf16 v[98:101], v[158:161], v[202:205], v[98:101]
	v_mfma_f32_16x16x32_bf16 v[106:109], v[144:147], v[202:205], v[106:109]
	v_mfma_f32_16x16x32_bf16 v[90:93], v[144:147], v[210:213], v[90:93]
	v_mfma_f32_16x16x32_bf16 v[82:85], v[158:161], v[210:213], v[82:85]
	v_mfma_f32_16x16x32_bf16 v[54:57], v[158:161], v[218:221], v[54:57]
	v_mfma_f32_16x16x32_bf16 v[74:77], v[144:147], v[218:221], v[74:77]
	v_mfma_f32_16x16x32_bf16 v[126:129], v[154:157], v[198:201], v[126:129]
	v_mfma_f32_16x16x32_bf16 v[114:117], v[162:165], v[198:201], v[114:117]
	v_mfma_f32_16x16x32_bf16 v[98:101], v[162:165], v[206:209], v[98:101]
	v_mfma_f32_16x16x32_bf16 v[106:109], v[154:157], v[206:209], v[106:109]
	v_mfma_f32_16x16x32_bf16 v[90:93], v[154:157], v[214:217], v[90:93]
	v_mfma_f32_16x16x32_bf16 v[82:85], v[162:165], v[214:217], v[82:85]
	v_mfma_f32_16x16x32_bf16 v[54:57], v[162:165], v[238:241], v[54:57]
	v_mfma_f32_16x16x32_bf16 v[74:77], v[154:157], v[238:241], v[74:77]
	v_mfma_f32_16x16x32_bf16 v[118:121], v[166:169], v[194:197], v[118:121]
	v_mfma_f32_16x16x32_bf16 v[122:125], v[174:177], v[194:197], v[122:125]
	v_mfma_f32_16x16x32_bf16 v[110:113], v[174:177], v[202:205], v[110:113]
	v_mfma_f32_16x16x32_bf16 v[102:105], v[166:169], v[202:205], v[102:105]
	v_mfma_f32_16x16x32_bf16 v[86:89], v[166:169], v[210:213], v[86:89]
	v_mfma_f32_16x16x32_bf16 v[94:97], v[174:177], v[210:213], v[94:97]
	v_mfma_f32_16x16x32_bf16 v[78:81], v[174:177], v[218:221], v[78:81]
	v_mfma_f32_16x16x32_bf16 v[70:73], v[166:169], v[218:221], v[70:73]
	v_mfma_f32_16x16x32_bf16 v[118:121], v[170:173], v[198:201], v[118:121]
	v_mfma_f32_16x16x32_bf16 v[122:125], v[190:193], v[198:201], v[122:125]
	v_mfma_f32_16x16x32_bf16 v[110:113], v[190:193], v[206:209], v[110:113]
	v_mfma_f32_16x16x32_bf16 v[102:105], v[170:173], v[206:209], v[102:105]
	v_mfma_f32_16x16x32_bf16 v[86:89], v[170:173], v[214:217], v[86:89]
	v_mfma_f32_16x16x32_bf16 v[94:97], v[190:193], v[214:217], v[94:97]
	v_mfma_f32_16x16x32_bf16 v[78:81], v[190:193], v[238:241], v[78:81]
	v_mfma_f32_16x16x32_bf16 v[70:73], v[170:173], v[238:241], v[70:73]
	s_barrier
	s_setprio 0
	s_add_i32 s68, s68, s8
	v_lshl_add_u64 v[178:179], s[46:47], 0, v[134:135]
	s_mov_b32 m0, s68
	ds_read_b128 v[194:197], v153 offset:16384
	ds_read_b128 v[202:205], v153 offset:18432
	ds_read_b128 v[210:213], v153 offset:20480
	ds_read_b128 v[218:221], v153 offset:22528
	v_xor_b32_e32 v238, 64, v153
	ds_read_b128 v[198:201], v238 offset:16384
	ds_read_b128 v[206:209], v238 offset:18432
	ds_read_b128 v[214:217], v238 offset:20480
	ds_read_b128 v[238:241], v238 offset:22528
	global_load_lds_dwordx4 v[178:179], off
	s_add_i32 m0, s68, 0x2000
	s_add_u32 s68, s46, 0x80000
	v_lshl_add_u64 v[222:223], s[46:47], 0, v[138:139]
	s_addc_u32 s69, s47, 0
	s_add_i32 s70, s70, s8
	global_load_lds_dwordx4 v[222:223], off
	v_lshl_add_u64 v[242:243], s[68:69], 0, v[134:135]
	s_mov_b32 m0, s70
	v_lshl_add_u64 v[244:245], s[50:51], 0, v[136:137]
	global_load_lds_dwordx4 v[242:243], off
	v_lshl_add_u64 v[242:243], s[68:69], 0, v[138:139]
	s_add_i32 m0, s70, 0x2000
	s_nop 0
	global_load_lds_dwordx4 v[242:243], off
	v_lshl_add_u64 v[242:243], s[50:51], 0, v[132:133]
	s_mov_b32 m0, s56
	s_nop 0
	global_load_lds_dwordx4 v[242:243], off
	s_mov_b32 m0, s57
	s_nop 0
	global_load_lds_dwordx4 v[244:245], off
	s_waitcnt vmcnt(8)
	s_waitcnt lgkmcnt(0)
	s_setprio 1
	s_barrier
	v_mfma_f32_16x16x32_bf16 v[50:53], v[144:147], v[194:197], v[50:53]
	v_mfma_f32_16x16x32_bf16 v[38:41], v[158:161], v[194:197], v[38:41]
	v_mfma_f32_16x16x32_bf16 v[42:45], v[158:161], v[202:205], v[42:45]
	v_mfma_f32_16x16x32_bf16 v[22:25], v[144:147], v[202:205], v[22:25]
	v_mfma_f32_16x16x32_bf16 v[30:33], v[144:147], v[210:213], v[30:33]
	v_mfma_f32_16x16x32_bf16 v[18:21], v[158:161], v[210:213], v[18:21]
	v_mfma_f32_16x16x32_bf16 v[2:5], v[158:161], v[218:221], v[2:5]
	v_mfma_f32_16x16x32_bf16 v[10:13], v[144:147], v[218:221], v[10:13]
	v_mfma_f32_16x16x32_bf16 v[50:53], v[154:157], v[198:201], v[50:53]
	v_mfma_f32_16x16x32_bf16 v[38:41], v[162:165], v[198:201], v[38:41]
	v_mfma_f32_16x16x32_bf16 v[42:45], v[162:165], v[206:209], v[42:45]
	v_mfma_f32_16x16x32_bf16 v[22:25], v[154:157], v[206:209], v[22:25]
	v_mfma_f32_16x16x32_bf16 v[30:33], v[154:157], v[214:217], v[30:33]
	v_mfma_f32_16x16x32_bf16 v[18:21], v[162:165], v[214:217], v[18:21]
	v_mfma_f32_16x16x32_bf16 v[2:5], v[162:165], v[238:241], v[2:5]
	v_mfma_f32_16x16x32_bf16 v[10:13], v[154:157], v[238:241], v[10:13]
	v_mfma_f32_16x16x32_bf16 v[46:49], v[166:169], v[194:197], v[46:49]
	v_mfma_f32_16x16x32_bf16 v[58:61], v[174:177], v[194:197], v[58:61]
	v_mfma_f32_16x16x32_bf16 v[66:69], v[174:177], v[202:205], v[66:69]
	v_mfma_f32_16x16x32_bf16 v[62:65], v[166:169], v[202:205], v[62:65]
	v_mfma_f32_16x16x32_bf16 v[26:29], v[166:169], v[210:213], v[26:29]
	v_mfma_f32_16x16x32_bf16 v[34:37], v[174:177], v[210:213], v[34:37]
	v_mfma_f32_16x16x32_bf16 v[14:17], v[174:177], v[218:221], v[14:17]
	v_mfma_f32_16x16x32_bf16 v[6:9], v[166:169], v[218:221], v[6:9]
	v_mfma_f32_16x16x32_bf16 v[46:49], v[170:173], v[198:201], v[46:49]
	v_mfma_f32_16x16x32_bf16 v[58:61], v[190:193], v[198:201], v[58:61]
	v_mfma_f32_16x16x32_bf16 v[66:69], v[190:193], v[206:209], v[66:69]
	v_mfma_f32_16x16x32_bf16 v[62:65], v[170:173], v[206:209], v[62:65]
	v_mfma_f32_16x16x32_bf16 v[26:29], v[170:173], v[214:217], v[26:29]
	v_mfma_f32_16x16x32_bf16 v[34:37], v[190:193], v[214:217], v[34:37]
	v_mfma_f32_16x16x32_bf16 v[14:17], v[190:193], v[238:241], v[14:17]
	v_mfma_f32_16x16x32_bf16 v[6:9], v[170:173], v[238:241], v[6:9]
	s_barrier
	s_setprio 0
	s_add_i32 s68, 0, 0x18000
	s_add_i32 s69, 0, 0x1c000
	v_add_u32_e32 v162, s68, v152
	v_add_u32_e32 v190, s69, v152
	ds_read_b128 v[144:147], v162
	ds_read_b128 v[158:161], v162 offset:2048
	v_xor_b32_e32 v162, 64, v162
	ds_read_b128 v[154:157], v162
	ds_read_b128 v[162:165], v162 offset:2048
	ds_read_b128 v[166:169], v190
	ds_read_b128 v[174:177], v190 offset:2048
	v_xor_b32_e32 v190, 64, v190
	ds_read_b128 v[170:173], v190
	ds_read_b128 v[190:193], v190 offset:2048
	s_add_u32 s50, s50, 0x80000
	s_addc_u32 s51, s51, 0
	s_mov_b32 m0, s58
	v_lshl_add_u64 v[246:247], s[50:51], 0, v[132:133]
	ds_read_b128 v[194:197], v153 offset:32768
	ds_read_b128 v[202:205], v153 offset:34816
	ds_read_b128 v[210:213], v153 offset:36864
	ds_read_b128 v[218:221], v153 offset:38912
	v_xor_b32_e32 v238, 64, v153
	ds_read_b128 v[198:201], v238 offset:32768
	ds_read_b128 v[206:209], v238 offset:34816
	ds_read_b128 v[214:217], v238 offset:36864
	ds_read_b128 v[238:241], v238 offset:38912
	global_load_lds_dwordx4 v[246:247], off
	v_lshl_add_u64 v[246:247], s[50:51], 0, v[136:137]
	s_mov_b32 m0, s59
	s_nop 0
	global_load_lds_dwordx4 v[246:247], off
	s_waitcnt vmcnt(8)
	s_waitcnt lgkmcnt(0)
	s_setprio 1
	s_barrier
	v_mfma_f32_16x16x32_bf16 v[126:129], v[144:147], v[194:197], v[126:129]
	v_mfma_f32_16x16x32_bf16 v[114:117], v[158:161], v[194:197], v[114:117]
	v_mfma_f32_16x16x32_bf16 v[98:101], v[158:161], v[202:205], v[98:101]
	v_mfma_f32_16x16x32_bf16 v[106:109], v[144:147], v[202:205], v[106:109]
	v_mfma_f32_16x16x32_bf16 v[90:93], v[144:147], v[210:213], v[90:93]
	v_mfma_f32_16x16x32_bf16 v[82:85], v[158:161], v[210:213], v[82:85]
	v_mfma_f32_16x16x32_bf16 v[54:57], v[158:161], v[218:221], v[54:57]
	v_mfma_f32_16x16x32_bf16 v[74:77], v[144:147], v[218:221], v[74:77]
	v_mfma_f32_16x16x32_bf16 v[126:129], v[154:157], v[198:201], v[126:129]
	v_mfma_f32_16x16x32_bf16 v[114:117], v[162:165], v[198:201], v[114:117]
	v_mfma_f32_16x16x32_bf16 v[98:101], v[162:165], v[206:209], v[98:101]
	v_mfma_f32_16x16x32_bf16 v[106:109], v[154:157], v[206:209], v[106:109]
	v_mfma_f32_16x16x32_bf16 v[90:93], v[154:157], v[214:217], v[90:93]
	v_mfma_f32_16x16x32_bf16 v[82:85], v[162:165], v[214:217], v[82:85]
	v_mfma_f32_16x16x32_bf16 v[54:57], v[162:165], v[238:241], v[54:57]
	v_mfma_f32_16x16x32_bf16 v[74:77], v[154:157], v[238:241], v[74:77]
	v_mfma_f32_16x16x32_bf16 v[118:121], v[166:169], v[194:197], v[118:121]
	v_mfma_f32_16x16x32_bf16 v[122:125], v[174:177], v[194:197], v[122:125]
	v_mfma_f32_16x16x32_bf16 v[110:113], v[174:177], v[202:205], v[110:113]
	v_mfma_f32_16x16x32_bf16 v[102:105], v[166:169], v[202:205], v[102:105]
	v_mfma_f32_16x16x32_bf16 v[86:89], v[166:169], v[210:213], v[86:89]
	v_mfma_f32_16x16x32_bf16 v[94:97], v[174:177], v[210:213], v[94:97]
	v_mfma_f32_16x16x32_bf16 v[78:81], v[174:177], v[218:221], v[78:81]
	v_mfma_f32_16x16x32_bf16 v[70:73], v[166:169], v[218:221], v[70:73]
	v_mfma_f32_16x16x32_bf16 v[118:121], v[170:173], v[198:201], v[118:121]
	v_mfma_f32_16x16x32_bf16 v[122:125], v[190:193], v[198:201], v[122:125]
	v_mfma_f32_16x16x32_bf16 v[110:113], v[190:193], v[206:209], v[110:113]
	v_mfma_f32_16x16x32_bf16 v[102:105], v[170:173], v[206:209], v[102:105]
	v_mfma_f32_16x16x32_bf16 v[86:89], v[170:173], v[214:217], v[86:89]
	v_mfma_f32_16x16x32_bf16 v[94:97], v[190:193], v[214:217], v[94:97]
	v_mfma_f32_16x16x32_bf16 v[78:81], v[190:193], v[238:241], v[78:81]
	v_mfma_f32_16x16x32_bf16 v[70:73], v[170:173], v[238:241], v[70:73]
	s_barrier
	s_setprio 0
	s_add_i32 s50, s68, s8
	v_lshl_add_u64 v[178:179], v[178:179], 0, s[16:17]
	s_mov_b32 m0, s50
	ds_read_b128 v[194:197], v153 offset:49152
	ds_read_b128 v[202:205], v153 offset:51200
	ds_read_b128 v[210:213], v153 offset:53248
	ds_read_b128 v[218:221], v153 offset:55296
	v_xor_b32_e32 v238, 64, v153
	ds_read_b128 v[198:201], v238 offset:49152
	ds_read_b128 v[206:209], v238 offset:51200
	ds_read_b128 v[214:217], v238 offset:53248
	ds_read_b128 v[238:241], v238 offset:55296
	global_load_lds_dwordx4 v[178:179], off
	s_add_i32 m0, s50, 0x2000
	s_add_u32 s46, s46, 0x80080
	v_lshl_add_u64 v[178:179], v[222:223], 0, s[16:17]
	s_addc_u32 s47, s47, 0
	s_add_i32 s50, s69, s8
	global_load_lds_dwordx4 v[178:179], off
	v_lshl_add_u64 v[178:179], s[46:47], 0, v[134:135]
	s_mov_b32 m0, s50
	s_nop 0
	global_load_lds_dwordx4 v[178:179], off
	v_lshl_add_u64 v[178:179], s[46:47], 0, v[138:139]
	s_add_i32 m0, s50, 0x2000
	s_nop 0
	global_load_lds_dwordx4 v[178:179], off
	v_lshl_add_u64 v[178:179], v[242:243], 0, s[16:17]
	s_mov_b32 m0, s60
	s_nop 0
	global_load_lds_dwordx4 v[178:179], off
	v_lshl_add_u64 v[178:179], v[244:245], 0, s[16:17]
	s_mov_b32 m0, s61
	s_nop 0
	global_load_lds_dwordx4 v[178:179], off
	s_waitcnt vmcnt(8)
	s_waitcnt lgkmcnt(0)
	s_setprio 1
	s_barrier
	v_mfma_f32_16x16x32_bf16 v[50:53], v[144:147], v[194:197], v[50:53]
	v_mfma_f32_16x16x32_bf16 v[38:41], v[158:161], v[194:197], v[38:41]
	v_mfma_f32_16x16x32_bf16 v[42:45], v[158:161], v[202:205], v[42:45]
	v_mfma_f32_16x16x32_bf16 v[22:25], v[144:147], v[202:205], v[22:25]
	v_mfma_f32_16x16x32_bf16 v[30:33], v[144:147], v[210:213], v[30:33]
	v_mfma_f32_16x16x32_bf16 v[18:21], v[158:161], v[210:213], v[18:21]
	v_mfma_f32_16x16x32_bf16 v[2:5], v[158:161], v[218:221], v[2:5]
	v_mfma_f32_16x16x32_bf16 v[10:13], v[144:147], v[218:221], v[10:13]
	v_mfma_f32_16x16x32_bf16 v[50:53], v[154:157], v[198:201], v[50:53]
	v_mfma_f32_16x16x32_bf16 v[38:41], v[162:165], v[198:201], v[38:41]
	v_mfma_f32_16x16x32_bf16 v[42:45], v[162:165], v[206:209], v[42:45]
	v_mfma_f32_16x16x32_bf16 v[22:25], v[154:157], v[206:209], v[22:25]
	v_mfma_f32_16x16x32_bf16 v[30:33], v[154:157], v[214:217], v[30:33]
	v_mfma_f32_16x16x32_bf16 v[18:21], v[162:165], v[214:217], v[18:21]
	v_mfma_f32_16x16x32_bf16 v[2:5], v[162:165], v[238:241], v[2:5]
	v_mfma_f32_16x16x32_bf16 v[10:13], v[154:157], v[238:241], v[10:13]
	v_mfma_f32_16x16x32_bf16 v[46:49], v[166:169], v[194:197], v[46:49]
	v_mfma_f32_16x16x32_bf16 v[58:61], v[174:177], v[194:197], v[58:61]
	v_mfma_f32_16x16x32_bf16 v[66:69], v[174:177], v[202:205], v[66:69]
	v_mfma_f32_16x16x32_bf16 v[62:65], v[166:169], v[202:205], v[62:65]
	v_mfma_f32_16x16x32_bf16 v[26:29], v[166:169], v[210:213], v[26:29]
	v_mfma_f32_16x16x32_bf16 v[34:37], v[174:177], v[210:213], v[34:37]
	v_mfma_f32_16x16x32_bf16 v[14:17], v[174:177], v[218:221], v[14:17]
	v_mfma_f32_16x16x32_bf16 v[6:9], v[166:169], v[218:221], v[6:9]
	v_mfma_f32_16x16x32_bf16 v[46:49], v[170:173], v[198:201], v[46:49]
	v_mfma_f32_16x16x32_bf16 v[58:61], v[190:193], v[198:201], v[58:61]
	v_mfma_f32_16x16x32_bf16 v[66:69], v[190:193], v[206:209], v[66:69]
	v_mfma_f32_16x16x32_bf16 v[62:65], v[170:173], v[206:209], v[62:65]
	v_mfma_f32_16x16x32_bf16 v[26:29], v[170:173], v[214:217], v[26:29]
	v_mfma_f32_16x16x32_bf16 v[34:37], v[190:193], v[214:217], v[34:37]
	v_mfma_f32_16x16x32_bf16 v[14:17], v[190:193], v[238:241], v[14:17]
	v_mfma_f32_16x16x32_bf16 v[6:9], v[170:173], v[238:241], v[6:9]
	s_barrier
	s_setprio 0
	s_add_i32 s67, s67, 2
	s_add_u32 s48, s48, 0x100
	s_addc_u32 s49, s49, 0
	s_add_u32 s64, s64, 0x100
	s_addc_u32 s66, s66, 0
	s_cmp_gt_u32 s67, 29
	s_cbranch_scc0 .LBB0_1583
	s_and_b64 vcc, exec, s[28:29]
	s_cbranch_vccz .LBB0_1586
	s_barrier

.LBB0_1672:
	s_waitcnt lgkmcnt(0)
	v_readlane_b32 s15, v255, 43
	s_lshl_b32 s6, s15, 6
	s_mov_b32 s7, s13
	v_writelane_b32 v255, s6, 53
	s_mul_i32 s12, s15, 0x4200
	s_andn2_b64 vcc, exec, s[2:3]
	v_writelane_b32 v255, s7, 54
	s_cbranch_vccnz .LBB0_1753
	s_waitcnt lgkmcnt(0)
	v_ashrrev_i32_e32 v3, 31, v16
	v_lshrrev_b32_e32 v3, 26, v3
	v_add_u32_e32 v3, v16, v3
	v_ashrrev_i32_e32 v10, 6, v3
	v_bfe_i32 v3, v16, 27, 1
	v_lshlrev_b32_e32 v2, 4, v16
	v_lshrrev_b32_e32 v3, 22, v3
	v_add_u32_e32 v3, v2, v3
	s_load_dwordx4 s[36:39], s[0:1], s8 offset:0x110
	v_and_b32_e32 v3, 0xfffffc00, v3
	v_sub_u32_e32 v3, v2, v3
	v_lshrrev_b32_e32 v4, 4, v3
	v_bitop3_b32 v3, v4, v3, 32 bitop3:0x6c
	v_ashrrev_i32_e32 v5, 31, v3
	s_waitcnt lgkmcnt(0)
	s_add_u32 s29, s38, 0x1de00000
	v_lshrrev_b32_e32 v5, 26, v5
	s_mul_i32 s3, s15, 0x2b00000
	s_addc_u32 s64, s39, 0
	v_add_u32_e32 v5, v3, v5
	s_mul_hi_u32 s2, s15, 0x2b00000
	s_add_u32 s3, s38, s3
	v_lshlrev_b32_e32 v4, 3, v10
	v_ashrrev_i32_e32 v11, 6, v5
	v_and_b32_e32 v5, 0xc0, v5
	s_addc_u32 s2, s39, s2
	v_and_b32_e32 v4, -16, v4
	v_sub_u32_e32 v3, v3, v5
	s_add_u32 s76, s3, 0x5600000
	v_add_u32_e32 v4, v11, v4
	v_ashrrev_i16_sdwa v3, v224, sext(v3) dst_sel:DWORD dst_unused:UNUSED_PAD src0_sel:DWORD src1_sel:BYTE_0
	s_addc_u32 s22, s2, 0
	v_lshlrev_b32_e32 v6, 5, v10
	v_bfe_i32 v12, v3, 0, 16
	v_lshlrev_b32_e32 v3, 1, v4
	v_lshrrev_b32_e32 v5, 2, v4
	v_and_b32_e32 v7, 3, v11
	s_mov_b32 s2, 0xfffe0
	v_and_b32_e32 v6, 32, v6
	v_and_b32_e32 v3, 24, v3
	v_and_b32_e32 v5, 4, v5
	v_and_or_b32 v7, v4, s2, v7
	v_or3_b32 v3, v7, v5, v3
	v_add_lshl_u32 v5, v6, v12, 1
	v_add_u32_e32 v2, 0x2000, v2
	v_lshl_add_u32 v180, v3, 12, v5
	v_ashrrev_i32_e32 v3, 31, v2
	v_lshrrev_b32_e32 v3, 22, v3
	v_add_u32_e32 v3, v2, v3
	v_ashrrev_i32_e32 v13, 10, v3
	v_mul_i32_i24_e32 v3, 0x400, v13
	v_sub_u32_e32 v2, v2, v3
	v_lshrrev_b32_e32 v3, 4, v2
	v_bitop3_b32 v2, v3, v2, 32 bitop3:0x6c
	v_lshl_add_u32 v192, v4, 12, v5
	v_ashrrev_i32_e32 v4, 31, v2
	v_lshrrev_b32_e32 v4, 26, v4
	v_lshlrev_b32_e32 v3, 3, v13
	v_add_u32_e32 v4, v2, v4
	v_and_b32_e32 v3, -16, v3
	v_ashrrev_i32_e32 v14, 6, v4
	v_add_u32_e32 v3, v14, v3
	v_and_b32_e32 v4, 0xc0, v4
	v_and_b32_e32 v6, 3, v14
	s_ashr_i32 s14, s10, 6
	s_ashr_i32 s45, s44, 31
	s_ashr_i32 s27, s26, 31
	v_sub_u32_e32 v2, v2, v4
	v_and_or_b32 v6, v3, s2, v6
	s_ashr_i32 s11, s10, 8
	s_lshl_b32 s23, s14, 10
	s_lshl_b64 s[2:3], s[44:45], 20
	s_lshl_b64 s[6:7], s[26:27], 20
	v_ashrrev_i16_sdwa v2, v224, sext(v2) dst_sel:DWORD dst_unused:UNUSED_PAD src0_sel:DWORD src1_sel:BYTE_0
	s_add_u32 s46, s76, s6
	v_lshlrev_b32_e32 v5, 5, v13
	v_bfe_i32 v15, v2, 0, 16
	v_lshlrev_b32_e32 v2, 1, v3
	v_lshrrev_b32_e32 v4, 2, v3
	s_addc_u32 s47, s22, s7
	s_add_i32 s6, s23, 0
	v_and_b32_e32 v5, 32, v5
	v_and_b32_e32 v2, 24, v2
	v_and_b32_e32 v4, 4, v4
	s_add_i32 m0, s6, 0x10000
	v_or3_b32 v2, v6, v4, v2
	v_add_lshl_u32 v4, v5, v15, 1
	v_and_b32_e32 v114, 63, v0
	v_lshrrev_b32_e32 v115, 3, v114
	v_and_b32_e32 v114, 7, v114
	v_xor_b32_e32 v114, v114, v115
	v_lshlrev_b32_e32 v114, 4, v114
	v_lshrrev_b32_e32 v116, 6, v0
	v_lshl_add_u32 v115, v116, 3, v115
	v_mov_b32_e32 v116, 0x1000
	v_mad_u32_u24 v192, v115, v116, v114
	v_add_u32_e32 v194, 0x40000, v192
	v_and_b32_e32 v117, 15, v115
	v_lshrrev_b32_e32 v116, 2, v117
	v_and_b32_e32 v117, 3, v117
	v_lshl_add_u32 v117, v116, 3, v117
	v_bfe_u32 v116, v115, 4, 1
	v_lshl_add_u32 v117, v116, 2, v117
	v_and_b32_e32 v116, 0x60, v115
	v_or_b32_e32 v117, v116, v117
	v_mov_b32_e32 v116, 0x1000
	v_mad_u32_u24 v180, v117, v116, v114
	v_add_u32_e32 v196, 0x40000, v180
	global_load_lds_dwordx4 v180, s[46:47]
	s_add_i32 m0, s6, 0x12000
	s_nop 0
	s_add_u32 s18, s46, 0x80000
	global_load_lds_dwordx4 v196, s[46:47]
	s_addc_u32 s19, s47, 0
	s_add_i32 m0, s6, 0x14000
	s_nop 0
	global_load_lds_dwordx4 v180, s[18:19]
	s_add_i32 m0, s6, 0x16000
	s_add_u32 s48, s29, s2
	s_addc_u32 s49, s64, s3
	s_add_i32 s9, s6, 0x2000
	global_load_lds_dwordx4 v196, s[18:19]
	s_mov_b32 m0, s6
	s_add_u32 s2, s48, 0x80000
	global_load_lds_dwordx4 v192, s[48:49]
	s_mov_b32 m0, s9
	s_addc_u32 s3, s49, 0
	s_add_i32 s21, s6, 0x4000
	global_load_lds_dwordx4 v194, s[48:49]
	s_mov_b32 m0, s21
	s_add_i32 s7, s6, 0x6000
	global_load_lds_dwordx4 v192, s[2:3]
	s_mov_b32 m0, s7
	v_writelane_b32 v255, s97, 55
	global_load_lds_dwordx4 v194, s[2:3]
	s_load_dwordx2 s[2:3], s[0:1], s8 offset:0x38
	s_load_dwordx4 s[40:43], s[0:1], s8 offset:0xf8
	v_writelane_b32 v255, s96, 56
	v_mov_b32_e32 v197, v181
	v_mov_b32_e32 v193, v181
	v_mov_b32_e32 v195, v181
	s_cmp_eq_u32 s11, 1
	v_writelane_b32 v255, s70, 57
	v_lshl_add_u64 v[8:9], s[46:47], 0, v[180:181]
	v_lshl_add_u64 v[6:7], s[46:47], 0, v[196:197]
	v_lshl_add_u64 v[2:3], s[48:49], 0, v[192:193]
	s_cselect_b64 s[56:57], -1, 0
	s_cmp_lg_u32 s11, 1
	v_lshl_add_u64 v[4:5], s[48:49], 0, v[194:195]
	s_mov_b32 s8, s15
	s_cbranch_scc1 .LBB0_1675
	s_barrier
.LBB0_1675:
	s_lshl_b32 s18, s8, 3
	s_mul_hi_u32 s15, s8, 0x560000
	s_mul_i32 s27, s8, 0x560000
	s_mul_hi_u32 s30, s8, 0x10200
	s_mul_i32 s31, s8, 0x10200
	s_mul_hi_u32 s34, s8, 0x5600
	s_mul_i32 s35, s8, 0x5600
	v_writelane_b32 v255, s18, 44
	s_lshl_b32 s8, s8, 7
	s_lshl_b64 s[18:19], s[12:13], 3
	s_add_u32 s45, s38, s18
	s_addc_u32 s50, s39, s19
	s_add_u32 s58, s38, 0x31900000
	s_addc_u32 s59, s39, 0
	s_waitcnt lgkmcnt(0)
	s_add_u32 s60, s2, s27
	s_addc_u32 s61, s3, s15
	s_add_u32 s27, s40, s31
	s_addc_u32 s40, s41, s30
	s_add_u32 s41, s42, s35
	s_addc_u32 s42, s43, s34
	v_readlane_b32 s2, v255, 53
	s_add_u32 s62, s38, 0x3b000000
	v_readlane_b32 s3, v255, 54
	s_addc_u32 s63, s39, 0
	s_lshl_b64 s[2:3], s[2:3], 2
	s_add_u32 s2, s38, s2
	s_addc_u32 s3, s39, s3
	s_add_u32 s2, s2, 0x8000
	s_addc_u32 s3, s3, 0
	v_writelane_b32 v255, s2, 58
	v_and_b32_e32 v17, 63, v16
	v_and_b32_e32 v191, 15, v16
	v_bfe_u32 v238, v16, 4, 2
	v_and_b32_e32 v18, 48, v16
	v_lshlrev_b32_e32 v16, 2, v16
	v_writelane_b32 v255, s3, 59
	s_lshl_b32 s2, s11, 13
	v_lshl_or_b32 v18, v191, 6, v18
	v_and_b32_e32 v16, 32, v16
	v_bitop3_b32 v19, v18, s2, v16 bitop3:0xde
	s_lshl_b32 s2, s14, 5
	s_and_b32 s35, s2, 0x60
	s_add_i32 m0, s6, 0x18000
	v_lshl_add_u64 v[8:9], v[8:9], 0, s[16:17]
	s_lshl_b32 s34, s11, 6
	s_lshl_b32 s3, s35, 7
	s_waitcnt vmcnt(2)
	s_barrier
	global_load_lds_dwordx4 v[8:9], off
	v_lshl_add_u64 v[6:7], v[6:7], 0, s[16:17]
	s_add_i32 m0, s6, 0x1a000
	s_add_i32 s54, s6, 0x8000
	s_add_i32 s55, s6, 0xa000
	global_load_lds_dwordx4 v[6:7], off
	v_lshl_add_u64 v[2:3], v[2:3], 0, s[16:17]
	s_mov_b32 m0, s54
	s_add_u32 s18, s46, 0x80080
	global_load_lds_dwordx4 v[2:3], off
	v_lshl_add_u64 v[2:3], v[4:5], 0, s[16:17]
	s_mov_b32 m0, s55
	s_addc_u32 s19, s47, 0
	global_load_lds_dwordx4 v[2:3], off
	s_add_i32 m0, s6, 0x1c000
	v_lshl_add_u64 v[2:3], s[18:19], 0, v[180:181]
	global_load_lds_dwordx4 v[2:3], off
	v_lshl_add_u64 v[2:3], s[18:19], 0, v[196:197]
	s_add_i32 m0, s6, 0x1e000
	s_ashr_i32 s18, s10, 7
	global_load_lds_dwordx4 v[2:3], off
	v_bitop3_b32 v239, s3, v18, v16 bitop3:0xf6
	s_lshl_b32 s51, s18, 9
	s_ashr_i32 s3, s2, 31
	s_lshl_b32 s68, s14, 8
	s_cmpk_lt_u32 s10, 0x100
	s_cselect_b64 s[30:31], -1, 0
	s_lshl_b32 s14, s11, 1
	s_add_i32 s14, s14, 0x7ffff2
	s_cmp_gt_i32 s11, 0
	v_writelane_b32 v255, s14, 50
	s_cselect_b64 s[14:15], -1, 0
	s_lshl_b32 s66, s11, 10
	v_writelane_b32 v255, s14, 41
	s_cmpk_gt_u32 s10, 0xff
	s_mul_i32 s43, s18, 0x5600
	v_writelane_b32 v255, s15, 42
	s_cselect_b64 s[14:15], -1, 0
	s_cmp_gt_i32 s11, -1
	s_cselect_b64 s[70:71], -1, 0
	s_ashr_i32 s83, s28, 31
	s_mul_hi_i32 s19, s18, 0x5600
	s_add_u32 s11, s27, s43
	s_addc_u32 s19, s40, s19
	s_cmp_lt_i32 s18, 3
	s_cselect_b32 s18, s19, s42
	s_cselect_b32 s11, s11, s41
	s_lshl_b32 s10, s10, 2
	s_and_b32 s19, s10, 0x100
	s_add_u32 s10, s11, s19
	s_addc_u32 s11, s18, 0
	v_lshlrev_b32_e32 v2, 2, v17
	v_mov_b32_e32 v3, v181
	v_writelane_b32 v255, s70, 15
	v_lshl_add_u64 v[198:199], s[10:11], 0, v[2:3]
	s_add_i32 s10, s51, 0
	v_writelane_b32 v255, s71, 16
	s_add_i32 s70, s10, s19
	s_add_i32 s70, s70, 0x21000
	s_lshl_b64 s[2:3], s[2:3], 3
	s_add_u32 s2, s45, s2
	s_addc_u32 s3, s50, s3
	v_lshl_add_u64 v[2:3], s[2:3], 0, v[2:3]
	s_mov_b64 s[2:3], 0x20800
	v_lshl_add_u64 v[200:201], v[2:3], 0, s[2:3]
	s_add_u32 s74, s38, 0x3b300000
	v_lshlrev_b32_e32 v2, 15, v10
	s_addc_u32 s75, s39, 0
	s_add_i32 s2, s66, 0
	v_and_b32_e32 v2, 0xffff0000, v2
	s_add_i32 s2, s2, 0x20000
	v_lshl_add_u32 v2, v11, 12, v2
	v_and_b32_e32 v3, 1, v10
	s_add_u32 s96, s36, 0x5160000
	v_lshl_or_b32 v2, v3, 6, v2
	s_addc_u32 s97, s37, 0
	v_mov_b32_e32 v202, v192
	v_lshlrev_b32_e32 v2, 15, v13
	s_add_u32 s66, s36, 0x5e0c000
	v_and_b32_e32 v2, 0xffff0000, v2
	s_waitcnt vmcnt(6)
	v_writelane_b32 v255, s2, 46
	s_addc_u32 s67, s37, 0
	v_lshl_add_u32 v2, v14, 12, v2
	v_and_b32_e32 v3, 1, v13
	s_xor_b64 s[2:3], s[14:15], -1
	v_lshl_or_b32 v2, v3, 6, v2
	s_add_i32 s71, s68, 0
	v_writelane_b32 v255, s2, 48
	s_mov_b32 s82, 0
	v_mov_b32_e32 v203, v181
	v_mov_b32_e32 v204, v194
	v_mov_b32_e32 v205, v181
	s_add_i32 s71, s71, 0x21800
	v_add_u32_e32 v240, 0, v19
	v_writelane_b32 v255, s3, 49
	v_and_b32_e32 v114, 7, v0
	v_bfe_u32 v115, v0, 4, 2
	v_xor_b32_e32 v115, v115, v114
	v_lshlrev_b32_e32 v115, 4, v115
	v_lshl_add_u32 v115, v114, 7, v115
	v_bfe_u32 v114, v0, 3, 1
	v_lshl_add_u32 v115, v114, 10, v115
	v_lshrrev_b32_e32 v114, 8, v0
	v_lshl_add_u32 v240, v114, 13, v115
	v_bfe_u32 v114, v0, 6, 2
	v_lshl_add_u32 v239, v114, 12, v115
	s_barrier
	s_branch .LBB0_1678

.LBB0_1685:
	s_add_u32 s42, s40, 0xfff80080
	s_addc_u32 s43, s41, -1
	s_and_b64 s[26:27], s[26:27], exec
	s_cselect_b32 s43, s19, s43
	s_cselect_b32 s42, s45, s42
	s_cselect_b32 s27, s50, s39
	s_cselect_b32 s26, s51, s37
	s_add_i32 s47, 0, 0x10000
	s_add_i32 s69, 0, 0x14000
	v_add_u32_e32 v146, s47, v239
	v_add_u32_e32 v162, s69, v239
	ds_read_b128 v[114:117], v146
	ds_read_b128 v[122:125], v146 offset:2048
	v_xor_b32_e32 v146, 64, v146
	ds_read_b128 v[118:121], v146
	ds_read_b128 v[146:149], v146 offset:2048
	ds_read_b128 v[150:153], v162
	ds_read_b128 v[158:161], v162 offset:2048
	v_xor_b32_e32 v162, 64, v162
	ds_read_b128 v[154:157], v162
	ds_read_b128 v[162:165], v162 offset:2048
	v_lshl_add_u64 v[178:179], s[40:41], 0, v[202:203]
	s_add_i32 m0, s6, 0xc000
	ds_read_b128 v[166:169], v240
	ds_read_b128 v[174:177], v240 offset:2048
	ds_read_b128 v[210:213], v240 offset:4096
	ds_read_b128 v[218:221], v240 offset:6144
	v_xor_b32_e32 v242, 64, v240
	ds_read_b128 v[170:173], v242
	ds_read_b128 v[206:209], v242 offset:2048
	ds_read_b128 v[214:217], v242 offset:4096
	ds_read_b128 v[242:245], v242 offset:6144
	global_load_lds_dwordx4 v[178:179], off
	v_lshl_add_u64 v[178:179], s[40:41], 0, v[204:205]
	s_add_i32 m0, s6, 0xe000
	s_nop 0
	global_load_lds_dwordx4 v[178:179], off
	s_waitcnt vmcnt(8)
	s_waitcnt lgkmcnt(0)
	s_setprio 1
	s_barrier
	v_mfma_f32_16x16x32_bf16 v[142:145], v[114:117], v[166:169], v[142:145]
	v_mfma_f32_16x16x32_bf16 v[62:65], v[122:125], v[166:169], v[62:65]
	v_mfma_f32_16x16x32_bf16 v[54:57], v[122:125], v[174:177], v[54:57]
	v_mfma_f32_16x16x32_bf16 v[134:137], v[114:117], v[174:177], v[134:137]
	v_mfma_f32_16x16x32_bf16 v[126:129], v[114:117], v[210:213], v[126:129]
	v_mfma_f32_16x16x32_bf16 v[46:49], v[122:125], v[210:213], v[46:49]
	v_mfma_f32_16x16x32_bf16 v[38:41], v[122:125], v[218:221], v[38:41]
	v_mfma_f32_16x16x32_bf16 v[102:105], v[114:117], v[218:221], v[102:105]
	v_mfma_f32_16x16x32_bf16 v[142:145], v[118:121], v[170:173], v[142:145]
	v_mfma_f32_16x16x32_bf16 v[62:65], v[146:149], v[170:173], v[62:65]
	v_mfma_f32_16x16x32_bf16 v[54:57], v[146:149], v[206:209], v[54:57]
	v_mfma_f32_16x16x32_bf16 v[134:137], v[118:121], v[206:209], v[134:137]
	v_mfma_f32_16x16x32_bf16 v[126:129], v[118:121], v[214:217], v[126:129]
	v_mfma_f32_16x16x32_bf16 v[46:49], v[146:149], v[214:217], v[46:49]
	v_mfma_f32_16x16x32_bf16 v[38:41], v[146:149], v[242:245], v[38:41]
	v_mfma_f32_16x16x32_bf16 v[102:105], v[118:121], v[242:245], v[102:105]
	v_mfma_f32_16x16x32_bf16 v[138:141], v[150:153], v[166:169], v[138:141]
	v_mfma_f32_16x16x32_bf16 v[58:61], v[158:161], v[166:169], v[58:61]
	v_mfma_f32_16x16x32_bf16 v[50:53], v[158:161], v[174:177], v[50:53]
	v_mfma_f32_16x16x32_bf16 v[130:133], v[150:153], v[174:177], v[130:133]
	v_mfma_f32_16x16x32_bf16 v[106:109], v[150:153], v[210:213], v[106:109]
	v_mfma_f32_16x16x32_bf16 v[42:45], v[158:161], v[210:213], v[42:45]
	v_mfma_f32_16x16x32_bf16 v[34:37], v[158:161], v[218:221], v[34:37]
	v_mfma_f32_16x16x32_bf16 v[98:101], v[150:153], v[218:221], v[98:101]
	v_mfma_f32_16x16x32_bf16 v[138:141], v[154:157], v[170:173], v[138:141]
	v_mfma_f32_16x16x32_bf16 v[58:61], v[162:165], v[170:173], v[58:61]
	v_mfma_f32_16x16x32_bf16 v[50:53], v[162:165], v[206:209], v[50:53]
	v_mfma_f32_16x16x32_bf16 v[130:133], v[154:157], v[206:209], v[130:133]
	v_mfma_f32_16x16x32_bf16 v[106:109], v[154:157], v[214:217], v[106:109]
	v_mfma_f32_16x16x32_bf16 v[42:45], v[162:165], v[214:217], v[42:45]
	v_mfma_f32_16x16x32_bf16 v[34:37], v[162:165], v[242:245], v[34:37]
	v_mfma_f32_16x16x32_bf16 v[98:101], v[154:157], v[242:245], v[98:101]
	s_barrier
	s_setprio 0
	s_add_i32 s47, s47, s23
	v_lshl_add_u64 v[178:179], s[26:27], 0, v[180:181]
	s_mov_b32 m0, s47
	ds_read_b128 v[166:169], v240 offset:16384
	ds_read_b128 v[174:177], v240 offset:18432
	ds_read_b128 v[210:213], v240 offset:20480
	ds_read_b128 v[218:221], v240 offset:22528
	v_xor_b32_e32 v242, 64, v240
	ds_read_b128 v[170:173], v242 offset:16384
	ds_read_b128 v[206:209], v242 offset:18432
	ds_read_b128 v[214:217], v242 offset:20480
	ds_read_b128 v[242:245], v242 offset:22528
	global_load_lds_dwordx4 v[178:179], off
	s_add_i32 m0, s47, 0x2000
	s_add_u32 s48, s26, 0x80000
	v_lshl_add_u64 v[222:223], s[26:27], 0, v[196:197]
	s_addc_u32 s49, s27, 0
	s_add_i32 s47, s69, s23
	global_load_lds_dwordx4 v[222:223], off
	v_lshl_add_u64 v[246:247], s[48:49], 0, v[180:181]
	s_mov_b32 m0, s47
	v_lshl_add_u64 v[248:249], s[42:43], 0, v[194:195]
	global_load_lds_dwordx4 v[246:247], off
	v_lshl_add_u64 v[246:247], s[48:49], 0, v[196:197]
	s_add_i32 m0, s47, 0x2000
	s_nop 0
	global_load_lds_dwordx4 v[246:247], off
	v_lshl_add_u64 v[246:247], s[42:43], 0, v[192:193]
	s_mov_b32 m0, s6
	s_nop 0
	global_load_lds_dwordx4 v[246:247], off
	s_mov_b32 m0, s9
	s_nop 0
	global_load_lds_dwordx4 v[248:249], off
	s_waitcnt vmcnt(8)
	s_waitcnt lgkmcnt(0)
	s_setprio 1
	s_barrier
	v_mfma_f32_16x16x32_bf16 v[94:97], v[114:117], v[166:169], v[94:97]
	v_mfma_f32_16x16x32_bf16 v[30:33], v[122:125], v[166:169], v[30:33]
	v_mfma_f32_16x16x32_bf16 v[22:25], v[122:125], v[174:177], v[22:25]
	v_mfma_f32_16x16x32_bf16 v[86:89], v[114:117], v[174:177], v[86:89]
	v_mfma_f32_16x16x32_bf16 v[78:81], v[114:117], v[210:213], v[78:81]
	v_mfma_f32_16x16x32_bf16 v[14:17], v[122:125], v[210:213], v[14:17]
	v_mfma_f32_16x16x32_bf16 v[6:9], v[122:125], v[218:221], v[6:9]
	v_mfma_f32_16x16x32_bf16 v[70:73], v[114:117], v[218:221], v[70:73]
	v_mfma_f32_16x16x32_bf16 v[94:97], v[118:121], v[170:173], v[94:97]
	v_mfma_f32_16x16x32_bf16 v[30:33], v[146:149], v[170:173], v[30:33]
	v_mfma_f32_16x16x32_bf16 v[22:25], v[146:149], v[206:209], v[22:25]
	v_mfma_f32_16x16x32_bf16 v[86:89], v[118:121], v[206:209], v[86:89]
	v_mfma_f32_16x16x32_bf16 v[78:81], v[118:121], v[214:217], v[78:81]
	v_mfma_f32_16x16x32_bf16 v[14:17], v[146:149], v[214:217], v[14:17]
	v_mfma_f32_16x16x32_bf16 v[6:9], v[146:149], v[242:245], v[6:9]
	v_mfma_f32_16x16x32_bf16 v[70:73], v[118:121], v[242:245], v[70:73]
	v_mfma_f32_16x16x32_bf16 v[90:93], v[150:153], v[166:169], v[90:93]
	v_mfma_f32_16x16x32_bf16 v[26:29], v[158:161], v[166:169], v[26:29]
	v_mfma_f32_16x16x32_bf16 v[18:21], v[158:161], v[174:177], v[18:21]
	v_mfma_f32_16x16x32_bf16 v[82:85], v[150:153], v[174:177], v[82:85]
	v_mfma_f32_16x16x32_bf16 v[74:77], v[150:153], v[210:213], v[74:77]
	v_mfma_f32_16x16x32_bf16 v[10:13], v[158:161], v[210:213], v[10:13]
	v_mfma_f32_16x16x32_bf16 v[2:5], v[158:161], v[218:221], v[2:5]
	v_mfma_f32_16x16x32_bf16 v[66:69], v[150:153], v[218:221], v[66:69]
	v_mfma_f32_16x16x32_bf16 v[90:93], v[154:157], v[170:173], v[90:93]
	v_mfma_f32_16x16x32_bf16 v[26:29], v[162:165], v[170:173], v[26:29]
	v_mfma_f32_16x16x32_bf16 v[18:21], v[162:165], v[206:209], v[18:21]
	v_mfma_f32_16x16x32_bf16 v[82:85], v[154:157], v[206:209], v[82:85]
	v_mfma_f32_16x16x32_bf16 v[74:77], v[154:157], v[214:217], v[74:77]
	v_mfma_f32_16x16x32_bf16 v[10:13], v[162:165], v[214:217], v[10:13]
	v_mfma_f32_16x16x32_bf16 v[2:5], v[162:165], v[242:245], v[2:5]
	v_mfma_f32_16x16x32_bf16 v[66:69], v[154:157], v[242:245], v[66:69]
	s_barrier
	s_setprio 0
	s_add_i32 s47, 0, 0x18000
	s_add_i32 s48, 0, 0x1c000
	v_add_u32_e32 v146, s47, v239
	v_add_u32_e32 v162, s48, v239
	ds_read_b128 v[114:117], v146
	ds_read_b128 v[122:125], v146 offset:2048
	v_xor_b32_e32 v146, 64, v146
	ds_read_b128 v[118:121], v146
	ds_read_b128 v[146:149], v146 offset:2048
	ds_read_b128 v[150:153], v162
	ds_read_b128 v[158:161], v162 offset:2048
	v_xor_b32_e32 v162, 64, v162
	ds_read_b128 v[154:157], v162
	ds_read_b128 v[162:165], v162 offset:2048
	s_add_u32 s42, s42, 0x80000
	s_addc_u32 s43, s43, 0
	s_mov_b32 m0, s21
	v_lshl_add_u64 v[250:251], s[42:43], 0, v[192:193]
	ds_read_b128 v[166:169], v240 offset:32768
	ds_read_b128 v[174:177], v240 offset:34816
	ds_read_b128 v[210:213], v240 offset:36864
	ds_read_b128 v[218:221], v240 offset:38912
	v_xor_b32_e32 v242, 64, v240
	ds_read_b128 v[170:173], v242 offset:32768
	ds_read_b128 v[206:209], v242 offset:34816
	ds_read_b128 v[214:217], v242 offset:36864
	ds_read_b128 v[242:245], v242 offset:38912
	global_load_lds_dwordx4 v[250:251], off
	v_lshl_add_u64 v[250:251], s[42:43], 0, v[194:195]
	s_mov_b32 m0, s7
	s_nop 0
	global_load_lds_dwordx4 v[250:251], off
	s_waitcnt vmcnt(8)
	s_waitcnt lgkmcnt(0)
	s_setprio 1
	s_barrier
	v_mfma_f32_16x16x32_bf16 v[142:145], v[114:117], v[166:169], v[142:145]
	v_mfma_f32_16x16x32_bf16 v[62:65], v[122:125], v[166:169], v[62:65]
	v_mfma_f32_16x16x32_bf16 v[54:57], v[122:125], v[174:177], v[54:57]
	v_mfma_f32_16x16x32_bf16 v[134:137], v[114:117], v[174:177], v[134:137]
	v_mfma_f32_16x16x32_bf16 v[126:129], v[114:117], v[210:213], v[126:129]
	v_mfma_f32_16x16x32_bf16 v[46:49], v[122:125], v[210:213], v[46:49]
	v_mfma_f32_16x16x32_bf16 v[38:41], v[122:125], v[218:221], v[38:41]
	v_mfma_f32_16x16x32_bf16 v[102:105], v[114:117], v[218:221], v[102:105]
	v_mfma_f32_16x16x32_bf16 v[142:145], v[118:121], v[170:173], v[142:145]
	v_mfma_f32_16x16x32_bf16 v[62:65], v[146:149], v[170:173], v[62:65]
	v_mfma_f32_16x16x32_bf16 v[54:57], v[146:149], v[206:209], v[54:57]
	v_mfma_f32_16x16x32_bf16 v[134:137], v[118:121], v[206:209], v[134:137]
	v_mfma_f32_16x16x32_bf16 v[126:129], v[118:121], v[214:217], v[126:129]
	v_mfma_f32_16x16x32_bf16 v[46:49], v[146:149], v[214:217], v[46:49]
	v_mfma_f32_16x16x32_bf16 v[38:41], v[146:149], v[242:245], v[38:41]
	v_mfma_f32_16x16x32_bf16 v[102:105], v[118:121], v[242:245], v[102:105]
	v_mfma_f32_16x16x32_bf16 v[138:141], v[150:153], v[166:169], v[138:141]
	v_mfma_f32_16x16x32_bf16 v[58:61], v[158:161], v[166:169], v[58:61]
	v_mfma_f32_16x16x32_bf16 v[50:53], v[158:161], v[174:177], v[50:53]
	v_mfma_f32_16x16x32_bf16 v[130:133], v[150:153], v[174:177], v[130:133]
	v_mfma_f32_16x16x32_bf16 v[106:109], v[150:153], v[210:213], v[106:109]
	v_mfma_f32_16x16x32_bf16 v[42:45], v[158:161], v[210:213], v[42:45]
	v_mfma_f32_16x16x32_bf16 v[34:37], v[158:161], v[218:221], v[34:37]
	v_mfma_f32_16x16x32_bf16 v[98:101], v[150:153], v[218:221], v[98:101]
	v_mfma_f32_16x16x32_bf16 v[138:141], v[154:157], v[170:173], v[138:141]
	v_mfma_f32_16x16x32_bf16 v[58:61], v[162:165], v[170:173], v[58:61]
	v_mfma_f32_16x16x32_bf16 v[50:53], v[162:165], v[206:209], v[50:53]
	v_mfma_f32_16x16x32_bf16 v[130:133], v[154:157], v[206:209], v[130:133]
	v_mfma_f32_16x16x32_bf16 v[106:109], v[154:157], v[214:217], v[106:109]
	v_mfma_f32_16x16x32_bf16 v[42:45], v[162:165], v[214:217], v[42:45]
	v_mfma_f32_16x16x32_bf16 v[34:37], v[162:165], v[242:245], v[34:37]
	v_mfma_f32_16x16x32_bf16 v[98:101], v[154:157], v[242:245], v[98:101]
	s_barrier
	s_setprio 0
	s_add_i32 s42, s47, s23
	v_lshl_add_u64 v[178:179], v[178:179], 0, s[16:17]
	s_mov_b32 m0, s42
	ds_read_b128 v[166:169], v240 offset:49152
	ds_read_b128 v[174:177], v240 offset:51200
	ds_read_b128 v[210:213], v240 offset:53248
	ds_read_b128 v[218:221], v240 offset:55296
	v_xor_b32_e32 v242, 64, v240
	ds_read_b128 v[170:173], v242 offset:49152
	ds_read_b128 v[206:209], v242 offset:51200
	ds_read_b128 v[214:217], v242 offset:53248
	ds_read_b128 v[242:245], v242 offset:55296
	global_load_lds_dwordx4 v[178:179], off
	s_add_i32 m0, s42, 0x2000
	s_add_u32 s26, s26, 0x80080
	v_lshl_add_u64 v[178:179], v[222:223], 0, s[16:17]
	s_addc_u32 s27, s27, 0
	s_add_i32 s42, s48, s23
	global_load_lds_dwordx4 v[178:179], off
	v_lshl_add_u64 v[178:179], s[26:27], 0, v[180:181]
	s_mov_b32 m0, s42
	s_nop 0
	global_load_lds_dwordx4 v[178:179], off
	v_lshl_add_u64 v[178:179], s[26:27], 0, v[196:197]
	s_add_i32 m0, s42, 0x2000
	s_nop 0
	global_load_lds_dwordx4 v[178:179], off
	v_lshl_add_u64 v[178:179], v[246:247], 0, s[16:17]
	s_mov_b32 m0, s54
	s_nop 0
	global_load_lds_dwordx4 v[178:179], off
	v_lshl_add_u64 v[178:179], v[248:249], 0, s[16:17]
	s_mov_b32 m0, s55
	s_nop 0
	global_load_lds_dwordx4 v[178:179], off
	s_waitcnt vmcnt(8)
	s_waitcnt lgkmcnt(0)
	s_setprio 1
	s_barrier
	v_mfma_f32_16x16x32_bf16 v[94:97], v[114:117], v[166:169], v[94:97]
	v_mfma_f32_16x16x32_bf16 v[30:33], v[122:125], v[166:169], v[30:33]
	v_mfma_f32_16x16x32_bf16 v[22:25], v[122:125], v[174:177], v[22:25]
	v_mfma_f32_16x16x32_bf16 v[86:89], v[114:117], v[174:177], v[86:89]
	v_mfma_f32_16x16x32_bf16 v[78:81], v[114:117], v[210:213], v[78:81]
	v_mfma_f32_16x16x32_bf16 v[14:17], v[122:125], v[210:213], v[14:17]
	v_mfma_f32_16x16x32_bf16 v[6:9], v[122:125], v[218:221], v[6:9]
	v_mfma_f32_16x16x32_bf16 v[70:73], v[114:117], v[218:221], v[70:73]
	v_mfma_f32_16x16x32_bf16 v[94:97], v[118:121], v[170:173], v[94:97]
	v_mfma_f32_16x16x32_bf16 v[30:33], v[146:149], v[170:173], v[30:33]
	v_mfma_f32_16x16x32_bf16 v[22:25], v[146:149], v[206:209], v[22:25]
	v_mfma_f32_16x16x32_bf16 v[86:89], v[118:121], v[206:209], v[86:89]
	v_mfma_f32_16x16x32_bf16 v[78:81], v[118:121], v[214:217], v[78:81]
	v_mfma_f32_16x16x32_bf16 v[14:17], v[146:149], v[214:217], v[14:17]
	v_mfma_f32_16x16x32_bf16 v[6:9], v[146:149], v[242:245], v[6:9]
	v_mfma_f32_16x16x32_bf16 v[70:73], v[118:121], v[242:245], v[70:73]
	v_mfma_f32_16x16x32_bf16 v[90:93], v[150:153], v[166:169], v[90:93]
	v_mfma_f32_16x16x32_bf16 v[26:29], v[158:161], v[166:169], v[26:29]
	v_mfma_f32_16x16x32_bf16 v[18:21], v[158:161], v[174:177], v[18:21]
	v_mfma_f32_16x16x32_bf16 v[82:85], v[150:153], v[174:177], v[82:85]
	v_mfma_f32_16x16x32_bf16 v[74:77], v[150:153], v[210:213], v[74:77]
	v_mfma_f32_16x16x32_bf16 v[10:13], v[158:161], v[210:213], v[10:13]
	v_mfma_f32_16x16x32_bf16 v[2:5], v[158:161], v[218:221], v[2:5]
	v_mfma_f32_16x16x32_bf16 v[66:69], v[150:153], v[218:221], v[66:69]
	v_mfma_f32_16x16x32_bf16 v[90:93], v[154:157], v[170:173], v[90:93]
	v_mfma_f32_16x16x32_bf16 v[26:29], v[162:165], v[170:173], v[26:29]
	v_mfma_f32_16x16x32_bf16 v[18:21], v[162:165], v[206:209], v[18:21]
	v_mfma_f32_16x16x32_bf16 v[82:85], v[154:157], v[206:209], v[82:85]
	v_mfma_f32_16x16x32_bf16 v[74:77], v[154:157], v[214:217], v[74:77]
	v_mfma_f32_16x16x32_bf16 v[10:13], v[162:165], v[214:217], v[10:13]
	v_mfma_f32_16x16x32_bf16 v[2:5], v[162:165], v[242:245], v[2:5]
	v_mfma_f32_16x16x32_bf16 v[66:69], v[154:157], v[242:245], v[66:69]
	s_barrier
	s_setprio 0
	s_add_i32 s46, s46, 2
	s_add_u32 s40, s40, 0x100
	s_addc_u32 s41, s41, 0
	s_add_u32 s37, s37, 0x100
	s_addc_u32 s39, s39, 0
	s_cmp_gt_u32 s46, 29
	s_cbranch_scc1 .LBB0_1688

.LBB0_1753:
	s_load_dwordx2 s[26:27], s[24:25], 0x118
	v_sub_co_u32_e64 v150, s[2:3], s15, 1
	s_andn2_b64 vcc, exec, s[2:3]
	s_cbranch_vccnz .LBB0_1858
	s_add_i32 s6, s28, s33
	v_readlane_b32 s2, v255, 19
	s_sub_i32 s2, s6, s2
	s_ashr_i32 s3, s2, 31
	s_abs_i32 s2, s2
	v_readlane_b32 s7, v255, 20
	s_mul_hi_u32 s7, s2, s7
	v_readlane_b32 s8, v255, 21
	s_mul_i32 s7, s7, s8
	s_sub_i32 s2, s2, s7
	s_sub_i32 s7, s2, s8
	s_cmp_ge_u32 s2, s8
	s_cselect_b32 s2, s7, s2
	s_sub_i32 s7, s2, s8
	s_cmp_ge_u32 s2, s8
	s_cselect_b32 s2, s7, s2
	s_xor_b32 s2, s2, s3
	v_mov_b32_e32 v16, v0
	s_sub_i32 s7, s2, s3
	s_cmp_gt_i32 s7, 47
	v_readfirstlane_b32 s34, v16
	s_cbranch_scc1 .LBB0_1768
	v_lshlrev_b32_e32 v2, 4, v16
	s_waitcnt lgkmcnt(0)
	v_add_u32_e32 v3, 0x2000, v2
	v_ashrrev_i32_e32 v4, 31, v3
	v_lshrrev_b32_e32 v4, 22, v4
	v_add_u32_e32 v4, v3, v4
	v_ashrrev_i32_e32 v10, 10, v4
	v_mul_i32_i24_e32 v5, 0x400, v10
	v_sub_u32_e32 v3, v3, v5
	v_lshrrev_b32_e32 v5, 4, v3
	v_bitop3_b32 v3, v5, v3, 32 bitop3:0x6c
	v_ashrrev_i32_e32 v5, 31, v3
	v_lshrrev_b32_e32 v5, 26, v5
	v_add_u32_e32 v5, v3, v5
	v_ashrrev_i32_e32 v11, 6, v5
	v_and_b32_e32 v5, 0xc0, v5
	v_sub_u32_e32 v3, v3, v5
	v_lshlrev_b32_e32 v4, 5, v10
	v_ashrrev_i16_sdwa v3, v224, sext(v3) dst_sel:DWORD dst_unused:UNUSED_PAD src0_sel:DWORD src1_sel:BYTE_0
	v_and_b32_e32 v4, 32, v4
	v_bfe_i32 v12, v3, 0, 16
	v_add_u32_e32 v3, v4, v12
	v_lshlrev_b32_e32 v4, 3, v10
	v_and_b32_e32 v4, 0xffff0, v4
	v_add_lshl_u32 v4, v11, v4, 12
	v_lshl_add_u32 v130, v3, 1, v4
	v_bfe_i32 v4, v16, 27, 1
	v_lshrrev_b32_e32 v4, 22, v4
	v_add_u32_e32 v4, v2, v4
	v_and_b32_e32 v4, 0xfffffc00, v4
	v_sub_u32_e32 v2, v2, v4
	v_lshrrev_b32_e32 v4, 4, v2
	v_bitop3_b32 v2, v4, v2, 32 bitop3:0x6c
	v_ashrrev_i32_e32 v4, 31, v2
	s_add_u32 s8, s26, 0x1ff00000
	v_ashrrev_i32_e32 v3, 31, v16
	v_lshrrev_b32_e32 v4, 26, v4
	s_addc_u32 s9, s27, 0
	v_lshrrev_b32_e32 v3, 26, v3
	v_add_u32_e32 v4, v2, v4
	s_add_u32 s21, s26, 0x15800000
	v_add_u32_e32 v3, v16, v3
	v_ashrrev_i32_e32 v14, 6, v4
	v_and_b32_e32 v4, 0xc0, v4
	s_addc_u32 s42, s27, 0
	s_add_i32 s2, s7, 16
	v_ashrrev_i32_e32 v13, 6, v3
	v_sub_u32_e32 v2, v2, v4
	s_ashr_i32 s2, s2, 2
	v_lshlrev_b32_e32 v3, 5, v13
	v_ashrrev_i16_sdwa v2, v224, sext(v2) dst_sel:DWORD dst_unused:UNUSED_PAD src0_sel:DWORD src1_sel:BYTE_0
	s_ashr_i32 s35, s34, 6
	s_and_b32 s44, s7, 3
	v_and_b32_e32 v3, 32, v3
	v_bfe_i32 v15, v2, 0, 16
	s_ashr_i32 s3, s2, 31
	s_ashr_i32 s36, s34, 8
	s_lshl_b32 s43, s35, 10
	v_add_u32_e32 v2, v3, v15
	v_lshlrev_b32_e32 v3, 3, v13
	s_lshl_b32 s18, s44, 20
	s_lshl_b64 s[10:11], s[2:3], 20
	v_and_b32_e32 v3, 0xffff0, v3
	s_add_u32 s10, s21, s10
	v_add_lshl_u32 v3, v14, v3, 12
	s_addc_u32 s11, s42, s11
	s_add_i32 s3, s43, 0
	v_lshl_add_u32 v132, v2, 1, v3
	s_add_i32 m0, s3, 0x10000
	v_mov_b32_e32 v133, v181
	v_and_b32_e32 v138, 63, v0
	v_lshrrev_b32_e32 v139, 3, v138
	v_and_b32_e32 v138, 7, v138
	v_xor_b32_e32 v138, v138, v139
	v_lshlrev_b32_e32 v138, 4, v138
	v_lshrrev_b32_e32 v140, 6, v0
	v_lshl_add_u32 v139, v140, 3, v139
	v_mov_b32_e32 v140, 0x1000
	v_mad_u32_u24 v132, v139, v140, v138
	v_add_u32_e32 v130, 0x40000, v132
	global_load_lds_dwordx4 v132, s[10:11]
	s_add_i32 m0, s3, 0x12000
	s_add_u32 s14, s10, 0x80000
	global_load_lds_dwordx4 v130, s[10:11]
	s_addc_u32 s15, s11, 0
	s_add_i32 m0, s3, 0x14000
	v_mov_b32_e32 v131, v181
	global_load_lds_dwordx4 v132, s[14:15]
	s_add_i32 m0, s3, 0x16000
	s_add_u32 s18, s8, s18
	s_addc_u32 s19, s9, 0
	s_add_i32 s45, s3, 0x2000
	global_load_lds_dwordx4 v130, s[14:15]
	s_mov_b32 m0, s3
	s_add_u32 s14, s18, 0x80000
	global_load_lds_dwordx4 v132, s[18:19]
	s_mov_b32 m0, s45
	s_addc_u32 s15, s19, 0
	s_add_i32 s46, s3, 0x4000
	global_load_lds_dwordx4 v130, s[18:19]
	s_mov_b32 m0, s46
	s_add_i32 s47, s3, 0x6000
	global_load_lds_dwordx4 v132, s[14:15]
	s_mov_b32 m0, s47
	s_cmp_eq_u32 s36, 1
	global_load_lds_dwordx4 v130, s[14:15]
	s_load_dwordx2 s[14:15], s[24:25], 0x110
	v_lshl_add_u64 v[8:9], s[10:11], 0, v[132:133]
	v_lshl_add_u64 v[6:7], s[10:11], 0, v[130:131]
	v_lshl_add_u64 v[2:3], s[18:19], 0, v[132:133]
	s_cselect_b64 s[22:23], -1, 0
	s_cmp_lg_u32 s36, 1
	v_lshl_add_u64 v[4:5], s[18:19], 0, v[130:131]
	s_cbranch_scc1 .LBB0_1757
	s_barrier
.LBB0_1757:
	s_add_u32 s28, s26, 0xe0000
	s_addc_u32 s29, s27, 0
	v_bfe_u32 v152, v16, 4, 2
	s_add_u32 s30, s26, 0x20300000
	v_and_b32_e32 v151, 15, v16
	v_lshlrev_b32_e32 v17, 4, v152
	v_lshlrev_b32_e32 v16, 2, v16
	s_addc_u32 s31, s27, 0
	v_lshl_or_b32 v17, v151, 6, v17
	s_lshl_b32 s26, s36, 13
	v_and_b32_e32 v16, 32, v16
	v_bitop3_b32 v18, v17, s26, v16 bitop3:0xde
	s_lshl_b32 s26, s35, 5
	s_and_b32 s49, s26, 0x60
	s_add_i32 m0, s3, 0x18000
	v_lshl_add_u64 v[8:9], v[8:9], 0, s[16:17]
	s_lshl_b32 s48, s36, 6
	s_lshl_b32 s26, s49, 7
	s_waitcnt vmcnt(2)
	s_barrier
	global_load_lds_dwordx4 v[8:9], off
	v_lshl_add_u64 v[6:7], v[6:7], 0, s[16:17]
	s_add_i32 m0, s3, 0x1a000
	s_add_i32 s50, s3, 0x8000
	s_add_i32 s51, s3, 0xa000
	v_bitop3_b32 v153, v17, s26, v16 bitop3:0xde
	global_load_lds_dwordx4 v[6:7], off
	v_lshl_add_u64 v[2:3], v[2:3], 0, s[16:17]
	s_mov_b32 m0, s50
	s_add_u32 s26, s10, 0x80080
	global_load_lds_dwordx4 v[2:3], off
	v_lshl_add_u64 v[2:3], v[4:5], 0, s[16:17]
	s_mov_b32 m0, s51
	s_addc_u32 s27, s11, 0
	global_load_lds_dwordx4 v[2:3], off
	s_add_i32 m0, s3, 0x1c000
	v_lshl_add_u64 v[2:3], s[26:27], 0, v[132:133]
	global_load_lds_dwordx4 v[2:3], off
	v_lshl_add_u64 v[2:3], s[26:27], 0, v[130:131]
	s_add_i32 m0, s3, 0x1e000
	s_cmpk_lt_u32 s34, 0x100
	global_load_lds_dwordx4 v[2:3], off
	v_lshlrev_b32_e32 v2, 15, v13
	v_and_b32_e32 v2, 0xffff0000, v2
	v_lshl_add_u32 v2, v14, 12, v2
	v_and_b32_e32 v3, 1, v13
	v_lshl_or_b32 v2, v3, 6, v2
	v_mov_b32_e32 v134, v132
	v_lshlrev_b32_e32 v2, 15, v10
	v_and_b32_e32 v2, 0xffff0000, v2
	s_waitcnt vmcnt(6)
	v_lshl_add_u32 v2, v11, 12, v2
	v_and_b32_e32 v3, 1, v10
	v_lshl_or_b32 v2, v3, 6, v2
	s_cselect_b64 s[34:35], -1, 0
	v_mov_b32_e32 v135, v181
	v_mov_b32_e32 v136, v130
	v_mov_b32_e32 v137, v181
	s_mov_b32 s54, 0
	v_add_u32_e32 v154, 0, v18
	v_and_b32_e32 v138, 7, v0
	v_bfe_u32 v139, v0, 4, 2
	v_xor_b32_e32 v139, v139, v138
	v_lshlrev_b32_e32 v139, 4, v139
	v_lshl_add_u32 v139, v138, 7, v139
	v_bfe_u32 v138, v0, 3, 1
	v_lshl_add_u32 v139, v138, 10, v139
	v_lshrrev_b32_e32 v138, 8, v0
	v_lshl_add_u32 v154, v138, 13, v139
	v_bfe_u32 v138, v0, 6, 2
	v_lshl_add_u32 v153, v138, 12, v139
	s_barrier
	s_branch .LBB0_1760

.LBB0_1761:
	s_add_u32 s26, s38, 0xfff80080
	s_addc_u32 s27, s39, -1
	s_add_i32 s64, 0, 0x10000
	s_cmp_eq_u32 s63, 28
	s_cselect_b32 s41, s57, s27
	s_cselect_b32 s40, s58, s26
	v_add_u32_e32 v155, s64, v153
	s_cselect_b32 s27, s59, s62
	s_cselect_b32 s26, s60, s61
	s_add_i32 s68, 0, 0x14000
	ds_read_b128 v[138:141], v155
	ds_read_b128 v[146:149], v155 offset:2048
	v_xor_b32_e32 v155, 64, v155
	ds_read_b128 v[142:145], v155
	ds_read_b128 v[156:159], v155 offset:2048
	v_add_u32_e32 v155, s68, v153
	ds_read_b128 v[160:163], v155
	ds_read_b128 v[168:171], v155 offset:2048
	v_xor_b32_e32 v155, 64, v155
	ds_read_b128 v[164:167], v155
	ds_read_b128 v[172:175], v155 offset:2048
	v_lshl_add_u64 v[220:221], s[38:39], 0, v[134:135]
	s_add_i32 m0, s3, 0xc000
	ds_read_b128 v[176:179], v154
	ds_read_b128 v[196:199], v154 offset:2048
	ds_read_b128 v[204:207], v154 offset:4096
	ds_read_b128 v[212:215], v154 offset:6144
	v_xor_b32_e32 v216, 64, v154
	ds_read_b128 v[192:195], v216
	ds_read_b128 v[200:203], v216 offset:2048
	ds_read_b128 v[208:211], v216 offset:4096
	ds_read_b128 v[216:219], v216 offset:6144
	global_load_lds_dwordx4 v[220:221], off
	v_lshl_add_u64 v[220:221], s[38:39], 0, v[136:137]
	s_add_i32 m0, s3, 0xe000
	s_nop 0
	global_load_lds_dwordx4 v[220:221], off
	s_waitcnt vmcnt(8)
	s_waitcnt lgkmcnt(0)
	s_setprio 1
	s_barrier
	v_mfma_f32_16x16x32_bf16 v[126:129], v[138:141], v[176:179], v[126:129]
	v_mfma_f32_16x16x32_bf16 v[122:125], v[146:149], v[176:179], v[122:125]
	v_mfma_f32_16x16x32_bf16 v[106:109], v[146:149], v[196:199], v[106:109]
	v_mfma_f32_16x16x32_bf16 v[110:113], v[138:141], v[196:199], v[110:113]
	v_mfma_f32_16x16x32_bf16 v[94:97], v[138:141], v[204:207], v[94:97]
	v_mfma_f32_16x16x32_bf16 v[90:93], v[146:149], v[204:207], v[90:93]
	v_mfma_f32_16x16x32_bf16 v[74:77], v[146:149], v[212:215], v[74:77]
	v_mfma_f32_16x16x32_bf16 v[78:81], v[138:141], v[212:215], v[78:81]
	v_mfma_f32_16x16x32_bf16 v[126:129], v[142:145], v[192:195], v[126:129]
	v_mfma_f32_16x16x32_bf16 v[122:125], v[156:159], v[192:195], v[122:125]
	v_mfma_f32_16x16x32_bf16 v[106:109], v[156:159], v[200:203], v[106:109]
	v_mfma_f32_16x16x32_bf16 v[110:113], v[142:145], v[200:203], v[110:113]
	v_mfma_f32_16x16x32_bf16 v[94:97], v[142:145], v[208:211], v[94:97]
	v_mfma_f32_16x16x32_bf16 v[90:93], v[156:159], v[208:211], v[90:93]
	v_mfma_f32_16x16x32_bf16 v[74:77], v[156:159], v[216:219], v[74:77]
	v_mfma_f32_16x16x32_bf16 v[78:81], v[142:145], v[216:219], v[78:81]
	v_mfma_f32_16x16x32_bf16 v[118:121], v[160:163], v[176:179], v[118:121]
	v_mfma_f32_16x16x32_bf16 v[114:117], v[168:171], v[176:179], v[114:117]
	v_mfma_f32_16x16x32_bf16 v[98:101], v[168:171], v[196:199], v[98:101]
	v_mfma_f32_16x16x32_bf16 v[102:105], v[160:163], v[196:199], v[102:105]
	v_mfma_f32_16x16x32_bf16 v[86:89], v[160:163], v[204:207], v[86:89]
	v_mfma_f32_16x16x32_bf16 v[82:85], v[168:171], v[204:207], v[82:85]
	v_mfma_f32_16x16x32_bf16 v[66:69], v[168:171], v[212:215], v[66:69]
	v_mfma_f32_16x16x32_bf16 v[70:73], v[160:163], v[212:215], v[70:73]
	v_mfma_f32_16x16x32_bf16 v[118:121], v[164:167], v[192:195], v[118:121]
	v_mfma_f32_16x16x32_bf16 v[114:117], v[172:175], v[192:195], v[114:117]
	v_mfma_f32_16x16x32_bf16 v[98:101], v[172:175], v[200:203], v[98:101]
	v_mfma_f32_16x16x32_bf16 v[102:105], v[164:167], v[200:203], v[102:105]
	v_mfma_f32_16x16x32_bf16 v[86:89], v[164:167], v[208:211], v[86:89]
	v_mfma_f32_16x16x32_bf16 v[82:85], v[172:175], v[208:211], v[82:85]
	v_mfma_f32_16x16x32_bf16 v[66:69], v[172:175], v[216:219], v[66:69]
	v_mfma_f32_16x16x32_bf16 v[70:73], v[164:167], v[216:219], v[70:73]
	s_barrier
	s_setprio 0
	s_add_i32 s64, s64, s43
	v_lshl_add_u64 v[220:221], s[26:27], 0, v[132:133]
	s_mov_b32 m0, s64
	ds_read_b128 v[176:179], v154 offset:16384
	ds_read_b128 v[196:199], v154 offset:18432
	ds_read_b128 v[204:207], v154 offset:20480
	ds_read_b128 v[212:215], v154 offset:22528
	v_xor_b32_e32 v216, 64, v154
	ds_read_b128 v[192:195], v216 offset:16384
	ds_read_b128 v[200:203], v216 offset:18432
	ds_read_b128 v[208:211], v216 offset:20480
	ds_read_b128 v[216:219], v216 offset:22528
	global_load_lds_dwordx4 v[220:221], off
	s_add_i32 m0, s64, 0x2000
	s_add_u32 s66, s26, 0x80000
	v_lshl_add_u64 v[222:223], s[26:27], 0, v[130:131]
	s_addc_u32 s67, s27, 0
	s_add_i32 s64, s68, s43
	global_load_lds_dwordx4 v[222:223], off
	v_lshl_add_u64 v[238:239], s[66:67], 0, v[132:133]
	s_mov_b32 m0, s64
	v_lshl_add_u64 v[240:241], s[40:41], 0, v[130:131]
	global_load_lds_dwordx4 v[238:239], off
	v_lshl_add_u64 v[238:239], s[66:67], 0, v[130:131]
	s_add_i32 m0, s64, 0x2000
	s_nop 0
	global_load_lds_dwordx4 v[238:239], off
	v_lshl_add_u64 v[238:239], s[40:41], 0, v[132:133]
	s_mov_b32 m0, s3
	s_nop 0
	global_load_lds_dwordx4 v[238:239], off
	s_mov_b32 m0, s45
	s_nop 0
	global_load_lds_dwordx4 v[240:241], off
	s_waitcnt vmcnt(8)
	s_waitcnt lgkmcnt(0)
	s_setprio 1
	s_barrier
	v_mfma_f32_16x16x32_bf16 v[62:65], v[138:141], v[176:179], v[62:65]
	v_mfma_f32_16x16x32_bf16 v[58:61], v[146:149], v[176:179], v[58:61]
	v_mfma_f32_16x16x32_bf16 v[42:45], v[146:149], v[196:199], v[42:45]
	v_mfma_f32_16x16x32_bf16 v[46:49], v[138:141], v[196:199], v[46:49]
	v_mfma_f32_16x16x32_bf16 v[30:33], v[138:141], v[204:207], v[30:33]
	v_mfma_f32_16x16x32_bf16 v[26:29], v[146:149], v[204:207], v[26:29]
	v_mfma_f32_16x16x32_bf16 v[10:13], v[146:149], v[212:215], v[10:13]
	v_mfma_f32_16x16x32_bf16 v[14:17], v[138:141], v[212:215], v[14:17]
	v_mfma_f32_16x16x32_bf16 v[62:65], v[142:145], v[192:195], v[62:65]
	v_mfma_f32_16x16x32_bf16 v[58:61], v[156:159], v[192:195], v[58:61]
	v_mfma_f32_16x16x32_bf16 v[42:45], v[156:159], v[200:203], v[42:45]
	v_mfma_f32_16x16x32_bf16 v[46:49], v[142:145], v[200:203], v[46:49]
	v_mfma_f32_16x16x32_bf16 v[30:33], v[142:145], v[208:211], v[30:33]
	v_mfma_f32_16x16x32_bf16 v[26:29], v[156:159], v[208:211], v[26:29]
	v_mfma_f32_16x16x32_bf16 v[10:13], v[156:159], v[216:219], v[10:13]
	v_mfma_f32_16x16x32_bf16 v[14:17], v[142:145], v[216:219], v[14:17]
	v_mfma_f32_16x16x32_bf16 v[54:57], v[160:163], v[176:179], v[54:57]
	v_mfma_f32_16x16x32_bf16 v[50:53], v[168:171], v[176:179], v[50:53]
	v_mfma_f32_16x16x32_bf16 v[34:37], v[168:171], v[196:199], v[34:37]
	v_mfma_f32_16x16x32_bf16 v[38:41], v[160:163], v[196:199], v[38:41]
	v_mfma_f32_16x16x32_bf16 v[22:25], v[160:163], v[204:207], v[22:25]
	v_mfma_f32_16x16x32_bf16 v[18:21], v[168:171], v[204:207], v[18:21]
	v_mfma_f32_16x16x32_bf16 v[2:5], v[168:171], v[212:215], v[2:5]
	v_mfma_f32_16x16x32_bf16 v[6:9], v[160:163], v[212:215], v[6:9]
	v_mfma_f32_16x16x32_bf16 v[54:57], v[164:167], v[192:195], v[54:57]
	v_mfma_f32_16x16x32_bf16 v[50:53], v[172:175], v[192:195], v[50:53]
	v_mfma_f32_16x16x32_bf16 v[34:37], v[172:175], v[200:203], v[34:37]
	v_mfma_f32_16x16x32_bf16 v[38:41], v[164:167], v[200:203], v[38:41]
	v_mfma_f32_16x16x32_bf16 v[22:25], v[164:167], v[208:211], v[22:25]
	v_mfma_f32_16x16x32_bf16 v[18:21], v[172:175], v[208:211], v[18:21]
	v_mfma_f32_16x16x32_bf16 v[2:5], v[172:175], v[216:219], v[2:5]
	v_mfma_f32_16x16x32_bf16 v[6:9], v[164:167], v[216:219], v[6:9]
	s_barrier
	s_setprio 0
	s_add_i32 s64, 0, 0x18000
	v_add_u32_e32 v155, s64, v153
	s_add_i32 s66, 0, 0x1c000
	ds_read_b128 v[138:141], v155
	ds_read_b128 v[146:149], v155 offset:2048
	v_xor_b32_e32 v155, 64, v155
	ds_read_b128 v[142:145], v155
	ds_read_b128 v[156:159], v155 offset:2048
	v_add_u32_e32 v155, s66, v153
	ds_read_b128 v[160:163], v155
	ds_read_b128 v[168:171], v155 offset:2048
	v_xor_b32_e32 v155, 64, v155
	ds_read_b128 v[164:167], v155
	ds_read_b128 v[172:175], v155 offset:2048
	s_add_u32 s40, s40, 0x80000
	s_addc_u32 s41, s41, 0
	s_mov_b32 m0, s46
	v_lshl_add_u64 v[242:243], s[40:41], 0, v[132:133]
	ds_read_b128 v[176:179], v154 offset:32768
	ds_read_b128 v[196:199], v154 offset:34816
	ds_read_b128 v[204:207], v154 offset:36864
	ds_read_b128 v[212:215], v154 offset:38912
	v_xor_b32_e32 v216, 64, v154
	ds_read_b128 v[192:195], v216 offset:32768
	ds_read_b128 v[200:203], v216 offset:34816
	ds_read_b128 v[208:211], v216 offset:36864
	ds_read_b128 v[216:219], v216 offset:38912
	global_load_lds_dwordx4 v[242:243], off
	v_lshl_add_u64 v[242:243], s[40:41], 0, v[130:131]
	s_mov_b32 m0, s47
	s_nop 0
	global_load_lds_dwordx4 v[242:243], off
	s_waitcnt vmcnt(8)
	s_waitcnt lgkmcnt(0)
	s_setprio 1
	s_barrier
	v_mfma_f32_16x16x32_bf16 v[126:129], v[138:141], v[176:179], v[126:129]
	v_mfma_f32_16x16x32_bf16 v[122:125], v[146:149], v[176:179], v[122:125]
	v_mfma_f32_16x16x32_bf16 v[106:109], v[146:149], v[196:199], v[106:109]
	v_mfma_f32_16x16x32_bf16 v[110:113], v[138:141], v[196:199], v[110:113]
	v_mfma_f32_16x16x32_bf16 v[94:97], v[138:141], v[204:207], v[94:97]
	v_mfma_f32_16x16x32_bf16 v[90:93], v[146:149], v[204:207], v[90:93]
	v_mfma_f32_16x16x32_bf16 v[74:77], v[146:149], v[212:215], v[74:77]
	v_mfma_f32_16x16x32_bf16 v[78:81], v[138:141], v[212:215], v[78:81]
	v_mfma_f32_16x16x32_bf16 v[126:129], v[142:145], v[192:195], v[126:129]
	v_mfma_f32_16x16x32_bf16 v[122:125], v[156:159], v[192:195], v[122:125]
	v_mfma_f32_16x16x32_bf16 v[106:109], v[156:159], v[200:203], v[106:109]
	v_mfma_f32_16x16x32_bf16 v[110:113], v[142:145], v[200:203], v[110:113]
	v_mfma_f32_16x16x32_bf16 v[94:97], v[142:145], v[208:211], v[94:97]
	v_mfma_f32_16x16x32_bf16 v[90:93], v[156:159], v[208:211], v[90:93]
	v_mfma_f32_16x16x32_bf16 v[74:77], v[156:159], v[216:219], v[74:77]
	v_mfma_f32_16x16x32_bf16 v[78:81], v[142:145], v[216:219], v[78:81]
	v_mfma_f32_16x16x32_bf16 v[118:121], v[160:163], v[176:179], v[118:121]
	v_mfma_f32_16x16x32_bf16 v[114:117], v[168:171], v[176:179], v[114:117]
	v_mfma_f32_16x16x32_bf16 v[98:101], v[168:171], v[196:199], v[98:101]
	v_mfma_f32_16x16x32_bf16 v[102:105], v[160:163], v[196:199], v[102:105]
	v_mfma_f32_16x16x32_bf16 v[86:89], v[160:163], v[204:207], v[86:89]
	v_mfma_f32_16x16x32_bf16 v[82:85], v[168:171], v[204:207], v[82:85]
	v_mfma_f32_16x16x32_bf16 v[66:69], v[168:171], v[212:215], v[66:69]
	v_mfma_f32_16x16x32_bf16 v[70:73], v[160:163], v[212:215], v[70:73]
	v_mfma_f32_16x16x32_bf16 v[118:121], v[164:167], v[192:195], v[118:121]
	v_mfma_f32_16x16x32_bf16 v[114:117], v[172:175], v[192:195], v[114:117]
	v_mfma_f32_16x16x32_bf16 v[98:101], v[172:175], v[200:203], v[98:101]
	v_mfma_f32_16x16x32_bf16 v[102:105], v[164:167], v[200:203], v[102:105]
	v_mfma_f32_16x16x32_bf16 v[86:89], v[164:167], v[208:211], v[86:89]
	v_mfma_f32_16x16x32_bf16 v[82:85], v[172:175], v[208:211], v[82:85]
	v_mfma_f32_16x16x32_bf16 v[66:69], v[172:175], v[216:219], v[66:69]
	v_mfma_f32_16x16x32_bf16 v[70:73], v[164:167], v[216:219], v[70:73]
	s_barrier
	s_setprio 0
	s_add_i32 s40, s64, s43
	v_lshl_add_u64 v[220:221], v[220:221], 0, s[16:17]
	s_mov_b32 m0, s40
	ds_read_b128 v[176:179], v154 offset:49152
	ds_read_b128 v[196:199], v154 offset:51200
	ds_read_b128 v[204:207], v154 offset:53248
	ds_read_b128 v[212:215], v154 offset:55296
	v_xor_b32_e32 v216, 64, v154
	ds_read_b128 v[192:195], v216 offset:49152
	ds_read_b128 v[200:203], v216 offset:51200
	ds_read_b128 v[208:211], v216 offset:53248
	ds_read_b128 v[216:219], v216 offset:55296
	global_load_lds_dwordx4 v[220:221], off
	s_add_i32 m0, s40, 0x2000
	s_add_u32 s26, s26, 0x80080
	v_lshl_add_u64 v[220:221], v[222:223], 0, s[16:17]
	s_addc_u32 s27, s27, 0
	s_add_i32 s40, s66, s43
	global_load_lds_dwordx4 v[220:221], off
	v_lshl_add_u64 v[220:221], s[26:27], 0, v[132:133]
	s_mov_b32 m0, s40
	s_nop 0
	global_load_lds_dwordx4 v[220:221], off
	v_lshl_add_u64 v[220:221], s[26:27], 0, v[130:131]
	s_add_i32 m0, s40, 0x2000
	s_nop 0
	global_load_lds_dwordx4 v[220:221], off
	v_lshl_add_u64 v[220:221], v[238:239], 0, s[16:17]
	s_mov_b32 m0, s50
	s_nop 0
	global_load_lds_dwordx4 v[220:221], off
	v_lshl_add_u64 v[220:221], v[240:241], 0, s[16:17]
	s_mov_b32 m0, s51
	s_nop 0
	global_load_lds_dwordx4 v[220:221], off
	s_waitcnt vmcnt(8)
	s_waitcnt lgkmcnt(0)
	s_setprio 1
	s_barrier
	v_mfma_f32_16x16x32_bf16 v[62:65], v[138:141], v[176:179], v[62:65]
	v_mfma_f32_16x16x32_bf16 v[58:61], v[146:149], v[176:179], v[58:61]
	v_mfma_f32_16x16x32_bf16 v[42:45], v[146:149], v[196:199], v[42:45]
	v_mfma_f32_16x16x32_bf16 v[46:49], v[138:141], v[196:199], v[46:49]
	v_mfma_f32_16x16x32_bf16 v[30:33], v[138:141], v[204:207], v[30:33]
	v_mfma_f32_16x16x32_bf16 v[26:29], v[146:149], v[204:207], v[26:29]
	v_mfma_f32_16x16x32_bf16 v[10:13], v[146:149], v[212:215], v[10:13]
	v_mfma_f32_16x16x32_bf16 v[14:17], v[138:141], v[212:215], v[14:17]
	v_mfma_f32_16x16x32_bf16 v[62:65], v[142:145], v[192:195], v[62:65]
	v_mfma_f32_16x16x32_bf16 v[58:61], v[156:159], v[192:195], v[58:61]
	v_mfma_f32_16x16x32_bf16 v[42:45], v[156:159], v[200:203], v[42:45]
	v_mfma_f32_16x16x32_bf16 v[46:49], v[142:145], v[200:203], v[46:49]
	v_mfma_f32_16x16x32_bf16 v[30:33], v[142:145], v[208:211], v[30:33]
	v_mfma_f32_16x16x32_bf16 v[26:29], v[156:159], v[208:211], v[26:29]
	v_mfma_f32_16x16x32_bf16 v[10:13], v[156:159], v[216:219], v[10:13]
	v_mfma_f32_16x16x32_bf16 v[14:17], v[142:145], v[216:219], v[14:17]
	v_mfma_f32_16x16x32_bf16 v[54:57], v[160:163], v[176:179], v[54:57]
	v_mfma_f32_16x16x32_bf16 v[50:53], v[168:171], v[176:179], v[50:53]
	v_mfma_f32_16x16x32_bf16 v[34:37], v[168:171], v[196:199], v[34:37]
	v_mfma_f32_16x16x32_bf16 v[38:41], v[160:163], v[196:199], v[38:41]
	v_mfma_f32_16x16x32_bf16 v[22:25], v[160:163], v[204:207], v[22:25]
	v_mfma_f32_16x16x32_bf16 v[18:21], v[168:171], v[204:207], v[18:21]
	v_mfma_f32_16x16x32_bf16 v[2:5], v[168:171], v[212:215], v[2:5]
	v_mfma_f32_16x16x32_bf16 v[6:9], v[160:163], v[212:215], v[6:9]
	v_mfma_f32_16x16x32_bf16 v[54:57], v[164:167], v[192:195], v[54:57]
	v_mfma_f32_16x16x32_bf16 v[50:53], v[172:175], v[192:195], v[50:53]
	v_mfma_f32_16x16x32_bf16 v[34:37], v[172:175], v[200:203], v[34:37]
	v_mfma_f32_16x16x32_bf16 v[38:41], v[164:167], v[200:203], v[38:41]
	v_mfma_f32_16x16x32_bf16 v[22:25], v[164:167], v[208:211], v[22:25]
	v_mfma_f32_16x16x32_bf16 v[18:21], v[172:175], v[208:211], v[18:21]
	v_mfma_f32_16x16x32_bf16 v[2:5], v[172:175], v[216:219], v[2:5]
	v_mfma_f32_16x16x32_bf16 v[6:9], v[164:167], v[216:219], v[6:9]
	s_barrier
	s_setprio 0
	s_add_i32 s63, s63, 2
	s_add_u32 s38, s38, 0x100
	s_addc_u32 s39, s39, 0
	s_add_u32 s61, s61, 0x100
	s_addc_u32 s62, s62, 0
	s_cmp_gt_u32 s63, 29
	s_cbranch_scc0 .LBB0_1761
	s_and_b64 vcc, exec, s[34:35]
	s_cbranch_vccz .LBB0_1764
	s_barrier

.LBB0_2224:
	s_andn2_b64 vcc, exec, s[14:15]
	s_cbranch_vccnz .LBB0_2264
	v_ashrrev_i32_e32 v4, 31, v2
	v_lshrrev_b32_e32 v4, 26, v4
	v_add_u32_e32 v4, v2, v4
	v_ashrrev_i32_e32 v148, 6, v4
	v_bfe_i32 v4, v2, 27, 1
	v_lshlrev_b32_e32 v3, 4, v2
	v_lshrrev_b32_e32 v4, 22, v4
	v_add_u32_e32 v4, v3, v4
	v_and_b32_e32 v4, 0xfffffc00, v4
	v_sub_u32_e32 v4, v3, v4
	v_lshrrev_b32_e32 v5, 4, v4
	v_bitop3_b32 v4, v5, v4, 32 bitop3:0x6c
	v_ashrrev_i32_e32 v6, 31, v4
	v_lshrrev_b32_e32 v6, 26, v6
	v_lshlrev_b32_e32 v5, 3, v148
	v_add_u32_e32 v6, v4, v6
	v_and_b32_e32 v5, -16, v5
	v_ashrrev_i32_e32 v150, 6, v6
	v_and_b32_e32 v6, 0xc0, v6
	s_mov_b64 s[14:15], 0x1de00000
	v_add_u32_e32 v5, v150, v5
	v_lshlrev_b32_e32 v7, 5, v148
	v_sub_u32_e32 v4, v4, v6
	v_lshl_add_u64 v[132:133], v[130:131], 0, s[14:15]
	v_and_b32_e32 v149, 32, v7
	v_ashrrev_i16_sdwa v4, v224, sext(v4) dst_sel:DWORD dst_unused:UNUSED_PAD src0_sel:DWORD src1_sel:BYTE_0
	v_lshlrev_b32_e32 v6, 1, v5
	v_lshrrev_b32_e32 v7, 2, v5
	v_and_b32_e32 v8, 3, v150
	s_mov_b32 s14, 0x1ffffe0
	v_bfe_i32 v151, v4, 0, 16
	v_and_b32_e32 v6, 24, v6
	v_and_b32_e32 v7, 4, v7
	v_and_or_b32 v8, v5, s14, v8
	s_movk_i32 s12, 0x1580
	v_add_u32_e32 v4, v149, v151
	v_or3_b32 v6, v8, v7, v6
	v_mul_lo_u32 v5, v5, s12
	v_add_lshl_u32 v134, v4, v5, 1
	v_mul_lo_u32 v5, v6, s12
	v_add_u32_e32 v3, 0x2000, v3
	v_add_lshl_u32 v136, v5, v4, 1
	v_ashrrev_i32_e32 v4, 31, v3
	v_lshrrev_b32_e32 v4, 22, v4
	v_add_u32_e32 v4, v3, v4
	v_ashrrev_i32_e32 v157, 10, v4
	v_mul_i32_i24_e32 v4, 0x400, v157
	v_sub_u32_e32 v3, v3, v4
	v_lshrrev_b32_e32 v4, 4, v3
	v_bitop3_b32 v3, v4, v3, 32 bitop3:0x6c
	v_ashrrev_i32_e32 v5, 31, v3
	v_lshrrev_b32_e32 v5, 26, v5
	v_lshlrev_b32_e32 v4, 3, v157
	v_add_u32_e32 v5, v3, v5
	v_and_b32_e32 v4, -16, v4
	v_ashrrev_i32_e32 v159, 6, v5
	v_and_b32_e32 v5, 0xc0, v5
	v_add_u32_e32 v4, v159, v4
	v_lshlrev_b32_e32 v6, 5, v157
	v_sub_u32_e32 v3, v3, v5
	v_and_b32_e32 v158, 32, v6
	v_ashrrev_i16_sdwa v3, v224, sext(v3) dst_sel:DWORD dst_unused:UNUSED_PAD src0_sel:DWORD src1_sel:BYTE_0
	v_lshlrev_b32_e32 v5, 1, v4
	v_lshrrev_b32_e32 v6, 2, v4
	v_and_b32_e32 v7, 3, v159
	v_bfe_i32 v160, v3, 0, 16
	v_and_b32_e32 v5, 24, v5
	v_and_b32_e32 v6, 4, v6
	v_and_or_b32 v7, v4, s14, v7
	v_add_u32_e32 v3, v158, v160
	v_or3_b32 v5, v7, v6, v5
	v_mul_lo_u32 v4, v4, s12
	v_add_lshl_u32 v138, v3, v4, 1
	v_mul_lo_u32 v4, v5, s12
	s_ashr_i32 s12, s22, 6
	s_ashr_i32 s18, s22, 8
	s_lshl_b32 s40, s12, 10
	s_lshl_b32 s12, s12, 5
	s_lshl_b32 s41, s18, 6
	s_and_b32 s42, s12, 0x60
	s_lshl_b32 s12, s56, 8
	v_and_b32_e32 v154, 15, v2
	s_add_i32 s12, s12, s41
	v_bfe_u32 v153, v2, 4, 2
	v_or_b32_e32 v2, s12, v154
	v_add_lshl_u32 v140, v4, v3, 1
	v_ashrrev_i32_e32 v3, 31, v2
	v_lshlrev_b64 v[2:3], 12, v[2:3]
	s_lshl_b32 s14, s55, 8
	v_lshl_add_u64 v[2:3], v[132:133], 0, v[2:3]
	s_ashr_i32 s15, s14, 31
	v_lshl_add_u64 v[2:3], s[14:15], 1, v[2:3]
	s_lshl_b32 s12, s42, 1
	v_lshl_add_u64 v[2:3], v[2:3], 0, s[12:13]
	v_lshlrev_b32_e32 v180, 4, v153
	v_lshl_add_u64 v[2:3], v[2:3], 0, v[180:181]
	s_mov_b32 s14, 0x10000
	v_add_co_u32_e32 v4, vcc, s14, v2
	s_mov_b32 s14, 0x20000
	s_nop 0
	v_addc_co_u32_e32 v5, vcc, 0, v3, vcc
	global_load_dwordx4 v[64:67], v[2:3], off
	global_load_dwordx4 v[60:63], v[2:3], off offset:256
	global_load_dwordx4 v[56:59], v[4:5], off
	global_load_dwordx4 v[52:55], v[4:5], off offset:256
	v_add_co_u32_e32 v4, vcc, s14, v2
	s_mov_b32 s14, 0x30000
	s_nop 0
	v_addc_co_u32_e32 v5, vcc, 0, v3, vcc
	global_load_dwordx4 v[48:51], v[4:5], off
	global_load_dwordx4 v[44:47], v[4:5], off offset:256
	v_add_co_u32_e32 v4, vcc, s14, v2
	s_mov_b32 s14, 0x80000
	s_nop 0
	v_addc_co_u32_e32 v5, vcc, 0, v3, vcc
	global_load_dwordx4 v[40:43], v[4:5], off
	global_load_dwordx4 v[36:39], v[4:5], off offset:256
	v_add_co_u32_e32 v4, vcc, s14, v2
	s_mov_b32 s14, 0x90000
	s_nop 0
	v_addc_co_u32_e32 v5, vcc, 0, v3, vcc
	global_load_dwordx4 v[32:35], v[4:5], off
	global_load_dwordx4 v[28:31], v[4:5], off offset:256
	v_add_co_u32_e32 v4, vcc, s14, v2
	s_mov_b32 s14, 0xa0000
	s_nop 0
	v_addc_co_u32_e32 v5, vcc, 0, v3, vcc
	global_load_dwordx4 v[24:27], v[4:5], off
	global_load_dwordx4 v[18:21], v[4:5], off offset:256
	v_add_co_u32_e32 v4, vcc, s14, v2
	s_mov_b32 s14, 0xb0000
	s_nop 0
	v_addc_co_u32_e32 v5, vcc, 0, v3, vcc
	s_mul_i32 s15, s55, 0x2b0000
	v_add_co_u32_e32 v14, vcc, s14, v2
	s_mul_hi_i32 s14, s55, 0x2b0000
	s_add_u32 s28, s8, s15
	s_addc_u32 s29, s9, s14
	s_add_i32 s43, s40, 0
	v_addc_co_u32_e32 v15, vcc, 0, v3, vcc
	s_add_i32 m0, s43, 0x10000
	global_load_dwordx4 v[10:13], v[4:5], off
	global_load_dwordx4 v[6:9], v[4:5], off offset:256
	s_nop 0
	global_load_dwordx4 v[2:5], v[14:15], off
	s_nop 0
	global_load_dwordx4 v[14:17], v[14:15], off offset:256
	s_mul_i32 s23, s56, 0x2b0000
	v_and_b32_e32 v161, 63, v0
	v_lshrrev_b32_e32 v162, 3, v161
	v_and_b32_e32 v161, 7, v161
	v_xor_b32_e32 v161, v161, v162
	v_lshlrev_b32_e32 v161, 4, v161
	v_lshrrev_b32_e32 v163, 6, v0
	v_lshl_add_u32 v162, v163, 3, v162
	v_mov_b32_e32 v163, 0x2b00
	v_mad_u32_u24 v134, v162, v163, v161
	v_add_u32_e32 v138, 0xac000, v134
	v_and_b32_e32 v164, 15, v162
	v_lshrrev_b32_e32 v163, 2, v164
	v_and_b32_e32 v164, 3, v164
	v_lshl_add_u32 v164, v163, 3, v164
	v_bfe_u32 v163, v162, 4, 1
	v_lshl_add_u32 v164, v163, 2, v164
	v_and_b32_e32 v163, 0x60, v162
	v_or_b32_e32 v164, v163, v164
	v_mov_b32_e32 v163, 0x2b00
	v_mad_u32_u24 v136, v164, v163, v161
	v_add_u32_e32 v140, 0xac000, v136
	global_load_lds_dwordx4 v136, s[28:29]
	s_add_i32 m0, s43, 0x12000
	s_add_u32 s14, s28, 0x158000
	global_load_lds_dwordx4 v140, s[28:29]
	s_addc_u32 s15, s29, 0
	s_add_i32 m0, s43, 0x14000
	s_mul_hi_i32 s19, s56, 0x2b0000
	global_load_lds_dwordx4 v136, s[14:15]
	s_add_i32 m0, s43, 0x16000
	s_add_u32 s26, s6, s23
	s_addc_u32 s27, s7, s19
	s_add_i32 s44, s43, 0x2000
	global_load_lds_dwordx4 v140, s[14:15]
	s_mov_b32 m0, s43
	s_add_u32 s14, s26, 0x158000
	global_load_lds_dwordx4 v134, s[26:27]
	s_mov_b32 m0, s44
	s_addc_u32 s15, s27, 0
	s_add_i32 s45, s43, 0x4000
	global_load_lds_dwordx4 v138, s[26:27]
	s_mov_b32 m0, s45
	s_add_i32 s47, s43, 0x6000
	global_load_lds_dwordx4 v134, s[14:15]
	s_mov_b32 m0, s47
	v_mov_b32_e32 v137, v181
	global_load_lds_dwordx4 v138, s[14:15]
	v_mov_b32_e32 v141, v181
	v_mov_b32_e32 v135, v181
	v_mov_b32_e32 v139, v181
	s_cmp_eq_u32 s18, 1
	v_lshl_add_u64 v[146:147], s[28:29], 0, v[136:137]
	v_lshl_add_u64 v[144:145], s[28:29], 0, v[140:141]
	v_lshl_add_u64 v[68:69], s[26:27], 0, v[134:135]
	s_cselect_b64 s[14:15], -1, 0
	s_cmp_lg_u32 s18, 1
	v_lshl_add_u64 v[142:143], s[26:27], 0, v[138:139]
	s_cbranch_scc1 .LBB0_2227
	s_barrier
.LBB0_2227:
	s_waitcnt vmcnt(0)
	v_lshlrev_b32_e32 v90, 16, v48
	v_and_b32_e32 v91, 0xffff0000, v48
	v_lshlrev_b32_e32 v92, 16, v49
	v_and_b32_e32 v93, 0xffff0000, v49
	v_lshlrev_b32_e32 v94, 16, v46
	v_and_b32_e32 v95, 0xffff0000, v46
	v_lshlrev_b32_e32 v96, 16, v47
	v_and_b32_e32 v97, 0xffff0000, v47
	v_lshlrev_b32_e32 v46, 16, v28
	v_and_b32_e32 v47, 0xffff0000, v28
	v_lshlrev_b32_e32 v48, 16, v29
	v_and_b32_e32 v49, 0xffff0000, v29
	s_add_i32 m0, s43, 0x18000
	v_lshl_add_u64 v[28:29], v[146:147], 0, s[16:17]
	s_lshl_b32 s23, s18, 13
	s_lshl_b32 s24, s42, 7
	s_waitcnt vmcnt(2)
	s_barrier
	global_load_lds_dwordx4 v[28:29], off
	v_lshl_add_u64 v[28:29], v[144:145], 0, s[16:17]
	s_add_i32 m0, s43, 0x1a000
	s_add_i32 s48, s43, 0x8000
	s_add_i32 s49, s43, 0xa000
	global_load_lds_dwordx4 v[28:29], off
	v_lshl_add_u64 v[28:29], v[68:69], 0, s[16:17]
	s_mov_b32 m0, s48
	s_add_u32 s18, s28, 0x158080
	global_load_lds_dwordx4 v[28:29], off
	v_lshl_add_u64 v[28:29], v[142:143], 0, s[16:17]
	s_mov_b32 m0, s49
	s_addc_u32 s19, s29, 0
	global_load_lds_dwordx4 v[28:29], off
	s_add_i32 m0, s43, 0x1c000
	v_lshl_add_u64 v[28:29], s[18:19], 0, v[136:137]
	global_load_lds_dwordx4 v[28:29], off
	v_lshl_add_u64 v[28:29], s[18:19], 0, v[140:141]
	s_add_i32 m0, s43, 0x1e000
	v_readlane_b32 s18, v255, 43
	global_load_lds_dwordx4 v[28:29], off
	s_mulk_i32 s18, 0x4200
	s_mov_b32 s19, s13
	v_lshl_add_u64 v[142:143], s[18:19], 3, v[130:131]
	s_mov_b64 s[18:19], 0x31000
	v_or_b32_e32 v155, s41, v154
	v_lshl_add_u64 v[142:143], v[142:143], 0, s[18:19]
	v_lshlrev_b32_e32 v144, 6, v155
	s_movk_i32 s18, 0x3c0
	v_lshlrev_b32_e32 v145, 2, v155
	v_and_or_b32 v144, v144, s18, v180
	v_and_b32_e32 v145, 32, v145
	v_bitop3_b32 v162, v144, s23, v145 bitop3:0xde
	v_lshlrev_b32_e32 v145, 2, v154
	v_lshl_or_b32 v144, v154, 6, v180
	v_and_b32_e32 v145, 32, v145
	v_bitop3_b32 v156, v144, s24, v145 bitop3:0xde
	s_movk_i32 s24, 0x1580
	v_lshrrev_b32_e32 v145, 1, v148
	v_mul_lo_u32 v144, v150, s24
	s_mov_b32 s25, 0x15800
	s_cmpk_lt_u32 s22, 0x100
	v_mad_u64_u32 v[144:145], s[22:23], v145, s25, v[144:145]
	v_lshrrev_b32_e32 v147, 1, v157
	v_mul_lo_u32 v146, v159, s24
	v_or_b32_e32 v144, v144, v149
	v_mad_u64_u32 v[146:147], s[22:23], v147, s25, v[146:147]
	s_waitcnt vmcnt(6)
	v_add_lshl_u32 v180, v144, v151, 1
	s_mov_b64 s[30:31], 0x158080
	v_or_b32_e32 v146, v146, v158
	v_lshlrev_b32_e32 v161, 3, v153
	v_mov_b32_e32 v144, v134
	v_mov_b32_e32 v145, 0
	v_lshl_add_u64 v[144:145], v[144:145], 0, s[30:31]
	v_add_lshl_u32 v180, v146, v160, 1
	v_lshlrev_b32_e32 v126, 16, v64
	v_and_b32_e32 v127, 0xffff0000, v64
	v_lshlrev_b32_e32 v128, 16, v65
	v_and_b32_e32 v129, 0xffff0000, v65
	v_lshlrev_b32_e32 v114, 16, v66
	v_and_b32_e32 v115, 0xffff0000, v66
	v_lshlrev_b32_e32 v116, 16, v67
	v_and_b32_e32 v117, 0xffff0000, v67
	v_lshlrev_b32_e32 v118, 16, v60
	v_and_b32_e32 v119, 0xffff0000, v60
	v_lshlrev_b32_e32 v120, 16, v61
	v_and_b32_e32 v121, 0xffff0000, v61
	v_lshlrev_b32_e32 v122, 16, v62
	v_and_b32_e32 v123, 0xffff0000, v62
	v_lshlrev_b32_e32 v124, 16, v63
	v_and_b32_e32 v125, 0xffff0000, v63
	v_lshlrev_b32_e32 v106, 16, v56
	v_and_b32_e32 v107, 0xffff0000, v56
	v_lshlrev_b32_e32 v108, 16, v57
	v_and_b32_e32 v109, 0xffff0000, v57
	v_lshlrev_b32_e32 v98, 16, v58
	v_and_b32_e32 v99, 0xffff0000, v58
	v_lshlrev_b32_e32 v100, 16, v59
	v_and_b32_e32 v101, 0xffff0000, v59
	v_lshlrev_b32_e32 v102, 16, v52
	v_and_b32_e32 v103, 0xffff0000, v52
	v_lshlrev_b32_e32 v104, 16, v53
	v_and_b32_e32 v105, 0xffff0000, v53
	v_lshlrev_b32_e32 v110, 16, v54
	v_and_b32_e32 v111, 0xffff0000, v54
	v_lshlrev_b32_e32 v112, 16, v55
	v_and_b32_e32 v113, 0xffff0000, v55
	v_lshlrev_b32_e32 v82, 16, v50
	v_and_b32_e32 v83, 0xffff0000, v50
	v_lshlrev_b32_e32 v84, 16, v51
	v_and_b32_e32 v85, 0xffff0000, v51
	v_lshlrev_b32_e32 v86, 16, v44
	v_and_b32_e32 v87, 0xffff0000, v44
	v_lshlrev_b32_e32 v88, 16, v45
	v_and_b32_e32 v89, 0xffff0000, v45
	v_lshlrev_b32_e32 v74, 16, v40
	v_and_b32_e32 v75, 0xffff0000, v40
	v_lshlrev_b32_e32 v76, 16, v41
	v_and_b32_e32 v77, 0xffff0000, v41
	v_lshlrev_b32_e32 v54, 16, v42
	v_and_b32_e32 v55, 0xffff0000, v42
	v_lshlrev_b32_e32 v56, 16, v43
	v_and_b32_e32 v57, 0xffff0000, v43
	v_lshlrev_b32_e32 v70, 16, v36
	v_and_b32_e32 v71, 0xffff0000, v36
	v_lshlrev_b32_e32 v72, 16, v37
	v_and_b32_e32 v73, 0xffff0000, v37
	v_lshlrev_b32_e32 v78, 16, v38
	v_and_b32_e32 v79, 0xffff0000, v38
	v_lshlrev_b32_e32 v80, 16, v39
	v_and_b32_e32 v81, 0xffff0000, v39
	v_lshlrev_b32_e32 v50, 16, v32
	v_and_b32_e32 v51, 0xffff0000, v32
	v_lshlrev_b32_e32 v52, 16, v33
	v_and_b32_e32 v53, 0xffff0000, v33
	v_lshlrev_b32_e32 v38, 16, v34
	v_and_b32_e32 v39, 0xffff0000, v34
	v_lshlrev_b32_e32 v40, 16, v35
	v_and_b32_e32 v41, 0xffff0000, v35
	v_lshlrev_b32_e32 v58, 16, v30
	v_and_b32_e32 v59, 0xffff0000, v30
	v_lshlrev_b32_e32 v60, 16, v31
	v_and_b32_e32 v61, 0xffff0000, v31
	v_lshlrev_b32_e32 v22, 16, v24
	v_and_b32_e32 v23, 0xffff0000, v24
	v_lshlrev_b32_e32 v24, 16, v25
	v_and_b32_e32 v25, 0xffff0000, v25
	v_lshlrev_b32_e32 v42, 16, v26
	v_and_b32_e32 v43, 0xffff0000, v26
	v_lshlrev_b32_e32 v44, 16, v27
	v_and_b32_e32 v45, 0xffff0000, v27
	v_lshlrev_b32_e32 v62, 16, v18
	v_and_b32_e32 v63, 0xffff0000, v18
	v_lshlrev_b32_e32 v64, 16, v19
	v_and_b32_e32 v65, 0xffff0000, v19
	v_lshlrev_b32_e32 v66, 16, v20
	v_and_b32_e32 v67, 0xffff0000, v20
	v_lshlrev_b32_e32 v68, 16, v21
	v_and_b32_e32 v69, 0xffff0000, v21
	v_lshlrev_b32_e32 v30, 16, v10
	v_and_b32_e32 v31, 0xffff0000, v10
	v_lshlrev_b32_e32 v32, 16, v11
	v_and_b32_e32 v33, 0xffff0000, v11
	v_lshlrev_b32_e32 v18, 16, v12
	v_and_b32_e32 v19, 0xffff0000, v12
	v_lshlrev_b32_e32 v20, 16, v13
	v_and_b32_e32 v21, 0xffff0000, v13
	v_lshlrev_b32_e32 v26, 16, v6
	v_and_b32_e32 v27, 0xffff0000, v6
	v_lshlrev_b32_e32 v28, 16, v7
	v_and_b32_e32 v29, 0xffff0000, v7
	v_lshlrev_b32_e32 v34, 16, v8
	v_and_b32_e32 v35, 0xffff0000, v8
	v_lshlrev_b32_e32 v36, 16, v9
	v_and_b32_e32 v37, 0xffff0000, v9
	v_lshlrev_b32_e32 v10, 16, v2
	v_and_b32_e32 v11, 0xffff0000, v2
	v_lshlrev_b32_e32 v12, 16, v3
	v_and_b32_e32 v13, 0xffff0000, v3
	v_lshlrev_b32_e32 v2, 16, v4
	v_and_b32_e32 v3, 0xffff0000, v4
	v_lshlrev_b32_e32 v4, 16, v5
	v_and_b32_e32 v5, 0xffff0000, v5
	v_lshlrev_b32_e32 v6, 16, v14
	v_and_b32_e32 v7, 0xffff0000, v14
	v_lshlrev_b32_e32 v8, 16, v15
	v_and_b32_e32 v9, 0xffff0000, v15
	v_lshlrev_b32_e32 v14, 16, v16
	v_and_b32_e32 v15, 0xffff0000, v16
	v_lshlrev_b32_e32 v16, 16, v17
	v_and_b32_e32 v17, 0xffff0000, v17
	s_cselect_b64 s[18:19], -1, 0
	v_mov_b32_e32 v146, v138
	v_mov_b32_e32 v147, 0
	v_lshl_add_u64 v[146:147], v[146:147], 0, s[30:31]
	s_mov_b32 s50, 0
	v_add_u32_e32 v157, 0, v162
	v_lshlrev_b32_e32 v180, 1, v161
	v_and_b32_e32 v148, 7, v0
	v_bfe_u32 v149, v0, 4, 2
	v_xor_b32_e32 v149, v149, v148
	v_lshlrev_b32_e32 v149, 4, v149
	v_lshl_add_u32 v149, v148, 7, v149
	v_bfe_u32 v148, v0, 3, 1
	v_lshl_add_u32 v149, v148, 10, v149
	v_lshrrev_b32_e32 v148, 8, v0
	v_lshl_add_u32 v157, v148, 13, v149
	v_bfe_u32 v148, v0, 6, 2
	v_lshl_add_u32 v156, v148, 12, v149
	s_barrier
	s_branch .LBB0_2230

.LBB0_2241:
	s_add_u32 s28, s26, 0x100
	s_addc_u32 s29, s27, 0
	s_add_i32 s58, 0, 0x10000
	s_cmpk_eq_i32 s57, 0x52
	s_cselect_b32 s35, s23, s29
	s_cselect_b32 s34, s22, s28
	s_cselect_b32 s31, s25, s39
	s_cselect_b32 s30, s24, s38
	s_add_i32 s59, 0, 0x14000
	v_add_u32_e32 v166, s58, v156
	v_add_u32_e32 v178, s59, v156
	ds_read_b128 v[148:151], v166
	ds_read_b128 v[162:165], v166 offset:2048
	v_xor_b32_e32 v166, 64, v166
	ds_read_b128 v[158:161], v166
	ds_read_b128 v[166:169], v166 offset:2048
	ds_read_b128 v[170:173], v178
	ds_read_b128 v[190:193], v178 offset:2048
	v_xor_b32_e32 v178, 64, v178
	ds_read_b128 v[174:177], v178
	ds_read_b128 v[194:197], v178 offset:2048
	v_lshl_add_u64 v[178:179], s[26:27], 0, v[144:145]
	s_add_i32 m0, s43, 0xc000
	ds_read_b128 v[198:201], v157
	ds_read_b128 v[206:209], v157 offset:2048
	ds_read_b128 v[214:217], v157 offset:4096
	ds_read_b128 v[238:241], v157 offset:6144
	v_xor_b32_e32 v242, 64, v157
	ds_read_b128 v[202:205], v242
	ds_read_b128 v[210:213], v242 offset:2048
	ds_read_b128 v[218:221], v242 offset:4096
	ds_read_b128 v[242:245], v242 offset:6144
	global_load_lds_dwordx4 v[178:179], off
	v_lshl_add_u64 v[178:179], s[26:27], 0, v[146:147]
	s_add_i32 m0, s43, 0xe000
	s_nop 0
	global_load_lds_dwordx4 v[178:179], off
	s_waitcnt vmcnt(8)
	s_waitcnt lgkmcnt(0)
	s_setprio 1
	s_barrier
	v_mfma_f32_16x16x32_bf16 v[126:129], v[148:151], v[198:201], v[126:129]
	v_mfma_f32_16x16x32_bf16 v[114:117], v[162:165], v[198:201], v[114:117]
	v_mfma_f32_16x16x32_bf16 v[98:101], v[162:165], v[206:209], v[98:101]
	v_mfma_f32_16x16x32_bf16 v[106:109], v[148:151], v[206:209], v[106:109]
	v_mfma_f32_16x16x32_bf16 v[90:93], v[148:151], v[214:217], v[90:93]
	v_mfma_f32_16x16x32_bf16 v[82:85], v[162:165], v[214:217], v[82:85]
	v_mfma_f32_16x16x32_bf16 v[54:57], v[162:165], v[238:241], v[54:57]
	v_mfma_f32_16x16x32_bf16 v[74:77], v[148:151], v[238:241], v[74:77]
	v_mfma_f32_16x16x32_bf16 v[126:129], v[158:161], v[202:205], v[126:129]
	v_mfma_f32_16x16x32_bf16 v[114:117], v[166:169], v[202:205], v[114:117]
	v_mfma_f32_16x16x32_bf16 v[98:101], v[166:169], v[210:213], v[98:101]
	v_mfma_f32_16x16x32_bf16 v[106:109], v[158:161], v[210:213], v[106:109]
	v_mfma_f32_16x16x32_bf16 v[90:93], v[158:161], v[218:221], v[90:93]
	v_mfma_f32_16x16x32_bf16 v[82:85], v[166:169], v[218:221], v[82:85]
	v_mfma_f32_16x16x32_bf16 v[54:57], v[166:169], v[242:245], v[54:57]
	v_mfma_f32_16x16x32_bf16 v[74:77], v[158:161], v[242:245], v[74:77]
	v_mfma_f32_16x16x32_bf16 v[118:121], v[170:173], v[198:201], v[118:121]
	v_mfma_f32_16x16x32_bf16 v[122:125], v[190:193], v[198:201], v[122:125]
	v_mfma_f32_16x16x32_bf16 v[110:113], v[190:193], v[206:209], v[110:113]
	v_mfma_f32_16x16x32_bf16 v[102:105], v[170:173], v[206:209], v[102:105]
	v_mfma_f32_16x16x32_bf16 v[86:89], v[170:173], v[214:217], v[86:89]
	v_mfma_f32_16x16x32_bf16 v[94:97], v[190:193], v[214:217], v[94:97]
	v_mfma_f32_16x16x32_bf16 v[78:81], v[190:193], v[238:241], v[78:81]
	v_mfma_f32_16x16x32_bf16 v[70:73], v[170:173], v[238:241], v[70:73]
	v_mfma_f32_16x16x32_bf16 v[118:121], v[174:177], v[202:205], v[118:121]
	v_mfma_f32_16x16x32_bf16 v[122:125], v[194:197], v[202:205], v[122:125]
	v_mfma_f32_16x16x32_bf16 v[110:113], v[194:197], v[210:213], v[110:113]
	v_mfma_f32_16x16x32_bf16 v[102:105], v[174:177], v[210:213], v[102:105]
	v_mfma_f32_16x16x32_bf16 v[86:89], v[174:177], v[218:221], v[86:89]
	v_mfma_f32_16x16x32_bf16 v[94:97], v[194:197], v[218:221], v[94:97]
	v_mfma_f32_16x16x32_bf16 v[78:81], v[194:197], v[242:245], v[78:81]
	v_mfma_f32_16x16x32_bf16 v[70:73], v[174:177], v[242:245], v[70:73]
	s_barrier
	s_setprio 0
	s_add_i32 s26, s58, s40
	v_lshl_add_u64 v[178:179], s[30:31], 0, v[136:137]
	s_mov_b32 m0, s26
	ds_read_b128 v[198:201], v157 offset:16384
	ds_read_b128 v[206:209], v157 offset:18432
	ds_read_b128 v[214:217], v157 offset:20480
	ds_read_b128 v[238:241], v157 offset:22528
	v_xor_b32_e32 v242, 64, v157
	ds_read_b128 v[202:205], v242 offset:16384
	ds_read_b128 v[210:213], v242 offset:18432
	ds_read_b128 v[218:221], v242 offset:20480
	ds_read_b128 v[242:245], v242 offset:22528
	global_load_lds_dwordx4 v[178:179], off
	s_add_i32 m0, s26, 0x2000
	s_add_u32 s26, s30, 0x158000
	v_lshl_add_u64 v[222:223], s[30:31], 0, v[140:141]
	s_addc_u32 s27, s31, 0
	s_add_i32 s58, s59, s40
	global_load_lds_dwordx4 v[222:223], off
	v_lshl_add_u64 v[246:247], s[26:27], 0, v[136:137]
	s_mov_b32 m0, s58
	v_lshl_add_u64 v[248:249], s[34:35], 0, v[138:139]
	global_load_lds_dwordx4 v[246:247], off
	v_lshl_add_u64 v[246:247], s[26:27], 0, v[140:141]
	s_add_i32 m0, s58, 0x2000
	s_nop 0
	global_load_lds_dwordx4 v[246:247], off
	v_lshl_add_u64 v[246:247], s[34:35], 0, v[134:135]
	s_mov_b32 m0, s43
	s_nop 0
	global_load_lds_dwordx4 v[246:247], off
	s_mov_b32 m0, s44
	s_nop 0
	global_load_lds_dwordx4 v[248:249], off
	s_waitcnt vmcnt(8)
	s_waitcnt lgkmcnt(0)
	s_setprio 1
	s_barrier
	v_mfma_f32_16x16x32_bf16 v[50:53], v[148:151], v[198:201], v[50:53]
	v_mfma_f32_16x16x32_bf16 v[38:41], v[162:165], v[198:201], v[38:41]
	v_mfma_f32_16x16x32_bf16 v[42:45], v[162:165], v[206:209], v[42:45]
	v_mfma_f32_16x16x32_bf16 v[22:25], v[148:151], v[206:209], v[22:25]
	v_mfma_f32_16x16x32_bf16 v[30:33], v[148:151], v[214:217], v[30:33]
	v_mfma_f32_16x16x32_bf16 v[18:21], v[162:165], v[214:217], v[18:21]
	v_mfma_f32_16x16x32_bf16 v[2:5], v[162:165], v[238:241], v[2:5]
	v_mfma_f32_16x16x32_bf16 v[10:13], v[148:151], v[238:241], v[10:13]
	v_mfma_f32_16x16x32_bf16 v[50:53], v[158:161], v[202:205], v[50:53]
	v_mfma_f32_16x16x32_bf16 v[38:41], v[166:169], v[202:205], v[38:41]
	v_mfma_f32_16x16x32_bf16 v[42:45], v[166:169], v[210:213], v[42:45]
	v_mfma_f32_16x16x32_bf16 v[22:25], v[158:161], v[210:213], v[22:25]
	v_mfma_f32_16x16x32_bf16 v[30:33], v[158:161], v[218:221], v[30:33]
	v_mfma_f32_16x16x32_bf16 v[18:21], v[166:169], v[218:221], v[18:21]
	v_mfma_f32_16x16x32_bf16 v[2:5], v[166:169], v[242:245], v[2:5]
	v_mfma_f32_16x16x32_bf16 v[10:13], v[158:161], v[242:245], v[10:13]
	v_mfma_f32_16x16x32_bf16 v[46:49], v[170:173], v[198:201], v[46:49]
	v_mfma_f32_16x16x32_bf16 v[58:61], v[190:193], v[198:201], v[58:61]
	v_mfma_f32_16x16x32_bf16 v[66:69], v[190:193], v[206:209], v[66:69]
	v_mfma_f32_16x16x32_bf16 v[62:65], v[170:173], v[206:209], v[62:65]
	v_mfma_f32_16x16x32_bf16 v[26:29], v[170:173], v[214:217], v[26:29]
	v_mfma_f32_16x16x32_bf16 v[34:37], v[190:193], v[214:217], v[34:37]
	v_mfma_f32_16x16x32_bf16 v[14:17], v[190:193], v[238:241], v[14:17]
	v_mfma_f32_16x16x32_bf16 v[6:9], v[170:173], v[238:241], v[6:9]
	v_mfma_f32_16x16x32_bf16 v[46:49], v[174:177], v[202:205], v[46:49]
	v_mfma_f32_16x16x32_bf16 v[58:61], v[194:197], v[202:205], v[58:61]
	v_mfma_f32_16x16x32_bf16 v[66:69], v[194:197], v[210:213], v[66:69]
	v_mfma_f32_16x16x32_bf16 v[62:65], v[174:177], v[210:213], v[62:65]
	v_mfma_f32_16x16x32_bf16 v[26:29], v[174:177], v[218:221], v[26:29]
	v_mfma_f32_16x16x32_bf16 v[34:37], v[194:197], v[218:221], v[34:37]
	v_mfma_f32_16x16x32_bf16 v[14:17], v[194:197], v[242:245], v[14:17]
	v_mfma_f32_16x16x32_bf16 v[6:9], v[174:177], v[242:245], v[6:9]
	s_barrier
	s_setprio 0
	s_add_i32 s58, 0, 0x18000
	s_add_i32 s59, 0, 0x1c000
	v_add_u32_e32 v166, s58, v156
	v_add_u32_e32 v194, s59, v156
	ds_read_b128 v[148:151], v166
	ds_read_b128 v[162:165], v166 offset:2048
	v_xor_b32_e32 v166, 64, v166
	ds_read_b128 v[158:161], v166
	ds_read_b128 v[166:169], v166 offset:2048
	ds_read_b128 v[170:173], v194
	ds_read_b128 v[190:193], v194 offset:2048
	v_xor_b32_e32 v194, 64, v194
	ds_read_b128 v[174:177], v194
	ds_read_b128 v[194:197], v194 offset:2048
	s_add_u32 s26, s34, 0x158000
	s_addc_u32 s27, s35, 0
	s_mov_b32 m0, s45
	v_lshl_add_u64 v[250:251], s[26:27], 0, v[134:135]
	ds_read_b128 v[198:201], v157 offset:32768
	ds_read_b128 v[206:209], v157 offset:34816
	ds_read_b128 v[214:217], v157 offset:36864
	ds_read_b128 v[238:241], v157 offset:38912
	v_xor_b32_e32 v242, 64, v157
	ds_read_b128 v[202:205], v242 offset:32768
	ds_read_b128 v[210:213], v242 offset:34816
	ds_read_b128 v[218:221], v242 offset:36864
	ds_read_b128 v[242:245], v242 offset:38912
	global_load_lds_dwordx4 v[250:251], off
	v_lshl_add_u64 v[250:251], s[26:27], 0, v[138:139]
	s_mov_b32 m0, s47
	s_nop 0
	global_load_lds_dwordx4 v[250:251], off
	s_waitcnt vmcnt(8)
	s_waitcnt lgkmcnt(0)
	s_setprio 1
	s_barrier
	v_mfma_f32_16x16x32_bf16 v[126:129], v[148:151], v[198:201], v[126:129]
	v_mfma_f32_16x16x32_bf16 v[114:117], v[162:165], v[198:201], v[114:117]
	v_mfma_f32_16x16x32_bf16 v[98:101], v[162:165], v[206:209], v[98:101]
	v_mfma_f32_16x16x32_bf16 v[106:109], v[148:151], v[206:209], v[106:109]
	v_mfma_f32_16x16x32_bf16 v[90:93], v[148:151], v[214:217], v[90:93]
	v_mfma_f32_16x16x32_bf16 v[82:85], v[162:165], v[214:217], v[82:85]
	v_mfma_f32_16x16x32_bf16 v[54:57], v[162:165], v[238:241], v[54:57]
	v_mfma_f32_16x16x32_bf16 v[74:77], v[148:151], v[238:241], v[74:77]
	v_mfma_f32_16x16x32_bf16 v[126:129], v[158:161], v[202:205], v[126:129]
	v_mfma_f32_16x16x32_bf16 v[114:117], v[166:169], v[202:205], v[114:117]
	v_mfma_f32_16x16x32_bf16 v[98:101], v[166:169], v[210:213], v[98:101]
	v_mfma_f32_16x16x32_bf16 v[106:109], v[158:161], v[210:213], v[106:109]
	v_mfma_f32_16x16x32_bf16 v[90:93], v[158:161], v[218:221], v[90:93]
	v_mfma_f32_16x16x32_bf16 v[82:85], v[166:169], v[218:221], v[82:85]
	v_mfma_f32_16x16x32_bf16 v[54:57], v[166:169], v[242:245], v[54:57]
	v_mfma_f32_16x16x32_bf16 v[74:77], v[158:161], v[242:245], v[74:77]
	v_mfma_f32_16x16x32_bf16 v[118:121], v[170:173], v[198:201], v[118:121]
	v_mfma_f32_16x16x32_bf16 v[122:125], v[190:193], v[198:201], v[122:125]
	v_mfma_f32_16x16x32_bf16 v[110:113], v[190:193], v[206:209], v[110:113]
	v_mfma_f32_16x16x32_bf16 v[102:105], v[170:173], v[206:209], v[102:105]
	v_mfma_f32_16x16x32_bf16 v[86:89], v[170:173], v[214:217], v[86:89]
	v_mfma_f32_16x16x32_bf16 v[94:97], v[190:193], v[214:217], v[94:97]
	v_mfma_f32_16x16x32_bf16 v[78:81], v[190:193], v[238:241], v[78:81]
	v_mfma_f32_16x16x32_bf16 v[70:73], v[170:173], v[238:241], v[70:73]
	v_mfma_f32_16x16x32_bf16 v[118:121], v[174:177], v[202:205], v[118:121]
	v_mfma_f32_16x16x32_bf16 v[122:125], v[194:197], v[202:205], v[122:125]
	v_mfma_f32_16x16x32_bf16 v[110:113], v[194:197], v[210:213], v[110:113]
	v_mfma_f32_16x16x32_bf16 v[102:105], v[174:177], v[210:213], v[102:105]
	v_mfma_f32_16x16x32_bf16 v[86:89], v[174:177], v[218:221], v[86:89]
	v_mfma_f32_16x16x32_bf16 v[94:97], v[194:197], v[218:221], v[94:97]
	v_mfma_f32_16x16x32_bf16 v[78:81], v[194:197], v[242:245], v[78:81]
	v_mfma_f32_16x16x32_bf16 v[70:73], v[174:177], v[242:245], v[70:73]
	s_barrier
	s_setprio 0
	s_add_i32 s26, s58, s40
	v_lshl_add_u64 v[178:179], v[178:179], 0, s[16:17]
	s_mov_b32 m0, s26
	ds_read_b128 v[198:201], v157 offset:49152
	ds_read_b128 v[206:209], v157 offset:51200
	ds_read_b128 v[214:217], v157 offset:53248
	ds_read_b128 v[238:241], v157 offset:55296
	v_xor_b32_e32 v242, 64, v157
	ds_read_b128 v[202:205], v242 offset:49152
	ds_read_b128 v[210:213], v242 offset:51200
	ds_read_b128 v[218:221], v242 offset:53248
	ds_read_b128 v[242:245], v242 offset:55296
	global_load_lds_dwordx4 v[178:179], off
	s_add_i32 m0, s26, 0x2000
	s_add_u32 s26, s30, 0x158080
	v_lshl_add_u64 v[178:179], v[222:223], 0, s[16:17]
	s_addc_u32 s27, s31, 0
	s_add_i32 s30, s59, s40
	global_load_lds_dwordx4 v[178:179], off
	v_lshl_add_u64 v[178:179], s[26:27], 0, v[136:137]
	s_mov_b32 m0, s30
	s_nop 0
	global_load_lds_dwordx4 v[178:179], off
	v_lshl_add_u64 v[178:179], s[26:27], 0, v[140:141]
	s_add_i32 m0, s30, 0x2000
	s_nop 0
	global_load_lds_dwordx4 v[178:179], off
	v_lshl_add_u64 v[178:179], v[246:247], 0, s[16:17]
	s_mov_b32 m0, s48
	s_nop 0
	global_load_lds_dwordx4 v[178:179], off
	v_lshl_add_u64 v[178:179], v[248:249], 0, s[16:17]
	s_mov_b32 m0, s49
	s_nop 0
	global_load_lds_dwordx4 v[178:179], off
	s_waitcnt vmcnt(8)
	s_waitcnt lgkmcnt(0)
	s_setprio 1
	s_barrier
	v_mfma_f32_16x16x32_bf16 v[50:53], v[148:151], v[198:201], v[50:53]
	v_mfma_f32_16x16x32_bf16 v[38:41], v[162:165], v[198:201], v[38:41]
	v_mfma_f32_16x16x32_bf16 v[42:45], v[162:165], v[206:209], v[42:45]
	v_mfma_f32_16x16x32_bf16 v[22:25], v[148:151], v[206:209], v[22:25]
	v_mfma_f32_16x16x32_bf16 v[30:33], v[148:151], v[214:217], v[30:33]
	v_mfma_f32_16x16x32_bf16 v[18:21], v[162:165], v[214:217], v[18:21]
	v_mfma_f32_16x16x32_bf16 v[2:5], v[162:165], v[238:241], v[2:5]
	v_mfma_f32_16x16x32_bf16 v[10:13], v[148:151], v[238:241], v[10:13]
	v_mfma_f32_16x16x32_bf16 v[50:53], v[158:161], v[202:205], v[50:53]
	v_mfma_f32_16x16x32_bf16 v[38:41], v[166:169], v[202:205], v[38:41]
	v_mfma_f32_16x16x32_bf16 v[42:45], v[166:169], v[210:213], v[42:45]
	v_mfma_f32_16x16x32_bf16 v[22:25], v[158:161], v[210:213], v[22:25]
	v_mfma_f32_16x16x32_bf16 v[30:33], v[158:161], v[218:221], v[30:33]
	v_mfma_f32_16x16x32_bf16 v[18:21], v[166:169], v[218:221], v[18:21]
	v_mfma_f32_16x16x32_bf16 v[2:5], v[166:169], v[242:245], v[2:5]
	v_mfma_f32_16x16x32_bf16 v[10:13], v[158:161], v[242:245], v[10:13]
	v_mfma_f32_16x16x32_bf16 v[46:49], v[170:173], v[198:201], v[46:49]
	v_mfma_f32_16x16x32_bf16 v[58:61], v[190:193], v[198:201], v[58:61]
	v_mfma_f32_16x16x32_bf16 v[66:69], v[190:193], v[206:209], v[66:69]
	v_mfma_f32_16x16x32_bf16 v[62:65], v[170:173], v[206:209], v[62:65]
	v_mfma_f32_16x16x32_bf16 v[26:29], v[170:173], v[214:217], v[26:29]
	v_mfma_f32_16x16x32_bf16 v[34:37], v[190:193], v[214:217], v[34:37]
	v_mfma_f32_16x16x32_bf16 v[14:17], v[190:193], v[238:241], v[14:17]
	v_mfma_f32_16x16x32_bf16 v[6:9], v[170:173], v[238:241], v[6:9]
	v_mfma_f32_16x16x32_bf16 v[46:49], v[174:177], v[202:205], v[46:49]
	v_mfma_f32_16x16x32_bf16 v[58:61], v[194:197], v[202:205], v[58:61]
	v_mfma_f32_16x16x32_bf16 v[66:69], v[194:197], v[210:213], v[66:69]
	v_mfma_f32_16x16x32_bf16 v[62:65], v[174:177], v[210:213], v[62:65]
	v_mfma_f32_16x16x32_bf16 v[26:29], v[174:177], v[218:221], v[26:29]
	v_mfma_f32_16x16x32_bf16 v[34:37], v[194:197], v[218:221], v[34:37]
	v_mfma_f32_16x16x32_bf16 v[14:17], v[194:197], v[242:245], v[14:17]
	v_mfma_f32_16x16x32_bf16 v[6:9], v[174:177], v[242:245], v[6:9]
	s_barrier
	s_setprio 0
	s_add_i32 s57, s57, 2
	s_add_u32 s38, s38, 0x100
	s_addc_u32 s39, s39, 0
	s_cmpk_gt_u32 s57, 0x53
	s_mov_b64 s[26:27], s[28:29]
	s_cbranch_scc0 .LBB0_2241
	s_and_b64 vcc, exec, s[18:19]
	s_cbranch_vccz .LBB0_2244
	s_barrier

.LBB0_2276:
	s_andn2_b64 vcc, exec, s[18:19]
	s_cbranch_vccnz .LBB0_2330
	v_ashrrev_i32_e32 v4, 31, v2
	v_lshrrev_b32_e32 v4, 26, v4
	v_add_u32_e32 v4, v2, v4
	v_ashrrev_i32_e32 v132, 6, v4
	v_bfe_i32 v4, v2, 27, 1
	s_waitcnt lgkmcnt(0)
	v_lshlrev_b32_e32 v3, 4, v2
	v_lshrrev_b32_e32 v4, 22, v4
	v_add_u32_e32 v4, v3, v4
	v_and_b32_e32 v4, 0xfffffc00, v4
	v_sub_u32_e32 v4, v3, v4
	v_lshrrev_b32_e32 v5, 4, v4
	v_bitop3_b32 v4, v5, v4, 32 bitop3:0x6c
	v_ashrrev_i32_e32 v6, 31, v4
	v_lshrrev_b32_e32 v6, 26, v6
	v_lshlrev_b32_e32 v5, 3, v132
	v_add_u32_e32 v6, v4, v6
	v_and_b32_e32 v5, -16, v5
	v_ashrrev_i32_e32 v134, 6, v6
	v_and_b32_e32 v6, 0xc0, v6
	s_mov_b64 s[18:19], 0x1de00000
	v_add_u32_e32 v5, v134, v5
	v_lshlrev_b32_e32 v7, 5, v132
	v_sub_u32_e32 v4, v4, v6
	v_lshl_add_u64 v[146:147], v[130:131], 0, s[18:19]
	v_and_b32_e32 v133, 32, v7
	v_ashrrev_i16_sdwa v4, v224, sext(v4) dst_sel:DWORD dst_unused:UNUSED_PAD src0_sel:DWORD src1_sel:BYTE_0
	v_lshlrev_b32_e32 v6, 1, v5
	v_lshrrev_b32_e32 v7, 2, v5
	v_and_b32_e32 v8, 3, v134
	s_mov_b32 s18, 0x1ffffe0
	v_bfe_i32 v135, v4, 0, 16
	v_and_b32_e32 v6, 24, v6
	v_and_b32_e32 v7, 4, v7
	v_and_or_b32 v8, v5, s18, v8
	s_movk_i32 s12, 0x1580
	v_add_u32_e32 v4, v133, v135
	v_or3_b32 v6, v8, v7, v6
	v_mul_lo_u32 v5, v5, s12
	v_add_lshl_u32 v148, v4, v5, 1
	v_mul_lo_u32 v5, v6, s12
	v_add_u32_e32 v3, 0x2000, v3
	v_add_lshl_u32 v150, v5, v4, 1
	v_ashrrev_i32_e32 v4, 31, v3
	v_lshrrev_b32_e32 v4, 22, v4
	v_add_u32_e32 v4, v3, v4
	v_ashrrev_i32_e32 v136, 10, v4
	v_mul_i32_i24_e32 v4, 0x400, v136
	v_sub_u32_e32 v3, v3, v4
	v_lshrrev_b32_e32 v4, 4, v3
	v_bitop3_b32 v3, v4, v3, 32 bitop3:0x6c
	v_ashrrev_i32_e32 v5, 31, v3
	v_lshrrev_b32_e32 v5, 26, v5
	v_lshlrev_b32_e32 v4, 3, v136
	v_add_u32_e32 v5, v3, v5
	v_and_b32_e32 v4, -16, v4
	v_ashrrev_i32_e32 v138, 6, v5
	v_and_b32_e32 v5, 0xc0, v5
	v_add_u32_e32 v4, v138, v4
	v_lshlrev_b32_e32 v6, 5, v136
	v_sub_u32_e32 v3, v3, v5
	v_and_b32_e32 v137, 32, v6
	v_ashrrev_i16_sdwa v3, v224, sext(v3) dst_sel:DWORD dst_unused:UNUSED_PAD src0_sel:DWORD src1_sel:BYTE_0
	v_lshlrev_b32_e32 v5, 1, v4
	v_lshrrev_b32_e32 v6, 2, v4
	v_and_b32_e32 v7, 3, v138
	v_bfe_i32 v139, v3, 0, 16
	v_and_b32_e32 v5, 24, v5
	v_and_b32_e32 v6, 4, v6
	v_and_or_b32 v7, v4, s18, v7
	v_add_u32_e32 v3, v137, v139
	v_or3_b32 v5, v7, v6, v5
	v_mul_lo_u32 v4, v4, s12
	v_add_lshl_u32 v152, v3, v4, 1
	v_mul_lo_u32 v4, v5, s12
	s_ashr_i32 s12, s24, 6
	s_ashr_i32 s22, s24, 8
	s_lshl_b32 s21, s12, 10
	s_lshl_b32 s12, s12, 5
	s_lshl_b32 s54, s22, 6
	s_and_b32 s55, s12, 0x60
	s_lshl_b32 s12, s42, 8
	v_and_b32_e32 v197, 15, v2
	s_add_i32 s12, s12, s54
	v_bfe_u32 v198, v2, 4, 2
	v_or_b32_e32 v2, s12, v197
	v_add_lshl_u32 v154, v4, v3, 1
	v_ashrrev_i32_e32 v3, 31, v2
	v_lshlrev_b64 v[2:3], 12, v[2:3]
	s_lshl_b32 s18, s66, 8
	v_lshl_add_u64 v[2:3], v[146:147], 0, v[2:3]
	s_ashr_i32 s19, s18, 31
	v_lshl_add_u64 v[2:3], s[18:19], 1, v[2:3]
	s_lshl_b32 s12, s55, 1
	v_lshl_add_u64 v[2:3], v[2:3], 0, s[12:13]
	v_lshlrev_b32_e32 v180, 4, v198
	v_lshl_add_u64 v[6:7], v[2:3], 0, v[180:181]
	s_mov_b32 s18, 0x10000
	v_add_co_u32_e32 v2, vcc, s18, v6
	s_mov_b32 s18, 0x20000
	s_nop 0
	v_addc_co_u32_e32 v3, vcc, 0, v7, vcc
	global_load_dwordx4 v[62:65], v[6:7], off
	global_load_dwordx4 v[58:61], v[6:7], off offset:256
	global_load_dwordx4 v[54:57], v[2:3], off
	global_load_dwordx4 v[50:53], v[2:3], off offset:256
	v_add_co_u32_e32 v2, vcc, s18, v6
	s_mov_b32 s18, 0x30000
	s_nop 0
	v_addc_co_u32_e32 v3, vcc, 0, v7, vcc
	global_load_dwordx4 v[46:49], v[2:3], off
	global_load_dwordx4 v[30:33], v[2:3], off offset:256
	v_add_co_u32_e32 v2, vcc, s18, v6
	s_mov_b32 s18, 0x80000
	s_nop 0
	v_addc_co_u32_e32 v3, vcc, 0, v7, vcc
	global_load_dwordx4 v[34:37], v[2:3], off
	global_load_dwordx4 v[22:25], v[2:3], off offset:256
	v_add_co_u32_e32 v2, vcc, s18, v6
	s_mov_b32 s18, 0x90000
	s_nop 0
	v_addc_co_u32_e32 v3, vcc, 0, v7, vcc
	global_load_dwordx4 v[26:29], v[2:3], off
	global_load_dwordx4 v[10:13], v[2:3], off offset:256
	v_add_co_u32_e32 v2, vcc, s18, v6
	s_mov_b32 s18, 0xa0000
	s_nop 0
	v_addc_co_u32_e32 v3, vcc, 0, v7, vcc
	global_load_dwordx4 v[42:45], v[2:3], off
	global_load_dwordx4 v[38:41], v[2:3], off offset:256
	v_add_co_u32_e32 v2, vcc, s18, v6
	s_mov_b32 s18, 0xb0000
	s_nop 0
	v_addc_co_u32_e32 v3, vcc, 0, v7, vcc
	s_mul_i32 s19, s66, 0x2b0000
	v_add_co_u32_e32 v18, vcc, s18, v6
	s_mul_hi_i32 s18, s66, 0x2b0000
	s_add_u32 s30, s8, s19
	s_addc_u32 s31, s9, s18
	s_add_i32 s56, s21, 0
	v_addc_co_u32_e32 v19, vcc, 0, v7, vcc
	s_add_i32 m0, s56, 0x10000
	global_load_dwordx4 v[14:17], v[2:3], off
	s_nop 0
	global_load_dwordx4 v[2:5], v[2:3], off offset:256
	s_nop 0
	global_load_dwordx4 v[6:9], v[18:19], off
	s_nop 0
	global_load_dwordx4 v[18:21], v[18:19], off offset:256
	s_mul_i32 s25, s42, 0x2b0000
	v_and_b32_e32 v140, 63, v0
	v_lshrrev_b32_e32 v141, 3, v140
	v_and_b32_e32 v140, 7, v140
	v_xor_b32_e32 v140, v140, v141
	v_lshlrev_b32_e32 v140, 4, v140
	v_lshrrev_b32_e32 v142, 6, v0
	v_lshl_add_u32 v141, v142, 3, v141
	v_mov_b32_e32 v142, 0x2b00
	v_mad_u32_u24 v148, v141, v142, v140
	v_add_u32_e32 v152, 0xac000, v148
	v_and_b32_e32 v143, 15, v141
	v_lshrrev_b32_e32 v142, 2, v143
	v_and_b32_e32 v143, 3, v143
	v_lshl_add_u32 v143, v142, 3, v143
	v_bfe_u32 v142, v141, 4, 1
	v_lshl_add_u32 v143, v142, 2, v143
	v_and_b32_e32 v142, 0x60, v141
	v_or_b32_e32 v143, v142, v143
	v_mov_b32_e32 v142, 0x2b00
	v_mad_u32_u24 v150, v143, v142, v140
	v_add_u32_e32 v154, 0xac000, v150
	global_load_lds_dwordx4 v150, s[30:31]
	s_add_i32 m0, s56, 0x12000
	s_add_u32 s18, s30, 0x158000
	global_load_lds_dwordx4 v154, s[30:31]
	s_addc_u32 s19, s31, 0
	s_add_i32 m0, s56, 0x14000
	s_mul_hi_i32 s23, s42, 0x2b0000
	global_load_lds_dwordx4 v150, s[18:19]
	s_add_i32 m0, s56, 0x16000
	s_add_u32 s28, s6, s25
	s_addc_u32 s29, s7, s23
	s_add_i32 s57, s56, 0x2000
	global_load_lds_dwordx4 v154, s[18:19]
	s_mov_b32 m0, s56
	s_add_u32 s18, s28, 0x158000
	global_load_lds_dwordx4 v148, s[28:29]
	s_mov_b32 m0, s57
	s_addc_u32 s19, s29, 0
	s_add_i32 s58, s56, 0x4000
	global_load_lds_dwordx4 v152, s[28:29]
	s_mov_b32 m0, s58
	s_add_i32 s59, s56, 0x6000
	global_load_lds_dwordx4 v148, s[18:19]
	s_mov_b32 m0, s59
	v_mov_b32_e32 v151, v181
	global_load_lds_dwordx4 v152, s[18:19]
	v_mov_b32_e32 v155, v181
	v_mov_b32_e32 v149, v181
	v_mov_b32_e32 v153, v181
	s_cmp_eq_u32 s22, 1
	v_lshl_add_u64 v[80:81], s[30:31], 0, v[150:151]
	v_lshl_add_u64 v[78:79], s[30:31], 0, v[154:155]
	v_lshl_add_u64 v[66:67], s[28:29], 0, v[148:149]
	s_cselect_b64 s[18:19], -1, 0
	s_cmp_lg_u32 s22, 1
	v_lshl_add_u64 v[68:69], s[28:29], 0, v[152:153]
	s_cbranch_scc1 .LBB0_2279
	s_barrier
.LBB0_2279:
	s_waitcnt vmcnt(0)
	v_lshlrev_b32_e32 v106, 16, v50
	v_and_b32_e32 v107, 0xffff0000, v50
	v_lshlrev_b32_e32 v108, 16, v51
	v_and_b32_e32 v109, 0xffff0000, v51
	v_lshlrev_b32_e32 v110, 16, v52
	v_and_b32_e32 v111, 0xffff0000, v52
	v_lshlrev_b32_e32 v112, 16, v53
	v_and_b32_e32 v113, 0xffff0000, v53
	v_lshlrev_b32_e32 v50, 16, v12
	v_and_b32_e32 v51, 0xffff0000, v12
	v_lshlrev_b32_e32 v52, 16, v13
	v_and_b32_e32 v53, 0xffff0000, v13
	s_add_i32 m0, s56, 0x18000
	v_lshl_add_u64 v[12:13], v[80:81], 0, s[16:17]
	s_lshl_b32 s25, s22, 13
	s_lshl_b32 s26, s55, 7
	s_waitcnt vmcnt(2)
	s_barrier
	global_load_lds_dwordx4 v[12:13], off
	v_lshl_add_u64 v[12:13], v[78:79], 0, s[16:17]
	s_add_i32 m0, s56, 0x1a000
	s_add_i32 s60, s56, 0x8000
	s_add_i32 s61, s56, 0xa000
	global_load_lds_dwordx4 v[12:13], off
	v_lshl_add_u64 v[12:13], v[66:67], 0, s[16:17]
	s_mov_b32 m0, s60
	s_add_u32 s22, s30, 0x158080
	global_load_lds_dwordx4 v[12:13], off
	v_lshl_add_u64 v[12:13], v[68:69], 0, s[16:17]
	s_mov_b32 m0, s61
	s_addc_u32 s23, s31, 0
	global_load_lds_dwordx4 v[12:13], off
	s_add_i32 m0, s56, 0x1c000
	v_lshl_add_u64 v[12:13], s[22:23], 0, v[150:151]
	global_load_lds_dwordx4 v[12:13], off
	v_lshl_add_u64 v[12:13], s[22:23], 0, v[154:155]
	s_add_i32 m0, s56, 0x1e000
	s_mov_b64 s[22:23], 0x94000
	global_load_lds_dwordx4 v[12:13], off
	v_lshl_add_u64 v[156:157], v[130:131], 0, s[22:23]
	s_mov_b64 s[22:23], 0x9000
	v_or_b32_e32 v199, s54, v197
	v_lshl_add_u64 v[158:159], v[130:131], 0, s[22:23]
	v_lshlrev_b32_e32 v130, 6, v199
	s_movk_i32 s22, 0x3c0
	v_lshlrev_b32_e32 v131, 2, v199
	v_and_or_b32 v130, v130, s22, v180
	v_and_b32_e32 v131, 32, v131
	v_bitop3_b32 v141, v130, s25, v131 bitop3:0xde
	v_lshlrev_b32_e32 v131, 2, v197
	v_lshl_or_b32 v130, v197, 6, v180
	v_and_b32_e32 v131, 32, v131
	v_bitop3_b32 v200, v130, s26, v131 bitop3:0xde
	s_movk_i32 s26, 0x1580
	v_lshrrev_b32_e32 v131, 1, v132
	v_mul_lo_u32 v130, v134, s26
	s_mov_b32 s27, 0x15800
	s_cmpk_lt_u32 s24, 0x100
	v_mad_u64_u32 v[130:131], s[24:25], v131, s27, v[130:131]
	v_or_b32_e32 v130, v130, v133
	v_add_lshl_u32 v180, v130, v135, 1
	v_lshrrev_b32_e32 v131, 1, v136
	v_mul_lo_u32 v130, v138, s26
	v_mad_u64_u32 v[130:131], s[24:25], v131, s27, v[130:131]
	s_waitcnt vmcnt(6)
	s_mov_b64 s[34:35], 0x158080
	v_or_b32_e32 v130, v130, v137
	v_lshlrev_b32_e32 v140, 3, v198
	v_mov_b32_e32 v160, v148
	v_mov_b32_e32 v161, 0
	v_lshl_add_u64 v[160:161], v[160:161], 0, s[34:35]
	v_add_lshl_u32 v180, v130, v139, 1
	v_lshlrev_b32_e32 v118, 16, v62
	v_and_b32_e32 v119, 0xffff0000, v62
	v_lshlrev_b32_e32 v120, 16, v63
	v_and_b32_e32 v121, 0xffff0000, v63
	v_lshlrev_b32_e32 v114, 16, v64
	v_and_b32_e32 v115, 0xffff0000, v64
	v_lshlrev_b32_e32 v116, 16, v65
	v_and_b32_e32 v117, 0xffff0000, v65
	v_lshlrev_b32_e32 v126, 16, v58
	v_and_b32_e32 v127, 0xffff0000, v58
	v_lshlrev_b32_e32 v128, 16, v59
	v_and_b32_e32 v129, 0xffff0000, v59
	v_lshlrev_b32_e32 v122, 16, v60
	v_and_b32_e32 v123, 0xffff0000, v60
	v_lshlrev_b32_e32 v124, 16, v61
	v_and_b32_e32 v125, 0xffff0000, v61
	v_lshlrev_b32_e32 v98, 16, v54
	v_and_b32_e32 v99, 0xffff0000, v54
	v_lshlrev_b32_e32 v100, 16, v55
	v_and_b32_e32 v101, 0xffff0000, v55
	v_lshlrev_b32_e32 v102, 16, v56
	v_and_b32_e32 v103, 0xffff0000, v56
	v_lshlrev_b32_e32 v104, 16, v57
	v_and_b32_e32 v105, 0xffff0000, v57
	v_lshlrev_b32_e32 v70, 16, v46
	v_and_b32_e32 v71, 0xffff0000, v46
	v_lshlrev_b32_e32 v72, 16, v47
	v_and_b32_e32 v73, 0xffff0000, v47
	v_lshlrev_b32_e32 v74, 16, v48
	v_and_b32_e32 v75, 0xffff0000, v48
	v_lshlrev_b32_e32 v76, 16, v49
	v_and_b32_e32 v77, 0xffff0000, v49
	v_lshlrev_b32_e32 v82, 16, v30
	v_and_b32_e32 v83, 0xffff0000, v30
	v_lshlrev_b32_e32 v84, 16, v31
	v_and_b32_e32 v85, 0xffff0000, v31
	v_lshlrev_b32_e32 v86, 16, v32
	v_and_b32_e32 v87, 0xffff0000, v32
	v_lshlrev_b32_e32 v88, 16, v33
	v_and_b32_e32 v89, 0xffff0000, v33
	v_lshlrev_b32_e32 v30, 16, v34
	v_and_b32_e32 v31, 0xffff0000, v34
	v_lshlrev_b32_e32 v32, 16, v35
	v_and_b32_e32 v33, 0xffff0000, v35
	v_lshlrev_b32_e32 v34, 16, v36
	v_and_b32_e32 v35, 0xffff0000, v36
	v_lshlrev_b32_e32 v36, 16, v37
	v_and_b32_e32 v37, 0xffff0000, v37
	v_lshlrev_b32_e32 v54, 16, v22
	v_and_b32_e32 v55, 0xffff0000, v22
	v_lshlrev_b32_e32 v56, 16, v23
	v_and_b32_e32 v57, 0xffff0000, v23
	v_lshlrev_b32_e32 v58, 16, v24
	v_and_b32_e32 v59, 0xffff0000, v24
	v_lshlrev_b32_e32 v60, 16, v25
	v_and_b32_e32 v61, 0xffff0000, v25
	v_lshlrev_b32_e32 v22, 16, v26
	v_and_b32_e32 v23, 0xffff0000, v26
	v_lshlrev_b32_e32 v24, 16, v27
	v_and_b32_e32 v25, 0xffff0000, v27
	v_lshlrev_b32_e32 v26, 16, v28
	v_and_b32_e32 v27, 0xffff0000, v28
	v_lshlrev_b32_e32 v28, 16, v29
	v_and_b32_e32 v29, 0xffff0000, v29
	v_lshlrev_b32_e32 v46, 16, v10
	v_and_b32_e32 v47, 0xffff0000, v10
	v_lshlrev_b32_e32 v48, 16, v11
	v_and_b32_e32 v49, 0xffff0000, v11
	v_lshlrev_b32_e32 v10, 16, v42
	v_and_b32_e32 v11, 0xffff0000, v42
	v_lshlrev_b32_e32 v12, 16, v43
	v_and_b32_e32 v13, 0xffff0000, v43
	v_lshlrev_b32_e32 v78, 16, v44
	v_and_b32_e32 v79, 0xffff0000, v44
	v_lshlrev_b32_e32 v80, 16, v45
	v_and_b32_e32 v81, 0xffff0000, v45
	v_lshlrev_b32_e32 v90, 16, v38
	v_and_b32_e32 v91, 0xffff0000, v38
	v_lshlrev_b32_e32 v92, 16, v39
	v_and_b32_e32 v93, 0xffff0000, v39
	v_lshlrev_b32_e32 v94, 16, v40
	v_and_b32_e32 v95, 0xffff0000, v40
	v_lshlrev_b32_e32 v96, 16, v41
	v_and_b32_e32 v97, 0xffff0000, v41
	v_lshlrev_b32_e32 v38, 16, v14
	v_and_b32_e32 v39, 0xffff0000, v14
	v_lshlrev_b32_e32 v40, 16, v15
	v_and_b32_e32 v41, 0xffff0000, v15
	v_lshlrev_b32_e32 v42, 16, v16
	v_and_b32_e32 v43, 0xffff0000, v16
	v_lshlrev_b32_e32 v44, 16, v17
	v_and_b32_e32 v45, 0xffff0000, v17
	v_lshlrev_b32_e32 v62, 16, v2
	v_and_b32_e32 v63, 0xffff0000, v2
	v_lshlrev_b32_e32 v64, 16, v3
	v_and_b32_e32 v65, 0xffff0000, v3
	v_lshlrev_b32_e32 v66, 16, v4
	v_and_b32_e32 v67, 0xffff0000, v4
	v_lshlrev_b32_e32 v68, 16, v5
	v_and_b32_e32 v69, 0xffff0000, v5
	v_lshlrev_b32_e32 v2, 16, v6
	v_and_b32_e32 v3, 0xffff0000, v6
	v_lshlrev_b32_e32 v4, 16, v7
	v_and_b32_e32 v5, 0xffff0000, v7
	v_lshlrev_b32_e32 v6, 16, v8
	v_and_b32_e32 v7, 0xffff0000, v8
	v_lshlrev_b32_e32 v8, 16, v9
	v_and_b32_e32 v9, 0xffff0000, v9
	v_lshlrev_b32_e32 v14, 16, v18
	v_and_b32_e32 v15, 0xffff0000, v18
	v_lshlrev_b32_e32 v16, 16, v19
	v_and_b32_e32 v17, 0xffff0000, v19
	v_lshlrev_b32_e32 v18, 16, v20
	v_and_b32_e32 v19, 0xffff0000, v20
	v_lshlrev_b32_e32 v20, 16, v21
	v_and_b32_e32 v21, 0xffff0000, v21
	s_cselect_b64 s[22:23], -1, 0
	v_mov_b32_e32 v162, v152
	v_mov_b32_e32 v163, 0
	v_lshl_add_u64 v[162:163], v[162:163], 0, s[34:35]
	s_mov_b32 s62, 0
	v_add_u32_e32 v201, 0, v141
	v_lshlrev_b32_e32 v180, 1, v140
	v_and_b32_e32 v130, 7, v0
	v_bfe_u32 v131, v0, 4, 2
	v_xor_b32_e32 v131, v131, v130
	v_lshlrev_b32_e32 v131, 4, v131
	v_lshl_add_u32 v131, v130, 7, v131
	v_bfe_u32 v130, v0, 3, 1
	v_lshl_add_u32 v131, v130, 10, v131
	v_lshrrev_b32_e32 v130, 8, v0
	v_lshl_add_u32 v201, v130, 13, v131
	v_bfe_u32 v130, v0, 6, 2
	v_lshl_add_u32 v200, v130, 12, v131
	s_barrier
	s_branch .LBB0_2282

.LBB0_2293:
	s_add_u32 s30, s28, 0x100
	s_addc_u32 s31, s29, 0
	s_add_i32 s46, 0, 0x10000
	s_cmpk_eq_i32 s45, 0x52
	s_cselect_b32 s39, s25, s31
	s_cselect_b32 s38, s24, s30
	s_cselect_b32 s35, s27, s44
	s_cselect_b32 s34, s26, s43
	s_add_i32 s47, 0, 0x14000
	v_add_u32_e32 v142, s46, v200
	v_add_u32_e32 v176, s47, v200
	ds_read_b128 v[130:133], v142
	ds_read_b128 v[138:141], v142 offset:2048
	v_xor_b32_e32 v142, 64, v142
	ds_read_b128 v[134:137], v142
	ds_read_b128 v[142:145], v142 offset:2048
	ds_read_b128 v[164:167], v176
	ds_read_b128 v[172:175], v176 offset:2048
	v_xor_b32_e32 v176, 64, v176
	ds_read_b128 v[168:171], v176
	ds_read_b128 v[176:179], v176 offset:2048
	v_lshl_add_u64 v[222:223], s[28:29], 0, v[160:161]
	s_add_i32 m0, s56, 0xc000
	ds_read_b128 v[190:193], v201
	ds_read_b128 v[206:209], v201 offset:2048
	ds_read_b128 v[214:217], v201 offset:4096
	ds_read_b128 v[238:241], v201 offset:6144
	v_xor_b32_e32 v242, 64, v201
	ds_read_b128 v[202:205], v242
	ds_read_b128 v[210:213], v242 offset:2048
	ds_read_b128 v[218:221], v242 offset:4096
	ds_read_b128 v[242:245], v242 offset:6144
	global_load_lds_dwordx4 v[222:223], off
	v_lshl_add_u64 v[222:223], s[28:29], 0, v[162:163]
	s_add_i32 m0, s56, 0xe000
	s_nop 0
	global_load_lds_dwordx4 v[222:223], off
	s_waitcnt vmcnt(8)
	s_waitcnt lgkmcnt(0)
	s_setprio 1
	s_barrier
	v_mfma_f32_16x16x32_bf16 v[118:121], v[130:133], v[190:193], v[118:121]
	v_mfma_f32_16x16x32_bf16 v[114:117], v[138:141], v[190:193], v[114:117]
	v_mfma_f32_16x16x32_bf16 v[102:105], v[138:141], v[206:209], v[102:105]
	v_mfma_f32_16x16x32_bf16 v[98:101], v[130:133], v[206:209], v[98:101]
	v_mfma_f32_16x16x32_bf16 v[70:73], v[130:133], v[214:217], v[70:73]
	v_mfma_f32_16x16x32_bf16 v[74:77], v[138:141], v[214:217], v[74:77]
	v_mfma_f32_16x16x32_bf16 v[34:37], v[138:141], v[238:241], v[34:37]
	v_mfma_f32_16x16x32_bf16 v[30:33], v[130:133], v[238:241], v[30:33]
	v_mfma_f32_16x16x32_bf16 v[118:121], v[134:137], v[202:205], v[118:121]
	v_mfma_f32_16x16x32_bf16 v[114:117], v[142:145], v[202:205], v[114:117]
	v_mfma_f32_16x16x32_bf16 v[102:105], v[142:145], v[210:213], v[102:105]
	v_mfma_f32_16x16x32_bf16 v[98:101], v[134:137], v[210:213], v[98:101]
	v_mfma_f32_16x16x32_bf16 v[70:73], v[134:137], v[218:221], v[70:73]
	v_mfma_f32_16x16x32_bf16 v[74:77], v[142:145], v[218:221], v[74:77]
	v_mfma_f32_16x16x32_bf16 v[34:37], v[142:145], v[242:245], v[34:37]
	v_mfma_f32_16x16x32_bf16 v[30:33], v[134:137], v[242:245], v[30:33]
	v_mfma_f32_16x16x32_bf16 v[126:129], v[164:167], v[190:193], v[126:129]
	v_mfma_f32_16x16x32_bf16 v[122:125], v[172:175], v[190:193], v[122:125]
	v_mfma_f32_16x16x32_bf16 v[110:113], v[172:175], v[206:209], v[110:113]
	v_mfma_f32_16x16x32_bf16 v[106:109], v[164:167], v[206:209], v[106:109]
	v_mfma_f32_16x16x32_bf16 v[82:85], v[164:167], v[214:217], v[82:85]
	v_mfma_f32_16x16x32_bf16 v[86:89], v[172:175], v[214:217], v[86:89]
	v_mfma_f32_16x16x32_bf16 v[58:61], v[172:175], v[238:241], v[58:61]
	v_mfma_f32_16x16x32_bf16 v[54:57], v[164:167], v[238:241], v[54:57]
	v_mfma_f32_16x16x32_bf16 v[126:129], v[168:171], v[202:205], v[126:129]
	v_mfma_f32_16x16x32_bf16 v[122:125], v[176:179], v[202:205], v[122:125]
	v_mfma_f32_16x16x32_bf16 v[110:113], v[176:179], v[210:213], v[110:113]
	v_mfma_f32_16x16x32_bf16 v[106:109], v[168:171], v[210:213], v[106:109]
	v_mfma_f32_16x16x32_bf16 v[82:85], v[168:171], v[218:221], v[82:85]
	v_mfma_f32_16x16x32_bf16 v[86:89], v[176:179], v[218:221], v[86:89]
	v_mfma_f32_16x16x32_bf16 v[58:61], v[176:179], v[242:245], v[58:61]
	v_mfma_f32_16x16x32_bf16 v[54:57], v[168:171], v[242:245], v[54:57]
	s_barrier
	s_setprio 0
	s_add_i32 s28, s46, s21
	v_lshl_add_u64 v[222:223], s[34:35], 0, v[150:151]
	s_mov_b32 m0, s28
	ds_read_b128 v[190:193], v201 offset:16384
	ds_read_b128 v[206:209], v201 offset:18432
	ds_read_b128 v[214:217], v201 offset:20480
	ds_read_b128 v[238:241], v201 offset:22528
	v_xor_b32_e32 v242, 64, v201
	ds_read_b128 v[202:205], v242 offset:16384
	ds_read_b128 v[210:213], v242 offset:18432
	ds_read_b128 v[218:221], v242 offset:20480
	ds_read_b128 v[242:245], v242 offset:22528
	global_load_lds_dwordx4 v[222:223], off
	s_add_i32 m0, s28, 0x2000
	s_add_u32 s28, s34, 0x158000
	v_lshl_add_u64 v[246:247], s[34:35], 0, v[154:155]
	s_addc_u32 s29, s35, 0
	s_add_i32 s46, s47, s21
	global_load_lds_dwordx4 v[246:247], off
	v_lshl_add_u64 v[248:249], s[28:29], 0, v[150:151]
	s_mov_b32 m0, s46
	v_lshl_add_u64 v[250:251], s[38:39], 0, v[152:153]
	global_load_lds_dwordx4 v[248:249], off
	v_lshl_add_u64 v[248:249], s[28:29], 0, v[154:155]
	s_add_i32 m0, s46, 0x2000
	s_nop 0
	global_load_lds_dwordx4 v[248:249], off
	v_lshl_add_u64 v[248:249], s[38:39], 0, v[148:149]
	s_mov_b32 m0, s56
	s_nop 0
	global_load_lds_dwordx4 v[248:249], off
	s_mov_b32 m0, s57
	s_nop 0
	global_load_lds_dwordx4 v[250:251], off
	s_waitcnt vmcnt(8)
	s_waitcnt lgkmcnt(0)
	s_setprio 1
	s_barrier
	v_mfma_f32_16x16x32_bf16 v[22:25], v[130:133], v[190:193], v[22:25]
	v_mfma_f32_16x16x32_bf16 v[26:29], v[138:141], v[190:193], v[26:29]
	v_mfma_f32_16x16x32_bf16 v[78:81], v[138:141], v[206:209], v[78:81]
	v_mfma_f32_16x16x32_bf16 v[10:13], v[130:133], v[206:209], v[10:13]
	v_mfma_f32_16x16x32_bf16 v[38:41], v[130:133], v[214:217], v[38:41]
	v_mfma_f32_16x16x32_bf16 v[42:45], v[138:141], v[214:217], v[42:45]
	v_mfma_f32_16x16x32_bf16 v[6:9], v[138:141], v[238:241], v[6:9]
	v_mfma_f32_16x16x32_bf16 v[2:5], v[130:133], v[238:241], v[2:5]
	v_mfma_f32_16x16x32_bf16 v[22:25], v[134:137], v[202:205], v[22:25]
	v_mfma_f32_16x16x32_bf16 v[26:29], v[142:145], v[202:205], v[26:29]
	v_mfma_f32_16x16x32_bf16 v[78:81], v[142:145], v[210:213], v[78:81]
	v_mfma_f32_16x16x32_bf16 v[10:13], v[134:137], v[210:213], v[10:13]
	v_mfma_f32_16x16x32_bf16 v[38:41], v[134:137], v[218:221], v[38:41]
	v_mfma_f32_16x16x32_bf16 v[42:45], v[142:145], v[218:221], v[42:45]
	v_mfma_f32_16x16x32_bf16 v[6:9], v[142:145], v[242:245], v[6:9]
	v_mfma_f32_16x16x32_bf16 v[2:5], v[134:137], v[242:245], v[2:5]
	v_mfma_f32_16x16x32_bf16 v[46:49], v[164:167], v[190:193], v[46:49]
	v_mfma_f32_16x16x32_bf16 v[50:53], v[172:175], v[190:193], v[50:53]
	v_mfma_f32_16x16x32_bf16 v[94:97], v[172:175], v[206:209], v[94:97]
	v_mfma_f32_16x16x32_bf16 v[90:93], v[164:167], v[206:209], v[90:93]
	v_mfma_f32_16x16x32_bf16 v[62:65], v[164:167], v[214:217], v[62:65]
	v_mfma_f32_16x16x32_bf16 v[66:69], v[172:175], v[214:217], v[66:69]
	v_mfma_f32_16x16x32_bf16 v[18:21], v[172:175], v[238:241], v[18:21]
	v_mfma_f32_16x16x32_bf16 v[14:17], v[164:167], v[238:241], v[14:17]
	v_mfma_f32_16x16x32_bf16 v[46:49], v[168:171], v[202:205], v[46:49]
	v_mfma_f32_16x16x32_bf16 v[50:53], v[176:179], v[202:205], v[50:53]
	v_mfma_f32_16x16x32_bf16 v[94:97], v[176:179], v[210:213], v[94:97]
	v_mfma_f32_16x16x32_bf16 v[90:93], v[168:171], v[210:213], v[90:93]
	v_mfma_f32_16x16x32_bf16 v[62:65], v[168:171], v[218:221], v[62:65]
	v_mfma_f32_16x16x32_bf16 v[66:69], v[176:179], v[218:221], v[66:69]
	v_mfma_f32_16x16x32_bf16 v[18:21], v[176:179], v[242:245], v[18:21]
	v_mfma_f32_16x16x32_bf16 v[14:17], v[168:171], v[242:245], v[14:17]
	s_barrier
	s_setprio 0
	s_add_i32 s46, 0, 0x18000
	s_add_i32 s47, 0, 0x1c000
	v_add_u32_e32 v142, s46, v200
	v_add_u32_e32 v176, s47, v200
	ds_read_b128 v[130:133], v142
	ds_read_b128 v[138:141], v142 offset:2048
	v_xor_b32_e32 v142, 64, v142
	ds_read_b128 v[134:137], v142
	ds_read_b128 v[142:145], v142 offset:2048
	ds_read_b128 v[164:167], v176
	ds_read_b128 v[172:175], v176 offset:2048
	v_xor_b32_e32 v176, 64, v176
	ds_read_b128 v[168:171], v176
	ds_read_b128 v[176:179], v176 offset:2048
	s_add_u32 s28, s38, 0x158000
	s_addc_u32 s29, s39, 0
	s_mov_b32 m0, s58
	v_lshl_add_u64 v[252:253], s[28:29], 0, v[148:149]
	ds_read_b128 v[190:193], v201 offset:32768
	ds_read_b128 v[206:209], v201 offset:34816
	ds_read_b128 v[214:217], v201 offset:36864
	ds_read_b128 v[238:241], v201 offset:38912
	v_xor_b32_e32 v242, 64, v201
	ds_read_b128 v[202:205], v242 offset:32768
	ds_read_b128 v[210:213], v242 offset:34816
	ds_read_b128 v[218:221], v242 offset:36864
	ds_read_b128 v[242:245], v242 offset:38912
	global_load_lds_dwordx4 v[252:253], off
	v_lshl_add_u64 v[252:253], s[28:29], 0, v[152:153]
	s_mov_b32 m0, s59
	s_nop 0
	global_load_lds_dwordx4 v[252:253], off
	s_waitcnt vmcnt(8)
	s_waitcnt lgkmcnt(0)
	s_setprio 1
	s_barrier
	v_mfma_f32_16x16x32_bf16 v[118:121], v[130:133], v[190:193], v[118:121]
	v_mfma_f32_16x16x32_bf16 v[114:117], v[138:141], v[190:193], v[114:117]
	v_mfma_f32_16x16x32_bf16 v[102:105], v[138:141], v[206:209], v[102:105]
	v_mfma_f32_16x16x32_bf16 v[98:101], v[130:133], v[206:209], v[98:101]
	v_mfma_f32_16x16x32_bf16 v[70:73], v[130:133], v[214:217], v[70:73]
	v_mfma_f32_16x16x32_bf16 v[74:77], v[138:141], v[214:217], v[74:77]
	v_mfma_f32_16x16x32_bf16 v[34:37], v[138:141], v[238:241], v[34:37]
	v_mfma_f32_16x16x32_bf16 v[30:33], v[130:133], v[238:241], v[30:33]
	v_mfma_f32_16x16x32_bf16 v[118:121], v[134:137], v[202:205], v[118:121]
	v_mfma_f32_16x16x32_bf16 v[114:117], v[142:145], v[202:205], v[114:117]
	v_mfma_f32_16x16x32_bf16 v[102:105], v[142:145], v[210:213], v[102:105]
	v_mfma_f32_16x16x32_bf16 v[98:101], v[134:137], v[210:213], v[98:101]
	v_mfma_f32_16x16x32_bf16 v[70:73], v[134:137], v[218:221], v[70:73]
	v_mfma_f32_16x16x32_bf16 v[74:77], v[142:145], v[218:221], v[74:77]
	v_mfma_f32_16x16x32_bf16 v[34:37], v[142:145], v[242:245], v[34:37]
	v_mfma_f32_16x16x32_bf16 v[30:33], v[134:137], v[242:245], v[30:33]
	v_mfma_f32_16x16x32_bf16 v[126:129], v[164:167], v[190:193], v[126:129]
	v_mfma_f32_16x16x32_bf16 v[122:125], v[172:175], v[190:193], v[122:125]
	v_mfma_f32_16x16x32_bf16 v[110:113], v[172:175], v[206:209], v[110:113]
	v_mfma_f32_16x16x32_bf16 v[106:109], v[164:167], v[206:209], v[106:109]
	v_mfma_f32_16x16x32_bf16 v[82:85], v[164:167], v[214:217], v[82:85]
	v_mfma_f32_16x16x32_bf16 v[86:89], v[172:175], v[214:217], v[86:89]
	v_mfma_f32_16x16x32_bf16 v[58:61], v[172:175], v[238:241], v[58:61]
	v_mfma_f32_16x16x32_bf16 v[54:57], v[164:167], v[238:241], v[54:57]
	v_mfma_f32_16x16x32_bf16 v[126:129], v[168:171], v[202:205], v[126:129]
	v_mfma_f32_16x16x32_bf16 v[122:125], v[176:179], v[202:205], v[122:125]
	v_mfma_f32_16x16x32_bf16 v[110:113], v[176:179], v[210:213], v[110:113]
	v_mfma_f32_16x16x32_bf16 v[106:109], v[168:171], v[210:213], v[106:109]
	v_mfma_f32_16x16x32_bf16 v[82:85], v[168:171], v[218:221], v[82:85]
	v_mfma_f32_16x16x32_bf16 v[86:89], v[176:179], v[218:221], v[86:89]
	v_mfma_f32_16x16x32_bf16 v[58:61], v[176:179], v[242:245], v[58:61]
	v_mfma_f32_16x16x32_bf16 v[54:57], v[168:171], v[242:245], v[54:57]
	s_barrier
	s_setprio 0
	s_add_i32 s28, s46, s21
	v_lshl_add_u64 v[222:223], v[222:223], 0, s[16:17]
	s_mov_b32 m0, s28
	ds_read_b128 v[190:193], v201 offset:49152
	ds_read_b128 v[206:209], v201 offset:51200
	ds_read_b128 v[214:217], v201 offset:53248
	ds_read_b128 v[238:241], v201 offset:55296
	v_xor_b32_e32 v242, 64, v201
	ds_read_b128 v[202:205], v242 offset:49152
	ds_read_b128 v[210:213], v242 offset:51200
	ds_read_b128 v[218:221], v242 offset:53248
	ds_read_b128 v[242:245], v242 offset:55296
	global_load_lds_dwordx4 v[222:223], off
	s_add_i32 m0, s28, 0x2000
	s_add_u32 s28, s34, 0x158080
	v_lshl_add_u64 v[222:223], v[246:247], 0, s[16:17]
	s_addc_u32 s29, s35, 0
	s_add_i32 s34, s47, s21
	global_load_lds_dwordx4 v[222:223], off
	v_lshl_add_u64 v[222:223], s[28:29], 0, v[150:151]
	s_mov_b32 m0, s34
	s_nop 0
	global_load_lds_dwordx4 v[222:223], off
	v_lshl_add_u64 v[222:223], s[28:29], 0, v[154:155]
	s_add_i32 m0, s34, 0x2000
	s_nop 0
	global_load_lds_dwordx4 v[222:223], off
	v_lshl_add_u64 v[222:223], v[248:249], 0, s[16:17]
	s_mov_b32 m0, s60
	s_nop 0
	global_load_lds_dwordx4 v[222:223], off
	v_lshl_add_u64 v[222:223], v[250:251], 0, s[16:17]
	s_mov_b32 m0, s61
	s_nop 0
	global_load_lds_dwordx4 v[222:223], off
	s_waitcnt vmcnt(8)
	s_waitcnt lgkmcnt(0)
	s_setprio 1
	s_barrier
	v_mfma_f32_16x16x32_bf16 v[22:25], v[130:133], v[190:193], v[22:25]
	v_mfma_f32_16x16x32_bf16 v[26:29], v[138:141], v[190:193], v[26:29]
	v_mfma_f32_16x16x32_bf16 v[78:81], v[138:141], v[206:209], v[78:81]
	v_mfma_f32_16x16x32_bf16 v[10:13], v[130:133], v[206:209], v[10:13]
	v_mfma_f32_16x16x32_bf16 v[38:41], v[130:133], v[214:217], v[38:41]
	v_mfma_f32_16x16x32_bf16 v[42:45], v[138:141], v[214:217], v[42:45]
	v_mfma_f32_16x16x32_bf16 v[6:9], v[138:141], v[238:241], v[6:9]
	v_mfma_f32_16x16x32_bf16 v[2:5], v[130:133], v[238:241], v[2:5]
	v_mfma_f32_16x16x32_bf16 v[22:25], v[134:137], v[202:205], v[22:25]
	v_mfma_f32_16x16x32_bf16 v[26:29], v[142:145], v[202:205], v[26:29]
	v_mfma_f32_16x16x32_bf16 v[78:81], v[142:145], v[210:213], v[78:81]
	v_mfma_f32_16x16x32_bf16 v[10:13], v[134:137], v[210:213], v[10:13]
	v_mfma_f32_16x16x32_bf16 v[38:41], v[134:137], v[218:221], v[38:41]
	v_mfma_f32_16x16x32_bf16 v[42:45], v[142:145], v[218:221], v[42:45]
	v_mfma_f32_16x16x32_bf16 v[6:9], v[142:145], v[242:245], v[6:9]
	v_mfma_f32_16x16x32_bf16 v[2:5], v[134:137], v[242:245], v[2:5]
	v_mfma_f32_16x16x32_bf16 v[46:49], v[164:167], v[190:193], v[46:49]
	v_mfma_f32_16x16x32_bf16 v[50:53], v[172:175], v[190:193], v[50:53]
	v_mfma_f32_16x16x32_bf16 v[94:97], v[172:175], v[206:209], v[94:97]
	v_mfma_f32_16x16x32_bf16 v[90:93], v[164:167], v[206:209], v[90:93]
	v_mfma_f32_16x16x32_bf16 v[62:65], v[164:167], v[214:217], v[62:65]
	v_mfma_f32_16x16x32_bf16 v[66:69], v[172:175], v[214:217], v[66:69]
	v_mfma_f32_16x16x32_bf16 v[18:21], v[172:175], v[238:241], v[18:21]
	v_mfma_f32_16x16x32_bf16 v[14:17], v[164:167], v[238:241], v[14:17]
	v_mfma_f32_16x16x32_bf16 v[46:49], v[168:171], v[202:205], v[46:49]
	v_mfma_f32_16x16x32_bf16 v[50:53], v[176:179], v[202:205], v[50:53]
	v_mfma_f32_16x16x32_bf16 v[94:97], v[176:179], v[210:213], v[94:97]
	v_mfma_f32_16x16x32_bf16 v[90:93], v[168:171], v[210:213], v[90:93]
	v_mfma_f32_16x16x32_bf16 v[62:65], v[168:171], v[218:221], v[62:65]
	v_mfma_f32_16x16x32_bf16 v[66:69], v[176:179], v[218:221], v[66:69]
	v_mfma_f32_16x16x32_bf16 v[18:21], v[176:179], v[242:245], v[18:21]
	v_mfma_f32_16x16x32_bf16 v[14:17], v[168:171], v[242:245], v[14:17]
	s_barrier
	s_setprio 0
	s_add_i32 s45, s45, 2
	s_add_u32 s43, s43, 0x100
	s_addc_u32 s44, s44, 0
	s_cmpk_gt_u32 s45, 0x53
	s_mov_b64 s[28:29], s[30:31]
	s_cbranch_scc0 .LBB0_2293
	s_and_b64 vcc, exec, s[22:23]
	s_cbranch_vccz .LBB0_2296
	s_barrier
